# V pass as two 4-token sweeps: residual rows prefetched into the idle accumulator half, first half's epilogue stores drain under the second sweep
# speedup vs baseline: 1.0689x; 1.0003x over previous
; DI void peer_item_v(const Params& p, int item) {
;     ...
;     const size_t tok = (size_t)item * 32 + wave * 8 + ti;
;     const int e_lo = EG[tok * 128 + lane], e_hi = EG[tok * 128 + 64 + lane];
;     const int a_lo = __float_as_int(AG[tok * 128 + lane]), a_hi = __float_as_int(AG[tok * 128 + 64 + lane]);
;     float out[16];
; #pragma unroll
;     for (int i = 0; i < 16; ++i) out[i] = 0.f;
;     u32x4 vqa[8], vqb[8];
;     ...
;       y[i] = *(const float4*)(orow + 256 * i);
.Lvq_item:
	s_lshl_b32 s14, s10, 5
	s_add_u32 s14, s14, s56
	s_lshl_b32 s13, s14, 9
	s_add_u32 s58, s2, s13
	s_addc_u32 s59, s3, 0
	s_add_u32 s60, s4, s13
	s_addc_u32 s61, s5, 0
	v_lshrrev_b32_e32 v250, 3, v249
	v_and_b32_e32 v251, 7, v249
	v_lshlrev_b32_e32 v250, 6, v250
	v_lshl_add_u32 v250, v251, 2, v250
	global_load_dword v128, v250, s[58:59] offset:0
	global_load_dword v129, v250, s[58:59] offset:32
	global_load_dword v130, v250, s[60:61] offset:0
	global_load_dword v131, v250, s[60:61] offset:32
	global_load_dword v132, v250, s[58:59] offset:512
	global_load_dword v133, v250, s[58:59] offset:544
	global_load_dword v134, v250, s[60:61] offset:512
	global_load_dword v135, v250, s[60:61] offset:544
	global_load_dword v136, v250, s[58:59] offset:1024
	global_load_dword v137, v250, s[58:59] offset:1056
	global_load_dword v138, v250, s[60:61] offset:1024
	global_load_dword v139, v250, s[60:61] offset:1056
	global_load_dword v140, v250, s[58:59] offset:1536
	global_load_dword v141, v250, s[58:59] offset:1568
	global_load_dword v142, v250, s[60:61] offset:1536
	global_load_dword v143, v250, s[60:61] offset:1568
	global_load_dword v144, v250, s[58:59] offset:2048
	global_load_dword v145, v250, s[58:59] offset:2080
	global_load_dword v146, v250, s[60:61] offset:2048
	global_load_dword v147, v250, s[60:61] offset:2080
	global_load_dword v148, v250, s[58:59] offset:2560
	global_load_dword v149, v250, s[58:59] offset:2592
	global_load_dword v150, v250, s[60:61] offset:2560
	global_load_dword v151, v250, s[60:61] offset:2592
	global_load_dword v152, v250, s[58:59] offset:3072
	global_load_dword v153, v250, s[58:59] offset:3104
	global_load_dword v154, v250, s[60:61] offset:3072
	global_load_dword v155, v250, s[60:61] offset:3104
	global_load_dword v156, v250, s[58:59] offset:3584
	global_load_dword v157, v250, s[58:59] offset:3616
	global_load_dword v158, v250, s[60:61] offset:3584
	global_load_dword v159, v250, s[60:61] offset:3616
	v_add_u32_e32 v160, s57, v241
	v_mov_b32_e32 v161, 0
	v_mov_b32_e32 v162, 1
	v_lshrrev_b32_e32 v163, 3, v249
	v_and_b32_e32 v164, 7, v249
	v_lshlrev_b32_e32 v163, 6, v163
	v_lshl_add_u32 v163, v164, 2, v163
	v_add_u32_e32 v163, s57, v163
	v_add_u32_e32 v164, 32, v163
	v_subrev_u32_e32 v165, 1, v249
	v_subrev_u32_e32 v166, 2, v249
	v_subrev_u32_e32 v167, 4, v249
	v_subrev_u32_e32 v168, 8, v249
	v_subrev_u32_e32 v169, 16, v249
	v_subrev_u32_e32 v170, 32, v249
	v_lshlrev_b32_e32 v165, 2, v165
	v_lshlrev_b32_e32 v166, 2, v166
	v_lshlrev_b32_e32 v167, 2, v167
	v_lshlrev_b32_e32 v168, 2, v168
	v_lshlrev_b32_e32 v169, 2, v169
	v_lshlrev_b32_e32 v170, 2, v170
	v_mov_b32_e32 v0, 0
	v_mov_b32_e32 v1, 0
	v_mov_b32_e32 v2, 0
	v_mov_b32_e32 v3, 0
	v_mov_b32_e32 v4, 0
	v_mov_b32_e32 v5, 0
	v_mov_b32_e32 v6, 0
	v_mov_b32_e32 v7, 0
	v_mov_b32_e32 v8, 0
	v_mov_b32_e32 v9, 0
	v_mov_b32_e32 v10, 0
	v_mov_b32_e32 v11, 0
	v_mov_b32_e32 v12, 0
	v_mov_b32_e32 v13, 0
	v_mov_b32_e32 v14, 0
	v_mov_b32_e32 v15, 0
	v_mov_b32_e32 v16, 0
	v_mov_b32_e32 v17, 0
	v_mov_b32_e32 v18, 0
	v_mov_b32_e32 v19, 0
	v_mov_b32_e32 v20, 0
	v_mov_b32_e32 v21, 0
	v_mov_b32_e32 v22, 0
	v_mov_b32_e32 v23, 0
	v_mov_b32_e32 v24, 0
	v_mov_b32_e32 v25, 0
	v_mov_b32_e32 v26, 0
	v_mov_b32_e32 v27, 0
	v_mov_b32_e32 v28, 0
	v_mov_b32_e32 v29, 0
	v_mov_b32_e32 v30, 0
	v_mov_b32_e32 v31, 0
	v_mov_b32_e32 v32, 0
	v_mov_b32_e32 v33, 0
	v_mov_b32_e32 v34, 0
	v_mov_b32_e32 v35, 0
	v_mov_b32_e32 v36, 0
	v_mov_b32_e32 v37, 0
	v_mov_b32_e32 v38, 0
	v_mov_b32_e32 v39, 0
	v_mov_b32_e32 v40, 0
	v_mov_b32_e32 v41, 0
	v_mov_b32_e32 v42, 0
	v_mov_b32_e32 v43, 0
	v_mov_b32_e32 v44, 0
	v_mov_b32_e32 v45, 0
	v_mov_b32_e32 v46, 0
	v_mov_b32_e32 v47, 0
	v_mov_b32_e32 v48, 0
	v_mov_b32_e32 v49, 0
	v_mov_b32_e32 v50, 0
	v_mov_b32_e32 v51, 0
	v_mov_b32_e32 v52, 0
	v_mov_b32_e32 v53, 0
	v_mov_b32_e32 v54, 0
	v_mov_b32_e32 v55, 0
	v_mov_b32_e32 v56, 0
	v_mov_b32_e32 v57, 0
	v_mov_b32_e32 v58, 0
	v_mov_b32_e32 v59, 0
	v_mov_b32_e32 v60, 0
	v_mov_b32_e32 v61, 0
	v_mov_b32_e32 v62, 0
	v_mov_b32_e32 v63, 0
	s_waitcnt vmcnt(0)
	v_lshlrev_b32_e32 v128, 10, v128
	v_lshlrev_b32_e32 v129, 10, v129
	v_lshlrev_b32_e32 v132, 10, v132
	v_lshlrev_b32_e32 v133, 10, v133
	v_lshlrev_b32_e32 v136, 10, v136
	v_lshlrev_b32_e32 v137, 10, v137
	v_lshlrev_b32_e32 v140, 10, v140
	v_lshlrev_b32_e32 v141, 10, v141
	v_lshlrev_b32_e32 v144, 10, v144
	v_lshlrev_b32_e32 v145, 10, v145
	v_lshlrev_b32_e32 v148, 10, v148
	v_lshlrev_b32_e32 v149, 10, v149
	v_lshlrev_b32_e32 v152, 10, v152
	v_lshlrev_b32_e32 v153, 10, v153
	v_lshlrev_b32_e32 v156, 10, v156
	v_lshlrev_b32_e32 v157, 10, v157
	s_lshl_b32 s15, s14, 12
	s_add_u32 s62, s6, s15
	s_addc_u32 s63, s7, 0
	s_add_u32 s32, s62, 0
	s_addc_u32 s33, s63, 0
	s_add_u32 s34, s62, 4096
	s_addc_u32 s35, s63, 0
	s_add_u32 s36, s62, 8192
	s_addc_u32 s37, s63, 0
	s_add_u32 s38, s62, 12288
	s_addc_u32 s39, s63, 0
	global_load_dwordx4 v[64:67], v240, s[32:33]
	global_load_dwordx4 v[68:71], v240, s[32:33] offset:1024
	global_load_dwordx4 v[72:75], v240, s[32:33] offset:2048
	global_load_dwordx4 v[76:79], v240, s[32:33] offset:3072
	global_load_dwordx4 v[80:83], v240, s[34:35]
	global_load_dwordx4 v[84:87], v240, s[34:35] offset:1024
	global_load_dwordx4 v[88:91], v240, s[34:35] offset:2048
	global_load_dwordx4 v[92:95], v240, s[34:35] offset:3072
	global_load_dwordx4 v[96:99], v240, s[36:37]
	global_load_dwordx4 v[100:103], v240, s[36:37] offset:1024
	global_load_dwordx4 v[104:107], v240, s[36:37] offset:2048
	global_load_dwordx4 v[108:111], v240, s[36:37] offset:3072
	global_load_dwordx4 v[112:115], v240, s[38:39]
	global_load_dwordx4 v[116:119], v240, s[38:39] offset:1024
	global_load_dwordx4 v[120:123], v240, s[38:39] offset:2048
	global_load_dwordx4 v[124:127], v240, s[38:39] offset:3072
	s_mov_b32 s72, 0
	s_mov_b32 s73, 1
	s_mov_b32 s74, 2
	s_mov_b32 s75, 3
	s_mov_b32 s76, 4
	s_mov_b32 s77, 5
	s_mov_b32 s78, 6
	s_mov_b32 s79, 7
	s_nop 0
	v_readlane_b32 s48, v128, s72
	v_readlane_b32 s49, v128, s73
	v_readlane_b32 s50, v128, s74
	v_readlane_b32 s51, v128, s75
	v_readlane_b32 s52, v128, s76
	v_readlane_b32 s53, v128, s77
	v_readlane_b32 s54, v128, s78
	v_readlane_b32 s55, v128, s79
	s_add_u32 s32, s0, s48
	s_addc_u32 s33, s1, 0
	s_add_u32 s34, s0, s49
	s_addc_u32 s35, s1, 0
	s_add_u32 s36, s0, s50
	s_addc_u32 s37, s1, 0
	s_add_u32 s38, s0, s51
	s_addc_u32 s39, s1, 0
	s_add_u32 s40, s0, s52
	s_addc_u32 s41, s1, 0
	s_add_u32 s42, s0, s53
	s_addc_u32 s43, s1, 0
	s_add_u32 s44, s0, s54
	s_addc_u32 s45, s1, 0
	s_add_u32 s46, s0, s55
	s_addc_u32 s47, s1, 0
	global_load_dwordx4 v[160:163], v240, s[32:33]
	global_load_dwordx4 v[164:167], v240, s[34:35]
	global_load_dwordx4 v[168:171], v240, s[36:37]
	global_load_dwordx4 v[172:175], v240, s[38:39]
	global_load_dwordx4 v[176:179], v240, s[40:41]
	global_load_dwordx4 v[180:183], v240, s[42:43]
	global_load_dwordx4 v[184:187], v240, s[44:45]
	global_load_dwordx4 v[188:191], v240, s[46:47]
	s_mov_b32 s12, 0
; DI void peer_item_v(const Params& p, int item) {
;     ...
;     V_ISSUE(vqa, 0)
; #pragma unroll 1
;     for (int g = 0; g < 16; g += 2) {
;       V_ISSUE(vqb, g + 1)
;       V_CONSUME(vqa, g)
.Lvq_kA:
	v_readlane_b32 s16, v130, s72
	v_readlane_b32 s18, v130, s73
	v_readlane_b32 s20, v130, s74
	v_readlane_b32 s22, v130, s75
	v_readlane_b32 s24, v130, s76
	v_readlane_b32 s26, v130, s77
	v_readlane_b32 s28, v130, s78
	v_readlane_b32 s30, v130, s79
	v_readlane_b32 s48, v132, s72
	v_readlane_b32 s49, v132, s73
	v_readlane_b32 s50, v132, s74
	v_readlane_b32 s51, v132, s75
	v_readlane_b32 s52, v132, s76
	v_readlane_b32 s53, v132, s77
	v_readlane_b32 s54, v132, s78
	v_readlane_b32 s55, v132, s79
	s_add_u32 s32, s0, s48
	s_addc_u32 s33, s1, 0
	s_add_u32 s34, s0, s49
	s_addc_u32 s35, s1, 0
	s_add_u32 s36, s0, s50
	s_addc_u32 s37, s1, 0
	s_add_u32 s38, s0, s51
	s_addc_u32 s39, s1, 0
	s_add_u32 s40, s0, s52
	s_addc_u32 s41, s1, 0
	s_add_u32 s42, s0, s53
	s_addc_u32 s43, s1, 0
	s_add_u32 s44, s0, s54
	s_addc_u32 s45, s1, 0
	s_add_u32 s46, s0, s55
	s_addc_u32 s47, s1, 0
	global_load_dwordx4 v[192:195], v240, s[32:33]
	global_load_dwordx4 v[196:199], v240, s[34:35]
	global_load_dwordx4 v[200:203], v240, s[36:37]
	global_load_dwordx4 v[204:207], v240, s[38:39]
	global_load_dwordx4 v[208:211], v240, s[40:41]
	global_load_dwordx4 v[212:215], v240, s[42:43]
	global_load_dwordx4 v[216:219], v240, s[44:45]
	global_load_dwordx4 v[220:223], v240, s[46:47]
	s_waitcnt vmcnt(8)
	v_cvt_pk_f32_fp8_e32 v[224:225], v160
	v_cvt_pk_f32_fp8_sdwa v[226:227], v160 src0_sel:WORD_1
	v_cvt_pk_f32_fp8_e32 v[228:229], v161
	v_cvt_pk_f32_fp8_sdwa v[230:231], v161 src0_sel:WORD_1
	v_cvt_pk_f32_fp8_e32 v[232:233], v162
	v_cvt_pk_f32_fp8_sdwa v[234:235], v162 src0_sel:WORD_1
	v_cvt_pk_f32_fp8_e32 v[236:237], v163
	v_cvt_pk_f32_fp8_sdwa v[238:239], v163 src0_sel:WORD_1
	v_pk_fma_f32 v[0:1], v[224:225], s[16:17], v[0:1] op_sel_hi:[1,0,1]
	v_pk_fma_f32 v[2:3], v[226:227], s[16:17], v[2:3] op_sel_hi:[1,0,1]
	v_pk_fma_f32 v[4:5], v[228:229], s[16:17], v[4:5] op_sel_hi:[1,0,1]
	v_pk_fma_f32 v[6:7], v[230:231], s[16:17], v[6:7] op_sel_hi:[1,0,1]
	v_pk_fma_f32 v[8:9], v[232:233], s[16:17], v[8:9] op_sel_hi:[1,0,1]
	v_pk_fma_f32 v[10:11], v[234:235], s[16:17], v[10:11] op_sel_hi:[1,0,1]
	v_pk_fma_f32 v[12:13], v[236:237], s[16:17], v[12:13] op_sel_hi:[1,0,1]
	v_pk_fma_f32 v[14:15], v[238:239], s[16:17], v[14:15] op_sel_hi:[1,0,1]
	v_cvt_pk_f32_fp8_e32 v[224:225], v164
	v_cvt_pk_f32_fp8_sdwa v[226:227], v164 src0_sel:WORD_1
	v_cvt_pk_f32_fp8_e32 v[228:229], v165
	v_cvt_pk_f32_fp8_sdwa v[230:231], v165 src0_sel:WORD_1
	v_cvt_pk_f32_fp8_e32 v[232:233], v166
	v_cvt_pk_f32_fp8_sdwa v[234:235], v166 src0_sel:WORD_1
	v_cvt_pk_f32_fp8_e32 v[236:237], v167
	v_cvt_pk_f32_fp8_sdwa v[238:239], v167 src0_sel:WORD_1
	v_pk_fma_f32 v[0:1], v[224:225], s[18:19], v[0:1] op_sel_hi:[1,0,1]
	v_pk_fma_f32 v[2:3], v[226:227], s[18:19], v[2:3] op_sel_hi:[1,0,1]
	v_pk_fma_f32 v[4:5], v[228:229], s[18:19], v[4:5] op_sel_hi:[1,0,1]
	v_pk_fma_f32 v[6:7], v[230:231], s[18:19], v[6:7] op_sel_hi:[1,0,1]
	v_pk_fma_f32 v[8:9], v[232:233], s[18:19], v[8:9] op_sel_hi:[1,0,1]
	v_pk_fma_f32 v[10:11], v[234:235], s[18:19], v[10:11] op_sel_hi:[1,0,1]
	v_pk_fma_f32 v[12:13], v[236:237], s[18:19], v[12:13] op_sel_hi:[1,0,1]
	v_pk_fma_f32 v[14:15], v[238:239], s[18:19], v[14:15] op_sel_hi:[1,0,1]
	v_cvt_pk_f32_fp8_e32 v[224:225], v168
	v_cvt_pk_f32_fp8_sdwa v[226:227], v168 src0_sel:WORD_1
	v_cvt_pk_f32_fp8_e32 v[228:229], v169
	v_cvt_pk_f32_fp8_sdwa v[230:231], v169 src0_sel:WORD_1
	v_cvt_pk_f32_fp8_e32 v[232:233], v170
	v_cvt_pk_f32_fp8_sdwa v[234:235], v170 src0_sel:WORD_1
	v_cvt_pk_f32_fp8_e32 v[236:237], v171
	v_cvt_pk_f32_fp8_sdwa v[238:239], v171 src0_sel:WORD_1
	v_pk_fma_f32 v[0:1], v[224:225], s[20:21], v[0:1] op_sel_hi:[1,0,1]
	v_pk_fma_f32 v[2:3], v[226:227], s[20:21], v[2:3] op_sel_hi:[1,0,1]
	v_pk_fma_f32 v[4:5], v[228:229], s[20:21], v[4:5] op_sel_hi:[1,0,1]
	v_pk_fma_f32 v[6:7], v[230:231], s[20:21], v[6:7] op_sel_hi:[1,0,1]
	v_pk_fma_f32 v[8:9], v[232:233], s[20:21], v[8:9] op_sel_hi:[1,0,1]
	v_pk_fma_f32 v[10:11], v[234:235], s[20:21], v[10:11] op_sel_hi:[1,0,1]
	v_pk_fma_f32 v[12:13], v[236:237], s[20:21], v[12:13] op_sel_hi:[1,0,1]
	v_pk_fma_f32 v[14:15], v[238:239], s[20:21], v[14:15] op_sel_hi:[1,0,1]
	v_cvt_pk_f32_fp8_e32 v[224:225], v172
	v_cvt_pk_f32_fp8_sdwa v[226:227], v172 src0_sel:WORD_1
	v_cvt_pk_f32_fp8_e32 v[228:229], v173
	v_cvt_pk_f32_fp8_sdwa v[230:231], v173 src0_sel:WORD_1
	v_cvt_pk_f32_fp8_e32 v[232:233], v174
	v_cvt_pk_f32_fp8_sdwa v[234:235], v174 src0_sel:WORD_1
	v_cvt_pk_f32_fp8_e32 v[236:237], v175
	v_cvt_pk_f32_fp8_sdwa v[238:239], v175 src0_sel:WORD_1
	v_pk_fma_f32 v[0:1], v[224:225], s[22:23], v[0:1] op_sel_hi:[1,0,1]
	v_pk_fma_f32 v[2:3], v[226:227], s[22:23], v[2:3] op_sel_hi:[1,0,1]
	v_pk_fma_f32 v[4:5], v[228:229], s[22:23], v[4:5] op_sel_hi:[1,0,1]
	v_pk_fma_f32 v[6:7], v[230:231], s[22:23], v[6:7] op_sel_hi:[1,0,1]
	v_pk_fma_f32 v[8:9], v[232:233], s[22:23], v[8:9] op_sel_hi:[1,0,1]
	v_pk_fma_f32 v[10:11], v[234:235], s[22:23], v[10:11] op_sel_hi:[1,0,1]
	v_pk_fma_f32 v[12:13], v[236:237], s[22:23], v[12:13] op_sel_hi:[1,0,1]
	v_pk_fma_f32 v[14:15], v[238:239], s[22:23], v[14:15] op_sel_hi:[1,0,1]
	v_cvt_pk_f32_fp8_e32 v[224:225], v176
	v_cvt_pk_f32_fp8_sdwa v[226:227], v176 src0_sel:WORD_1
	v_cvt_pk_f32_fp8_e32 v[228:229], v177
	v_cvt_pk_f32_fp8_sdwa v[230:231], v177 src0_sel:WORD_1
	v_cvt_pk_f32_fp8_e32 v[232:233], v178
	v_cvt_pk_f32_fp8_sdwa v[234:235], v178 src0_sel:WORD_1
	v_cvt_pk_f32_fp8_e32 v[236:237], v179
	v_cvt_pk_f32_fp8_sdwa v[238:239], v179 src0_sel:WORD_1
	v_pk_fma_f32 v[0:1], v[224:225], s[24:25], v[0:1] op_sel_hi:[1,0,1]
	v_pk_fma_f32 v[2:3], v[226:227], s[24:25], v[2:3] op_sel_hi:[1,0,1]
	v_pk_fma_f32 v[4:5], v[228:229], s[24:25], v[4:5] op_sel_hi:[1,0,1]
; DI void peer_item_v(const Params& p, int item) {
;     ...
;     V_ISSUE(vqa, 0)
; #pragma unroll 1
;     for (int g = 0; g < 16; g += 2) {
;       V_ISSUE(vqb, g + 1)
;       V_CONSUME(vqa, g)
;       if (g + 2 < 16) V_ISSUE(vqa, g + 2)
;       V_CONSUME(vqb, g + 1)
;     }
	v_pk_fma_f32 v[6:7], v[230:231], s[24:25], v[6:7] op_sel_hi:[1,0,1]
	v_pk_fma_f32 v[8:9], v[232:233], s[24:25], v[8:9] op_sel_hi:[1,0,1]
	v_pk_fma_f32 v[10:11], v[234:235], s[24:25], v[10:11] op_sel_hi:[1,0,1]
	v_pk_fma_f32 v[12:13], v[236:237], s[24:25], v[12:13] op_sel_hi:[1,0,1]
	v_pk_fma_f32 v[14:15], v[238:239], s[24:25], v[14:15] op_sel_hi:[1,0,1]
	v_cvt_pk_f32_fp8_e32 v[224:225], v180
	v_cvt_pk_f32_fp8_sdwa v[226:227], v180 src0_sel:WORD_1
	v_cvt_pk_f32_fp8_e32 v[228:229], v181
	v_cvt_pk_f32_fp8_sdwa v[230:231], v181 src0_sel:WORD_1
	v_cvt_pk_f32_fp8_e32 v[232:233], v182
	v_cvt_pk_f32_fp8_sdwa v[234:235], v182 src0_sel:WORD_1
	v_cvt_pk_f32_fp8_e32 v[236:237], v183
	v_cvt_pk_f32_fp8_sdwa v[238:239], v183 src0_sel:WORD_1
	v_pk_fma_f32 v[0:1], v[224:225], s[26:27], v[0:1] op_sel_hi:[1,0,1]
	v_pk_fma_f32 v[2:3], v[226:227], s[26:27], v[2:3] op_sel_hi:[1,0,1]
	v_pk_fma_f32 v[4:5], v[228:229], s[26:27], v[4:5] op_sel_hi:[1,0,1]
	v_pk_fma_f32 v[6:7], v[230:231], s[26:27], v[6:7] op_sel_hi:[1,0,1]
	v_pk_fma_f32 v[8:9], v[232:233], s[26:27], v[8:9] op_sel_hi:[1,0,1]
	v_pk_fma_f32 v[10:11], v[234:235], s[26:27], v[10:11] op_sel_hi:[1,0,1]
	v_pk_fma_f32 v[12:13], v[236:237], s[26:27], v[12:13] op_sel_hi:[1,0,1]
	v_pk_fma_f32 v[14:15], v[238:239], s[26:27], v[14:15] op_sel_hi:[1,0,1]
	v_cvt_pk_f32_fp8_e32 v[224:225], v184
	v_cvt_pk_f32_fp8_sdwa v[226:227], v184 src0_sel:WORD_1
	v_cvt_pk_f32_fp8_e32 v[228:229], v185
	v_cvt_pk_f32_fp8_sdwa v[230:231], v185 src0_sel:WORD_1
	v_cvt_pk_f32_fp8_e32 v[232:233], v186
	v_cvt_pk_f32_fp8_sdwa v[234:235], v186 src0_sel:WORD_1
	v_cvt_pk_f32_fp8_e32 v[236:237], v187
	v_cvt_pk_f32_fp8_sdwa v[238:239], v187 src0_sel:WORD_1
	v_pk_fma_f32 v[0:1], v[224:225], s[28:29], v[0:1] op_sel_hi:[1,0,1]
	v_pk_fma_f32 v[2:3], v[226:227], s[28:29], v[2:3] op_sel_hi:[1,0,1]
	v_pk_fma_f32 v[4:5], v[228:229], s[28:29], v[4:5] op_sel_hi:[1,0,1]
	v_pk_fma_f32 v[6:7], v[230:231], s[28:29], v[6:7] op_sel_hi:[1,0,1]
	v_pk_fma_f32 v[8:9], v[232:233], s[28:29], v[8:9] op_sel_hi:[1,0,1]
	v_pk_fma_f32 v[10:11], v[234:235], s[28:29], v[10:11] op_sel_hi:[1,0,1]
	v_pk_fma_f32 v[12:13], v[236:237], s[28:29], v[12:13] op_sel_hi:[1,0,1]
	v_pk_fma_f32 v[14:15], v[238:239], s[28:29], v[14:15] op_sel_hi:[1,0,1]
	v_cvt_pk_f32_fp8_e32 v[224:225], v188
	v_cvt_pk_f32_fp8_sdwa v[226:227], v188 src0_sel:WORD_1
	v_cvt_pk_f32_fp8_e32 v[228:229], v189
	v_cvt_pk_f32_fp8_sdwa v[230:231], v189 src0_sel:WORD_1
	v_cvt_pk_f32_fp8_e32 v[232:233], v190
	v_cvt_pk_f32_fp8_sdwa v[234:235], v190 src0_sel:WORD_1
	v_cvt_pk_f32_fp8_e32 v[236:237], v191
	v_cvt_pk_f32_fp8_sdwa v[238:239], v191 src0_sel:WORD_1
	v_pk_fma_f32 v[0:1], v[224:225], s[30:31], v[0:1] op_sel_hi:[1,0,1]
	v_pk_fma_f32 v[2:3], v[226:227], s[30:31], v[2:3] op_sel_hi:[1,0,1]
	v_pk_fma_f32 v[4:5], v[228:229], s[30:31], v[4:5] op_sel_hi:[1,0,1]
	v_pk_fma_f32 v[6:7], v[230:231], s[30:31], v[6:7] op_sel_hi:[1,0,1]
	v_pk_fma_f32 v[8:9], v[232:233], s[30:31], v[8:9] op_sel_hi:[1,0,1]
	v_pk_fma_f32 v[10:11], v[234:235], s[30:31], v[10:11] op_sel_hi:[1,0,1]
	v_pk_fma_f32 v[12:13], v[236:237], s[30:31], v[12:13] op_sel_hi:[1,0,1]
	v_pk_fma_f32 v[14:15], v[238:239], s[30:31], v[14:15] op_sel_hi:[1,0,1]
	v_readlane_b32 s16, v134, s72
	v_readlane_b32 s18, v134, s73
	v_readlane_b32 s20, v134, s74
	v_readlane_b32 s22, v134, s75
	v_readlane_b32 s24, v134, s76
	v_readlane_b32 s26, v134, s77
	v_readlane_b32 s28, v134, s78
	v_readlane_b32 s30, v134, s79
	v_readlane_b32 s48, v136, s72
	v_readlane_b32 s49, v136, s73
	v_readlane_b32 s50, v136, s74
	v_readlane_b32 s51, v136, s75
	v_readlane_b32 s52, v136, s76
	v_readlane_b32 s53, v136, s77
	v_readlane_b32 s54, v136, s78
	v_readlane_b32 s55, v136, s79
	s_add_u32 s32, s0, s48
	s_addc_u32 s33, s1, 0
	s_add_u32 s34, s0, s49
	s_addc_u32 s35, s1, 0
	s_add_u32 s36, s0, s50
	s_addc_u32 s37, s1, 0
	s_add_u32 s38, s0, s51
	s_addc_u32 s39, s1, 0
	s_add_u32 s40, s0, s52
	s_addc_u32 s41, s1, 0
	s_add_u32 s42, s0, s53
	s_addc_u32 s43, s1, 0
	s_add_u32 s44, s0, s54
	s_addc_u32 s45, s1, 0
	s_add_u32 s46, s0, s55
	s_addc_u32 s47, s1, 0
	global_load_dwordx4 v[160:163], v240, s[32:33]
	global_load_dwordx4 v[164:167], v240, s[34:35]
	global_load_dwordx4 v[168:171], v240, s[36:37]
	global_load_dwordx4 v[172:175], v240, s[38:39]
	global_load_dwordx4 v[176:179], v240, s[40:41]
	global_load_dwordx4 v[180:183], v240, s[42:43]
	global_load_dwordx4 v[184:187], v240, s[44:45]
	global_load_dwordx4 v[188:191], v240, s[46:47]
	s_waitcnt vmcnt(8)
	v_cvt_pk_f32_fp8_e32 v[224:225], v192
	v_cvt_pk_f32_fp8_sdwa v[226:227], v192 src0_sel:WORD_1
	v_cvt_pk_f32_fp8_e32 v[228:229], v193
	v_cvt_pk_f32_fp8_sdwa v[230:231], v193 src0_sel:WORD_1
	v_cvt_pk_f32_fp8_e32 v[232:233], v194
	v_cvt_pk_f32_fp8_sdwa v[234:235], v194 src0_sel:WORD_1
	v_cvt_pk_f32_fp8_e32 v[236:237], v195
	v_cvt_pk_f32_fp8_sdwa v[238:239], v195 src0_sel:WORD_1
	v_pk_fma_f32 v[16:17], v[224:225], s[16:17], v[16:17] op_sel_hi:[1,0,1]
	v_pk_fma_f32 v[18:19], v[226:227], s[16:17], v[18:19] op_sel_hi:[1,0,1]
	v_pk_fma_f32 v[20:21], v[228:229], s[16:17], v[20:21] op_sel_hi:[1,0,1]
	v_pk_fma_f32 v[22:23], v[230:231], s[16:17], v[22:23] op_sel_hi:[1,0,1]
	v_pk_fma_f32 v[24:25], v[232:233], s[16:17], v[24:25] op_sel_hi:[1,0,1]
	v_pk_fma_f32 v[26:27], v[234:235], s[16:17], v[26:27] op_sel_hi:[1,0,1]
	v_pk_fma_f32 v[28:29], v[236:237], s[16:17], v[28:29] op_sel_hi:[1,0,1]
	v_pk_fma_f32 v[30:31], v[238:239], s[16:17], v[30:31] op_sel_hi:[1,0,1]
	v_cvt_pk_f32_fp8_e32 v[224:225], v196
	v_cvt_pk_f32_fp8_sdwa v[226:227], v196 src0_sel:WORD_1
	v_cvt_pk_f32_fp8_e32 v[228:229], v197
	v_cvt_pk_f32_fp8_sdwa v[230:231], v197 src0_sel:WORD_1
	v_cvt_pk_f32_fp8_e32 v[232:233], v198
	v_cvt_pk_f32_fp8_sdwa v[234:235], v198 src0_sel:WORD_1
	v_cvt_pk_f32_fp8_e32 v[236:237], v199
	v_cvt_pk_f32_fp8_sdwa v[238:239], v199 src0_sel:WORD_1
	v_pk_fma_f32 v[16:17], v[224:225], s[18:19], v[16:17] op_sel_hi:[1,0,1]
	v_pk_fma_f32 v[18:19], v[226:227], s[18:19], v[18:19] op_sel_hi:[1,0,1]
	v_pk_fma_f32 v[20:21], v[228:229], s[18:19], v[20:21] op_sel_hi:[1,0,1]
	v_pk_fma_f32 v[22:23], v[230:231], s[18:19], v[22:23] op_sel_hi:[1,0,1]
	v_pk_fma_f32 v[24:25], v[232:233], s[18:19], v[24:25] op_sel_hi:[1,0,1]
	v_pk_fma_f32 v[26:27], v[234:235], s[18:19], v[26:27] op_sel_hi:[1,0,1]
	v_pk_fma_f32 v[28:29], v[236:237], s[18:19], v[28:29] op_sel_hi:[1,0,1]
	v_pk_fma_f32 v[30:31], v[238:239], s[18:19], v[30:31] op_sel_hi:[1,0,1]
	v_cvt_pk_f32_fp8_e32 v[224:225], v200
	v_cvt_pk_f32_fp8_sdwa v[226:227], v200 src0_sel:WORD_1
	v_cvt_pk_f32_fp8_e32 v[228:229], v201
	v_cvt_pk_f32_fp8_sdwa v[230:231], v201 src0_sel:WORD_1
	v_cvt_pk_f32_fp8_e32 v[232:233], v202
	v_cvt_pk_f32_fp8_sdwa v[234:235], v202 src0_sel:WORD_1
	v_cvt_pk_f32_fp8_e32 v[236:237], v203
	v_cvt_pk_f32_fp8_sdwa v[238:239], v203 src0_sel:WORD_1
	v_pk_fma_f32 v[16:17], v[224:225], s[20:21], v[16:17] op_sel_hi:[1,0,1]
	v_pk_fma_f32 v[18:19], v[226:227], s[20:21], v[18:19] op_sel_hi:[1,0,1]
	v_pk_fma_f32 v[20:21], v[228:229], s[20:21], v[20:21] op_sel_hi:[1,0,1]
	v_pk_fma_f32 v[22:23], v[230:231], s[20:21], v[22:23] op_sel_hi:[1,0,1]
	v_pk_fma_f32 v[24:25], v[232:233], s[20:21], v[24:25] op_sel_hi:[1,0,1]
	v_pk_fma_f32 v[26:27], v[234:235], s[20:21], v[26:27] op_sel_hi:[1,0,1]
	v_pk_fma_f32 v[28:29], v[236:237], s[20:21], v[28:29] op_sel_hi:[1,0,1]
	v_pk_fma_f32 v[30:31], v[238:239], s[20:21], v[30:31] op_sel_hi:[1,0,1]
	v_cvt_pk_f32_fp8_e32 v[224:225], v204
	v_cvt_pk_f32_fp8_sdwa v[226:227], v204 src0_sel:WORD_1
	v_cvt_pk_f32_fp8_e32 v[228:229], v205
	v_cvt_pk_f32_fp8_sdwa v[230:231], v205 src0_sel:WORD_1
	v_cvt_pk_f32_fp8_e32 v[232:233], v206
	v_cvt_pk_f32_fp8_sdwa v[234:235], v206 src0_sel:WORD_1
	v_cvt_pk_f32_fp8_e32 v[236:237], v207
	v_cvt_pk_f32_fp8_sdwa v[238:239], v207 src0_sel:WORD_1
	v_pk_fma_f32 v[16:17], v[224:225], s[22:23], v[16:17] op_sel_hi:[1,0,1]
	v_pk_fma_f32 v[18:19], v[226:227], s[22:23], v[18:19] op_sel_hi:[1,0,1]
	v_pk_fma_f32 v[20:21], v[228:229], s[22:23], v[20:21] op_sel_hi:[1,0,1]
	v_pk_fma_f32 v[22:23], v[230:231], s[22:23], v[22:23] op_sel_hi:[1,0,1]
	v_pk_fma_f32 v[24:25], v[232:233], s[22:23], v[24:25] op_sel_hi:[1,0,1]
	v_pk_fma_f32 v[26:27], v[234:235], s[22:23], v[26:27] op_sel_hi:[1,0,1]
	v_pk_fma_f32 v[28:29], v[236:237], s[22:23], v[28:29] op_sel_hi:[1,0,1]
	v_pk_fma_f32 v[30:31], v[238:239], s[22:23], v[30:31] op_sel_hi:[1,0,1]
	v_cvt_pk_f32_fp8_e32 v[224:225], v208
	v_cvt_pk_f32_fp8_sdwa v[226:227], v208 src0_sel:WORD_1
	v_cvt_pk_f32_fp8_e32 v[228:229], v209
	v_cvt_pk_f32_fp8_sdwa v[230:231], v209 src0_sel:WORD_1
	v_cvt_pk_f32_fp8_e32 v[232:233], v210
	v_cvt_pk_f32_fp8_sdwa v[234:235], v210 src0_sel:WORD_1
	v_cvt_pk_f32_fp8_e32 v[236:237], v211
	v_cvt_pk_f32_fp8_sdwa v[238:239], v211 src0_sel:WORD_1
	v_pk_fma_f32 v[16:17], v[224:225], s[24:25], v[16:17] op_sel_hi:[1,0,1]
	v_pk_fma_f32 v[18:19], v[226:227], s[24:25], v[18:19] op_sel_hi:[1,0,1]
	v_pk_fma_f32 v[20:21], v[228:229], s[24:25], v[20:21] op_sel_hi:[1,0,1]
	v_pk_fma_f32 v[22:23], v[230:231], s[24:25], v[22:23] op_sel_hi:[1,0,1]
	v_pk_fma_f32 v[24:25], v[232:233], s[24:25], v[24:25] op_sel_hi:[1,0,1]
	v_pk_fma_f32 v[26:27], v[234:235], s[24:25], v[26:27] op_sel_hi:[1,0,1]
	v_pk_fma_f32 v[28:29], v[236:237], s[24:25], v[28:29] op_sel_hi:[1,0,1]
	v_pk_fma_f32 v[30:31], v[238:239], s[24:25], v[30:31] op_sel_hi:[1,0,1]
	v_cvt_pk_f32_fp8_e32 v[224:225], v212
	v_cvt_pk_f32_fp8_sdwa v[226:227], v212 src0_sel:WORD_1
	v_cvt_pk_f32_fp8_e32 v[228:229], v213
	v_cvt_pk_f32_fp8_sdwa v[230:231], v213 src0_sel:WORD_1
	v_cvt_pk_f32_fp8_e32 v[232:233], v214
	v_cvt_pk_f32_fp8_sdwa v[234:235], v214 src0_sel:WORD_1
	v_cvt_pk_f32_fp8_e32 v[236:237], v215
	v_cvt_pk_f32_fp8_sdwa v[238:239], v215 src0_sel:WORD_1
	v_pk_fma_f32 v[16:17], v[224:225], s[26:27], v[16:17] op_sel_hi:[1,0,1]
	v_pk_fma_f32 v[18:19], v[226:227], s[26:27], v[18:19] op_sel_hi:[1,0,1]
	v_pk_fma_f32 v[20:21], v[228:229], s[26:27], v[20:21] op_sel_hi:[1,0,1]
	v_pk_fma_f32 v[22:23], v[230:231], s[26:27], v[22:23] op_sel_hi:[1,0,1]
	v_pk_fma_f32 v[24:25], v[232:233], s[26:27], v[24:25] op_sel_hi:[1,0,1]
	v_pk_fma_f32 v[26:27], v[234:235], s[26:27], v[26:27] op_sel_hi:[1,0,1]
; DI void peer_item_v(const Params& p, int item) {
;     ...
;     V_ISSUE(vqa, 0)
; #pragma unroll 1
;     for (int g = 0; g < 16; g += 2) {
;       V_ISSUE(vqb, g + 1)
;       V_CONSUME(vqa, g)
;       if (g + 2 < 16) V_ISSUE(vqa, g + 2)
;       V_CONSUME(vqb, g + 1)
;     }
	v_pk_fma_f32 v[28:29], v[236:237], s[26:27], v[28:29] op_sel_hi:[1,0,1]
	v_pk_fma_f32 v[30:31], v[238:239], s[26:27], v[30:31] op_sel_hi:[1,0,1]
	v_cvt_pk_f32_fp8_e32 v[224:225], v216
	v_cvt_pk_f32_fp8_sdwa v[226:227], v216 src0_sel:WORD_1
	v_cvt_pk_f32_fp8_e32 v[228:229], v217
	v_cvt_pk_f32_fp8_sdwa v[230:231], v217 src0_sel:WORD_1
	v_cvt_pk_f32_fp8_e32 v[232:233], v218
	v_cvt_pk_f32_fp8_sdwa v[234:235], v218 src0_sel:WORD_1
	v_cvt_pk_f32_fp8_e32 v[236:237], v219
	v_cvt_pk_f32_fp8_sdwa v[238:239], v219 src0_sel:WORD_1
	v_pk_fma_f32 v[16:17], v[224:225], s[28:29], v[16:17] op_sel_hi:[1,0,1]
	v_pk_fma_f32 v[18:19], v[226:227], s[28:29], v[18:19] op_sel_hi:[1,0,1]
	v_pk_fma_f32 v[20:21], v[228:229], s[28:29], v[20:21] op_sel_hi:[1,0,1]
	v_pk_fma_f32 v[22:23], v[230:231], s[28:29], v[22:23] op_sel_hi:[1,0,1]
	v_pk_fma_f32 v[24:25], v[232:233], s[28:29], v[24:25] op_sel_hi:[1,0,1]
	v_pk_fma_f32 v[26:27], v[234:235], s[28:29], v[26:27] op_sel_hi:[1,0,1]
	v_pk_fma_f32 v[28:29], v[236:237], s[28:29], v[28:29] op_sel_hi:[1,0,1]
	v_pk_fma_f32 v[30:31], v[238:239], s[28:29], v[30:31] op_sel_hi:[1,0,1]
	v_cvt_pk_f32_fp8_e32 v[224:225], v220
	v_cvt_pk_f32_fp8_sdwa v[226:227], v220 src0_sel:WORD_1
	v_cvt_pk_f32_fp8_e32 v[228:229], v221
	v_cvt_pk_f32_fp8_sdwa v[230:231], v221 src0_sel:WORD_1
	v_cvt_pk_f32_fp8_e32 v[232:233], v222
	v_cvt_pk_f32_fp8_sdwa v[234:235], v222 src0_sel:WORD_1
	v_cvt_pk_f32_fp8_e32 v[236:237], v223
	v_cvt_pk_f32_fp8_sdwa v[238:239], v223 src0_sel:WORD_1
	v_pk_fma_f32 v[16:17], v[224:225], s[30:31], v[16:17] op_sel_hi:[1,0,1]
	v_pk_fma_f32 v[18:19], v[226:227], s[30:31], v[18:19] op_sel_hi:[1,0,1]
	v_pk_fma_f32 v[20:21], v[228:229], s[30:31], v[20:21] op_sel_hi:[1,0,1]
	v_pk_fma_f32 v[22:23], v[230:231], s[30:31], v[22:23] op_sel_hi:[1,0,1]
	v_pk_fma_f32 v[24:25], v[232:233], s[30:31], v[24:25] op_sel_hi:[1,0,1]
	v_pk_fma_f32 v[26:27], v[234:235], s[30:31], v[26:27] op_sel_hi:[1,0,1]
	v_pk_fma_f32 v[28:29], v[236:237], s[30:31], v[28:29] op_sel_hi:[1,0,1]
	v_pk_fma_f32 v[30:31], v[238:239], s[30:31], v[30:31] op_sel_hi:[1,0,1]
	v_readlane_b32 s16, v138, s72
	v_readlane_b32 s18, v138, s73
	v_readlane_b32 s20, v138, s74
	v_readlane_b32 s22, v138, s75
	v_readlane_b32 s24, v138, s76
	v_readlane_b32 s26, v138, s77
	v_readlane_b32 s28, v138, s78
	v_readlane_b32 s30, v138, s79
	v_readlane_b32 s48, v140, s72
	v_readlane_b32 s49, v140, s73
	v_readlane_b32 s50, v140, s74
	v_readlane_b32 s51, v140, s75
	v_readlane_b32 s52, v140, s76
	v_readlane_b32 s53, v140, s77
	v_readlane_b32 s54, v140, s78
	v_readlane_b32 s55, v140, s79
	s_add_u32 s32, s0, s48
	s_addc_u32 s33, s1, 0
	s_add_u32 s34, s0, s49
	s_addc_u32 s35, s1, 0
	s_add_u32 s36, s0, s50
	s_addc_u32 s37, s1, 0
	s_add_u32 s38, s0, s51
	s_addc_u32 s39, s1, 0
	s_add_u32 s40, s0, s52
	s_addc_u32 s41, s1, 0
	s_add_u32 s42, s0, s53
	s_addc_u32 s43, s1, 0
	s_add_u32 s44, s0, s54
	s_addc_u32 s45, s1, 0
	s_add_u32 s46, s0, s55
	s_addc_u32 s47, s1, 0
	global_load_dwordx4 v[192:195], v240, s[32:33]
	global_load_dwordx4 v[196:199], v240, s[34:35]
	global_load_dwordx4 v[200:203], v240, s[36:37]
	global_load_dwordx4 v[204:207], v240, s[38:39]
	global_load_dwordx4 v[208:211], v240, s[40:41]
	global_load_dwordx4 v[212:215], v240, s[42:43]
	global_load_dwordx4 v[216:219], v240, s[44:45]
	global_load_dwordx4 v[220:223], v240, s[46:47]
	s_waitcnt vmcnt(8)
	v_cvt_pk_f32_fp8_e32 v[224:225], v160
	v_cvt_pk_f32_fp8_sdwa v[226:227], v160 src0_sel:WORD_1
	v_cvt_pk_f32_fp8_e32 v[228:229], v161
	v_cvt_pk_f32_fp8_sdwa v[230:231], v161 src0_sel:WORD_1
	v_cvt_pk_f32_fp8_e32 v[232:233], v162
	v_cvt_pk_f32_fp8_sdwa v[234:235], v162 src0_sel:WORD_1
	v_cvt_pk_f32_fp8_e32 v[236:237], v163
	v_cvt_pk_f32_fp8_sdwa v[238:239], v163 src0_sel:WORD_1
	v_pk_fma_f32 v[32:33], v[224:225], s[16:17], v[32:33] op_sel_hi:[1,0,1]
	v_pk_fma_f32 v[34:35], v[226:227], s[16:17], v[34:35] op_sel_hi:[1,0,1]
	v_pk_fma_f32 v[36:37], v[228:229], s[16:17], v[36:37] op_sel_hi:[1,0,1]
	v_pk_fma_f32 v[38:39], v[230:231], s[16:17], v[38:39] op_sel_hi:[1,0,1]
	v_pk_fma_f32 v[40:41], v[232:233], s[16:17], v[40:41] op_sel_hi:[1,0,1]
	v_pk_fma_f32 v[42:43], v[234:235], s[16:17], v[42:43] op_sel_hi:[1,0,1]
	v_pk_fma_f32 v[44:45], v[236:237], s[16:17], v[44:45] op_sel_hi:[1,0,1]
	v_pk_fma_f32 v[46:47], v[238:239], s[16:17], v[46:47] op_sel_hi:[1,0,1]
	v_cvt_pk_f32_fp8_e32 v[224:225], v164
	v_cvt_pk_f32_fp8_sdwa v[226:227], v164 src0_sel:WORD_1
	v_cvt_pk_f32_fp8_e32 v[228:229], v165
	v_cvt_pk_f32_fp8_sdwa v[230:231], v165 src0_sel:WORD_1
	v_cvt_pk_f32_fp8_e32 v[232:233], v166
	v_cvt_pk_f32_fp8_sdwa v[234:235], v166 src0_sel:WORD_1
	v_cvt_pk_f32_fp8_e32 v[236:237], v167
	v_cvt_pk_f32_fp8_sdwa v[238:239], v167 src0_sel:WORD_1
	v_pk_fma_f32 v[32:33], v[224:225], s[18:19], v[32:33] op_sel_hi:[1,0,1]
	v_pk_fma_f32 v[34:35], v[226:227], s[18:19], v[34:35] op_sel_hi:[1,0,1]
	v_pk_fma_f32 v[36:37], v[228:229], s[18:19], v[36:37] op_sel_hi:[1,0,1]
	v_pk_fma_f32 v[38:39], v[230:231], s[18:19], v[38:39] op_sel_hi:[1,0,1]
	v_pk_fma_f32 v[40:41], v[232:233], s[18:19], v[40:41] op_sel_hi:[1,0,1]
	v_pk_fma_f32 v[42:43], v[234:235], s[18:19], v[42:43] op_sel_hi:[1,0,1]
	v_pk_fma_f32 v[44:45], v[236:237], s[18:19], v[44:45] op_sel_hi:[1,0,1]
	v_pk_fma_f32 v[46:47], v[238:239], s[18:19], v[46:47] op_sel_hi:[1,0,1]
	v_cvt_pk_f32_fp8_e32 v[224:225], v168
	v_cvt_pk_f32_fp8_sdwa v[226:227], v168 src0_sel:WORD_1
	v_cvt_pk_f32_fp8_e32 v[228:229], v169
	v_cvt_pk_f32_fp8_sdwa v[230:231], v169 src0_sel:WORD_1
	v_cvt_pk_f32_fp8_e32 v[232:233], v170
	v_cvt_pk_f32_fp8_sdwa v[234:235], v170 src0_sel:WORD_1
	v_cvt_pk_f32_fp8_e32 v[236:237], v171
	v_cvt_pk_f32_fp8_sdwa v[238:239], v171 src0_sel:WORD_1
; DI void peer_item_v(const Params& p, int item) {
;     ...
;     V_ISSUE(vqa, 0)
; #pragma unroll 1
;     for (int g = 0; g < 16; g += 2) {
;       V_ISSUE(vqb, g + 1)
;       V_CONSUME(vqa, g)
;       if (g + 2 < 16) V_ISSUE(vqa, g + 2)
;       V_CONSUME(vqb, g + 1)
;     }
	v_pk_fma_f32 v[32:33], v[224:225], s[20:21], v[32:33] op_sel_hi:[1,0,1]
	v_pk_fma_f32 v[34:35], v[226:227], s[20:21], v[34:35] op_sel_hi:[1,0,1]
	v_pk_fma_f32 v[36:37], v[228:229], s[20:21], v[36:37] op_sel_hi:[1,0,1]
	v_pk_fma_f32 v[38:39], v[230:231], s[20:21], v[38:39] op_sel_hi:[1,0,1]
	v_pk_fma_f32 v[40:41], v[232:233], s[20:21], v[40:41] op_sel_hi:[1,0,1]
	v_pk_fma_f32 v[42:43], v[234:235], s[20:21], v[42:43] op_sel_hi:[1,0,1]
	v_pk_fma_f32 v[44:45], v[236:237], s[20:21], v[44:45] op_sel_hi:[1,0,1]
	v_pk_fma_f32 v[46:47], v[238:239], s[20:21], v[46:47] op_sel_hi:[1,0,1]
	v_cvt_pk_f32_fp8_e32 v[224:225], v172
	v_cvt_pk_f32_fp8_sdwa v[226:227], v172 src0_sel:WORD_1
	v_cvt_pk_f32_fp8_e32 v[228:229], v173
	v_cvt_pk_f32_fp8_sdwa v[230:231], v173 src0_sel:WORD_1
	v_cvt_pk_f32_fp8_e32 v[232:233], v174
	v_cvt_pk_f32_fp8_sdwa v[234:235], v174 src0_sel:WORD_1
	v_cvt_pk_f32_fp8_e32 v[236:237], v175
	v_cvt_pk_f32_fp8_sdwa v[238:239], v175 src0_sel:WORD_1
	v_pk_fma_f32 v[32:33], v[224:225], s[22:23], v[32:33] op_sel_hi:[1,0,1]
	v_pk_fma_f32 v[34:35], v[226:227], s[22:23], v[34:35] op_sel_hi:[1,0,1]
	v_pk_fma_f32 v[36:37], v[228:229], s[22:23], v[36:37] op_sel_hi:[1,0,1]
	v_pk_fma_f32 v[38:39], v[230:231], s[22:23], v[38:39] op_sel_hi:[1,0,1]
	v_pk_fma_f32 v[40:41], v[232:233], s[22:23], v[40:41] op_sel_hi:[1,0,1]
	v_pk_fma_f32 v[42:43], v[234:235], s[22:23], v[42:43] op_sel_hi:[1,0,1]
	v_pk_fma_f32 v[44:45], v[236:237], s[22:23], v[44:45] op_sel_hi:[1,0,1]
	v_pk_fma_f32 v[46:47], v[238:239], s[22:23], v[46:47] op_sel_hi:[1,0,1]
	v_cvt_pk_f32_fp8_e32 v[224:225], v176
	v_cvt_pk_f32_fp8_sdwa v[226:227], v176 src0_sel:WORD_1
	v_cvt_pk_f32_fp8_e32 v[228:229], v177
	v_cvt_pk_f32_fp8_sdwa v[230:231], v177 src0_sel:WORD_1
	v_cvt_pk_f32_fp8_e32 v[232:233], v178
	v_cvt_pk_f32_fp8_sdwa v[234:235], v178 src0_sel:WORD_1
	v_cvt_pk_f32_fp8_e32 v[236:237], v179
	v_cvt_pk_f32_fp8_sdwa v[238:239], v179 src0_sel:WORD_1
	v_pk_fma_f32 v[32:33], v[224:225], s[24:25], v[32:33] op_sel_hi:[1,0,1]
	v_pk_fma_f32 v[34:35], v[226:227], s[24:25], v[34:35] op_sel_hi:[1,0,1]
	v_pk_fma_f32 v[36:37], v[228:229], s[24:25], v[36:37] op_sel_hi:[1,0,1]
	v_pk_fma_f32 v[38:39], v[230:231], s[24:25], v[38:39] op_sel_hi:[1,0,1]
	v_pk_fma_f32 v[40:41], v[232:233], s[24:25], v[40:41] op_sel_hi:[1,0,1]
	v_pk_fma_f32 v[42:43], v[234:235], s[24:25], v[42:43] op_sel_hi:[1,0,1]
	v_pk_fma_f32 v[44:45], v[236:237], s[24:25], v[44:45] op_sel_hi:[1,0,1]
	v_pk_fma_f32 v[46:47], v[238:239], s[24:25], v[46:47] op_sel_hi:[1,0,1]
	v_cvt_pk_f32_fp8_e32 v[224:225], v180
	v_cvt_pk_f32_fp8_sdwa v[226:227], v180 src0_sel:WORD_1
	v_cvt_pk_f32_fp8_e32 v[228:229], v181
	v_cvt_pk_f32_fp8_sdwa v[230:231], v181 src0_sel:WORD_1
	v_cvt_pk_f32_fp8_e32 v[232:233], v182
	v_cvt_pk_f32_fp8_sdwa v[234:235], v182 src0_sel:WORD_1
	v_cvt_pk_f32_fp8_e32 v[236:237], v183
	v_cvt_pk_f32_fp8_sdwa v[238:239], v183 src0_sel:WORD_1
	v_pk_fma_f32 v[32:33], v[224:225], s[26:27], v[32:33] op_sel_hi:[1,0,1]
	v_pk_fma_f32 v[34:35], v[226:227], s[26:27], v[34:35] op_sel_hi:[1,0,1]
	v_pk_fma_f32 v[36:37], v[228:229], s[26:27], v[36:37] op_sel_hi:[1,0,1]
	v_pk_fma_f32 v[38:39], v[230:231], s[26:27], v[38:39] op_sel_hi:[1,0,1]
	v_pk_fma_f32 v[40:41], v[232:233], s[26:27], v[40:41] op_sel_hi:[1,0,1]
	v_pk_fma_f32 v[42:43], v[234:235], s[26:27], v[42:43] op_sel_hi:[1,0,1]
	v_pk_fma_f32 v[44:45], v[236:237], s[26:27], v[44:45] op_sel_hi:[1,0,1]
	v_pk_fma_f32 v[46:47], v[238:239], s[26:27], v[46:47] op_sel_hi:[1,0,1]
	v_cvt_pk_f32_fp8_e32 v[224:225], v184
	v_cvt_pk_f32_fp8_sdwa v[226:227], v184 src0_sel:WORD_1
	v_cvt_pk_f32_fp8_e32 v[228:229], v185
	v_cvt_pk_f32_fp8_sdwa v[230:231], v185 src0_sel:WORD_1
	v_cvt_pk_f32_fp8_e32 v[232:233], v186
	v_cvt_pk_f32_fp8_sdwa v[234:235], v186 src0_sel:WORD_1
	v_cvt_pk_f32_fp8_e32 v[236:237], v187
	v_cvt_pk_f32_fp8_sdwa v[238:239], v187 src0_sel:WORD_1
	v_pk_fma_f32 v[32:33], v[224:225], s[28:29], v[32:33] op_sel_hi:[1,0,1]
	v_pk_fma_f32 v[34:35], v[226:227], s[28:29], v[34:35] op_sel_hi:[1,0,1]
	v_pk_fma_f32 v[36:37], v[228:229], s[28:29], v[36:37] op_sel_hi:[1,0,1]
	v_pk_fma_f32 v[38:39], v[230:231], s[28:29], v[38:39] op_sel_hi:[1,0,1]
	v_pk_fma_f32 v[40:41], v[232:233], s[28:29], v[40:41] op_sel_hi:[1,0,1]
	v_pk_fma_f32 v[42:43], v[234:235], s[28:29], v[42:43] op_sel_hi:[1,0,1]
	v_pk_fma_f32 v[44:45], v[236:237], s[28:29], v[44:45] op_sel_hi:[1,0,1]
	v_pk_fma_f32 v[46:47], v[238:239], s[28:29], v[46:47] op_sel_hi:[1,0,1]
	v_cvt_pk_f32_fp8_e32 v[224:225], v188
	v_cvt_pk_f32_fp8_sdwa v[226:227], v188 src0_sel:WORD_1
	v_cvt_pk_f32_fp8_e32 v[228:229], v189
	v_cvt_pk_f32_fp8_sdwa v[230:231], v189 src0_sel:WORD_1
	v_cvt_pk_f32_fp8_e32 v[232:233], v190
	v_cvt_pk_f32_fp8_sdwa v[234:235], v190 src0_sel:WORD_1
	v_cvt_pk_f32_fp8_e32 v[236:237], v191
	v_cvt_pk_f32_fp8_sdwa v[238:239], v191 src0_sel:WORD_1
	v_pk_fma_f32 v[32:33], v[224:225], s[30:31], v[32:33] op_sel_hi:[1,0,1]
	v_pk_fma_f32 v[34:35], v[226:227], s[30:31], v[34:35] op_sel_hi:[1,0,1]
	v_pk_fma_f32 v[36:37], v[228:229], s[30:31], v[36:37] op_sel_hi:[1,0,1]
	v_pk_fma_f32 v[38:39], v[230:231], s[30:31], v[38:39] op_sel_hi:[1,0,1]
	v_pk_fma_f32 v[40:41], v[232:233], s[30:31], v[40:41] op_sel_hi:[1,0,1]
	v_pk_fma_f32 v[42:43], v[234:235], s[30:31], v[42:43] op_sel_hi:[1,0,1]
	v_pk_fma_f32 v[44:45], v[236:237], s[30:31], v[44:45] op_sel_hi:[1,0,1]
	v_pk_fma_f32 v[46:47], v[238:239], s[30:31], v[46:47] op_sel_hi:[1,0,1]
	v_readlane_b32 s16, v142, s72
	v_readlane_b32 s18, v142, s73
	v_readlane_b32 s20, v142, s74
	v_readlane_b32 s22, v142, s75
	v_readlane_b32 s24, v142, s76
	v_readlane_b32 s26, v142, s77
	v_readlane_b32 s28, v142, s78
	v_readlane_b32 s30, v142, s79
	v_readlane_b32 s48, v129, s72
	v_readlane_b32 s49, v129, s73
	v_readlane_b32 s50, v129, s74
	v_readlane_b32 s51, v129, s75
	v_readlane_b32 s52, v129, s76
	v_readlane_b32 s53, v129, s77
	v_readlane_b32 s54, v129, s78
	v_readlane_b32 s55, v129, s79
	s_add_u32 s32, s0, s48
	s_addc_u32 s33, s1, 0
	s_add_u32 s34, s0, s49
	s_addc_u32 s35, s1, 0
	s_add_u32 s36, s0, s50
	s_addc_u32 s37, s1, 0
	s_add_u32 s38, s0, s51
	s_addc_u32 s39, s1, 0
	s_add_u32 s40, s0, s52
	s_addc_u32 s41, s1, 0
	s_add_u32 s42, s0, s53
	s_addc_u32 s43, s1, 0
	s_add_u32 s44, s0, s54
	s_addc_u32 s45, s1, 0
	s_add_u32 s46, s0, s55
	s_addc_u32 s47, s1, 0
	global_load_dwordx4 v[160:163], v240, s[32:33]
	global_load_dwordx4 v[164:167], v240, s[34:35]
	global_load_dwordx4 v[168:171], v240, s[36:37]
	global_load_dwordx4 v[172:175], v240, s[38:39]
	global_load_dwordx4 v[176:179], v240, s[40:41]
	global_load_dwordx4 v[180:183], v240, s[42:43]
	global_load_dwordx4 v[184:187], v240, s[44:45]
	global_load_dwordx4 v[188:191], v240, s[46:47]
	s_waitcnt vmcnt(8)
	v_cvt_pk_f32_fp8_e32 v[224:225], v192
	v_cvt_pk_f32_fp8_sdwa v[226:227], v192 src0_sel:WORD_1
	v_cvt_pk_f32_fp8_e32 v[228:229], v193
	v_cvt_pk_f32_fp8_sdwa v[230:231], v193 src0_sel:WORD_1
	v_cvt_pk_f32_fp8_e32 v[232:233], v194
	v_cvt_pk_f32_fp8_sdwa v[234:235], v194 src0_sel:WORD_1
	v_cvt_pk_f32_fp8_e32 v[236:237], v195
	v_cvt_pk_f32_fp8_sdwa v[238:239], v195 src0_sel:WORD_1
	v_pk_fma_f32 v[48:49], v[224:225], s[16:17], v[48:49] op_sel_hi:[1,0,1]
	v_pk_fma_f32 v[50:51], v[226:227], s[16:17], v[50:51] op_sel_hi:[1,0,1]
	v_pk_fma_f32 v[52:53], v[228:229], s[16:17], v[52:53] op_sel_hi:[1,0,1]
	v_pk_fma_f32 v[54:55], v[230:231], s[16:17], v[54:55] op_sel_hi:[1,0,1]
	v_pk_fma_f32 v[56:57], v[232:233], s[16:17], v[56:57] op_sel_hi:[1,0,1]
	v_pk_fma_f32 v[58:59], v[234:235], s[16:17], v[58:59] op_sel_hi:[1,0,1]
	v_pk_fma_f32 v[60:61], v[236:237], s[16:17], v[60:61] op_sel_hi:[1,0,1]
	v_pk_fma_f32 v[62:63], v[238:239], s[16:17], v[62:63] op_sel_hi:[1,0,1]
	v_cvt_pk_f32_fp8_e32 v[224:225], v196
	v_cvt_pk_f32_fp8_sdwa v[226:227], v196 src0_sel:WORD_1
	v_cvt_pk_f32_fp8_e32 v[228:229], v197
	v_cvt_pk_f32_fp8_sdwa v[230:231], v197 src0_sel:WORD_1
	v_cvt_pk_f32_fp8_e32 v[232:233], v198
	v_cvt_pk_f32_fp8_sdwa v[234:235], v198 src0_sel:WORD_1
	v_cvt_pk_f32_fp8_e32 v[236:237], v199
	v_cvt_pk_f32_fp8_sdwa v[238:239], v199 src0_sel:WORD_1
	v_pk_fma_f32 v[48:49], v[224:225], s[18:19], v[48:49] op_sel_hi:[1,0,1]
	v_pk_fma_f32 v[50:51], v[226:227], s[18:19], v[50:51] op_sel_hi:[1,0,1]
	v_pk_fma_f32 v[52:53], v[228:229], s[18:19], v[52:53] op_sel_hi:[1,0,1]
	v_pk_fma_f32 v[54:55], v[230:231], s[18:19], v[54:55] op_sel_hi:[1,0,1]
	v_pk_fma_f32 v[56:57], v[232:233], s[18:19], v[56:57] op_sel_hi:[1,0,1]
	v_pk_fma_f32 v[58:59], v[234:235], s[18:19], v[58:59] op_sel_hi:[1,0,1]
	v_pk_fma_f32 v[60:61], v[236:237], s[18:19], v[60:61] op_sel_hi:[1,0,1]
	v_pk_fma_f32 v[62:63], v[238:239], s[18:19], v[62:63] op_sel_hi:[1,0,1]
	v_cvt_pk_f32_fp8_e32 v[224:225], v200
	v_cvt_pk_f32_fp8_sdwa v[226:227], v200 src0_sel:WORD_1
	v_cvt_pk_f32_fp8_e32 v[228:229], v201
	v_cvt_pk_f32_fp8_sdwa v[230:231], v201 src0_sel:WORD_1
	v_cvt_pk_f32_fp8_e32 v[232:233], v202
	v_cvt_pk_f32_fp8_sdwa v[234:235], v202 src0_sel:WORD_1
	v_cvt_pk_f32_fp8_e32 v[236:237], v203
	v_cvt_pk_f32_fp8_sdwa v[238:239], v203 src0_sel:WORD_1
	v_pk_fma_f32 v[48:49], v[224:225], s[20:21], v[48:49] op_sel_hi:[1,0,1]
	v_pk_fma_f32 v[50:51], v[226:227], s[20:21], v[50:51] op_sel_hi:[1,0,1]
	v_pk_fma_f32 v[52:53], v[228:229], s[20:21], v[52:53] op_sel_hi:[1,0,1]
	v_pk_fma_f32 v[54:55], v[230:231], s[20:21], v[54:55] op_sel_hi:[1,0,1]
	v_pk_fma_f32 v[56:57], v[232:233], s[20:21], v[56:57] op_sel_hi:[1,0,1]
	v_pk_fma_f32 v[58:59], v[234:235], s[20:21], v[58:59] op_sel_hi:[1,0,1]
	v_pk_fma_f32 v[60:61], v[236:237], s[20:21], v[60:61] op_sel_hi:[1,0,1]
	v_pk_fma_f32 v[62:63], v[238:239], s[20:21], v[62:63] op_sel_hi:[1,0,1]
	v_cvt_pk_f32_fp8_e32 v[224:225], v204
	v_cvt_pk_f32_fp8_sdwa v[226:227], v204 src0_sel:WORD_1
	v_cvt_pk_f32_fp8_e32 v[228:229], v205
	v_cvt_pk_f32_fp8_sdwa v[230:231], v205 src0_sel:WORD_1
	v_cvt_pk_f32_fp8_e32 v[232:233], v206
	v_cvt_pk_f32_fp8_sdwa v[234:235], v206 src0_sel:WORD_1
	v_cvt_pk_f32_fp8_e32 v[236:237], v207
	v_cvt_pk_f32_fp8_sdwa v[238:239], v207 src0_sel:WORD_1
	v_pk_fma_f32 v[48:49], v[224:225], s[22:23], v[48:49] op_sel_hi:[1,0,1]
	v_pk_fma_f32 v[50:51], v[226:227], s[22:23], v[50:51] op_sel_hi:[1,0,1]
	v_pk_fma_f32 v[52:53], v[228:229], s[22:23], v[52:53] op_sel_hi:[1,0,1]
	v_pk_fma_f32 v[54:55], v[230:231], s[22:23], v[54:55] op_sel_hi:[1,0,1]
	v_pk_fma_f32 v[56:57], v[232:233], s[22:23], v[56:57] op_sel_hi:[1,0,1]
	v_pk_fma_f32 v[58:59], v[234:235], s[22:23], v[58:59] op_sel_hi:[1,0,1]
	v_pk_fma_f32 v[60:61], v[236:237], s[22:23], v[60:61] op_sel_hi:[1,0,1]
	v_pk_fma_f32 v[62:63], v[238:239], s[22:23], v[62:63] op_sel_hi:[1,0,1]
	v_cvt_pk_f32_fp8_e32 v[224:225], v208
	v_cvt_pk_f32_fp8_sdwa v[226:227], v208 src0_sel:WORD_1
	v_cvt_pk_f32_fp8_e32 v[228:229], v209
	v_cvt_pk_f32_fp8_sdwa v[230:231], v209 src0_sel:WORD_1
	v_cvt_pk_f32_fp8_e32 v[232:233], v210
	v_cvt_pk_f32_fp8_sdwa v[234:235], v210 src0_sel:WORD_1
	v_cvt_pk_f32_fp8_e32 v[236:237], v211
	v_cvt_pk_f32_fp8_sdwa v[238:239], v211 src0_sel:WORD_1
	v_pk_fma_f32 v[48:49], v[224:225], s[24:25], v[48:49] op_sel_hi:[1,0,1]
	v_pk_fma_f32 v[50:51], v[226:227], s[24:25], v[50:51] op_sel_hi:[1,0,1]
	v_pk_fma_f32 v[52:53], v[228:229], s[24:25], v[52:53] op_sel_hi:[1,0,1]
	v_pk_fma_f32 v[54:55], v[230:231], s[24:25], v[54:55] op_sel_hi:[1,0,1]
	v_pk_fma_f32 v[56:57], v[232:233], s[24:25], v[56:57] op_sel_hi:[1,0,1]
	v_pk_fma_f32 v[58:59], v[234:235], s[24:25], v[58:59] op_sel_hi:[1,0,1]
	v_pk_fma_f32 v[60:61], v[236:237], s[24:25], v[60:61] op_sel_hi:[1,0,1]
	v_pk_fma_f32 v[62:63], v[238:239], s[24:25], v[62:63] op_sel_hi:[1,0,1]
	v_cvt_pk_f32_fp8_e32 v[224:225], v212
	v_cvt_pk_f32_fp8_sdwa v[226:227], v212 src0_sel:WORD_1
	v_cvt_pk_f32_fp8_e32 v[228:229], v213
	v_cvt_pk_f32_fp8_sdwa v[230:231], v213 src0_sel:WORD_1
	v_cvt_pk_f32_fp8_e32 v[232:233], v214
	v_cvt_pk_f32_fp8_sdwa v[234:235], v214 src0_sel:WORD_1
	v_cvt_pk_f32_fp8_e32 v[236:237], v215
	v_cvt_pk_f32_fp8_sdwa v[238:239], v215 src0_sel:WORD_1
	v_pk_fma_f32 v[48:49], v[224:225], s[26:27], v[48:49] op_sel_hi:[1,0,1]
	v_pk_fma_f32 v[50:51], v[226:227], s[26:27], v[50:51] op_sel_hi:[1,0,1]
	v_pk_fma_f32 v[52:53], v[228:229], s[26:27], v[52:53] op_sel_hi:[1,0,1]
	v_pk_fma_f32 v[54:55], v[230:231], s[26:27], v[54:55] op_sel_hi:[1,0,1]
	v_pk_fma_f32 v[56:57], v[232:233], s[26:27], v[56:57] op_sel_hi:[1,0,1]
	v_pk_fma_f32 v[58:59], v[234:235], s[26:27], v[58:59] op_sel_hi:[1,0,1]
; DI void peer_item_v(const Params& p, int item) {
;     ...
;     V_ISSUE(vqa, 0)
; #pragma unroll 1
;     for (int g = 0; g < 16; g += 2) {
;       V_ISSUE(vqb, g + 1)
;       V_CONSUME(vqa, g)
;       if (g + 2 < 16) V_ISSUE(vqa, g + 2)
;       V_CONSUME(vqb, g + 1)
;     }
	v_pk_fma_f32 v[60:61], v[236:237], s[26:27], v[60:61] op_sel_hi:[1,0,1]
	v_pk_fma_f32 v[62:63], v[238:239], s[26:27], v[62:63] op_sel_hi:[1,0,1]
	v_cvt_pk_f32_fp8_e32 v[224:225], v216
	v_cvt_pk_f32_fp8_sdwa v[226:227], v216 src0_sel:WORD_1
	v_cvt_pk_f32_fp8_e32 v[228:229], v217
	v_cvt_pk_f32_fp8_sdwa v[230:231], v217 src0_sel:WORD_1
	v_cvt_pk_f32_fp8_e32 v[232:233], v218
	v_cvt_pk_f32_fp8_sdwa v[234:235], v218 src0_sel:WORD_1
	v_cvt_pk_f32_fp8_e32 v[236:237], v219
	v_cvt_pk_f32_fp8_sdwa v[238:239], v219 src0_sel:WORD_1
	v_pk_fma_f32 v[48:49], v[224:225], s[28:29], v[48:49] op_sel_hi:[1,0,1]
	v_pk_fma_f32 v[50:51], v[226:227], s[28:29], v[50:51] op_sel_hi:[1,0,1]
	v_pk_fma_f32 v[52:53], v[228:229], s[28:29], v[52:53] op_sel_hi:[1,0,1]
	v_pk_fma_f32 v[54:55], v[230:231], s[28:29], v[54:55] op_sel_hi:[1,0,1]
	v_pk_fma_f32 v[56:57], v[232:233], s[28:29], v[56:57] op_sel_hi:[1,0,1]
	v_pk_fma_f32 v[58:59], v[234:235], s[28:29], v[58:59] op_sel_hi:[1,0,1]
	v_pk_fma_f32 v[60:61], v[236:237], s[28:29], v[60:61] op_sel_hi:[1,0,1]
	v_pk_fma_f32 v[62:63], v[238:239], s[28:29], v[62:63] op_sel_hi:[1,0,1]
	v_cvt_pk_f32_fp8_e32 v[224:225], v220
	v_cvt_pk_f32_fp8_sdwa v[226:227], v220 src0_sel:WORD_1
	v_cvt_pk_f32_fp8_e32 v[228:229], v221
	v_cvt_pk_f32_fp8_sdwa v[230:231], v221 src0_sel:WORD_1
	v_cvt_pk_f32_fp8_e32 v[232:233], v222
	v_cvt_pk_f32_fp8_sdwa v[234:235], v222 src0_sel:WORD_1
	v_cvt_pk_f32_fp8_e32 v[236:237], v223
	v_cvt_pk_f32_fp8_sdwa v[238:239], v223 src0_sel:WORD_1
	v_pk_fma_f32 v[48:49], v[224:225], s[30:31], v[48:49] op_sel_hi:[1,0,1]
	v_pk_fma_f32 v[50:51], v[226:227], s[30:31], v[50:51] op_sel_hi:[1,0,1]
	v_pk_fma_f32 v[52:53], v[228:229], s[30:31], v[52:53] op_sel_hi:[1,0,1]
	v_pk_fma_f32 v[54:55], v[230:231], s[30:31], v[54:55] op_sel_hi:[1,0,1]
	v_pk_fma_f32 v[56:57], v[232:233], s[30:31], v[56:57] op_sel_hi:[1,0,1]
	v_pk_fma_f32 v[58:59], v[234:235], s[30:31], v[58:59] op_sel_hi:[1,0,1]
	v_pk_fma_f32 v[60:61], v[236:237], s[30:31], v[60:61] op_sel_hi:[1,0,1]
	v_pk_fma_f32 v[62:63], v[238:239], s[30:31], v[62:63] op_sel_hi:[1,0,1]
	v_readlane_b32 s16, v131, s72
	v_readlane_b32 s18, v131, s73
	v_readlane_b32 s20, v131, s74
	v_readlane_b32 s22, v131, s75
	v_readlane_b32 s24, v131, s76
	v_readlane_b32 s26, v131, s77
	v_readlane_b32 s28, v131, s78
	v_readlane_b32 s30, v131, s79
	v_readlane_b32 s48, v133, s72
	v_readlane_b32 s49, v133, s73
	v_readlane_b32 s50, v133, s74
	v_readlane_b32 s51, v133, s75
	v_readlane_b32 s52, v133, s76
	v_readlane_b32 s53, v133, s77
	v_readlane_b32 s54, v133, s78
	v_readlane_b32 s55, v133, s79
	s_add_u32 s32, s0, s48
	s_addc_u32 s33, s1, 0
	s_add_u32 s34, s0, s49
	s_addc_u32 s35, s1, 0
	s_add_u32 s36, s0, s50
	s_addc_u32 s37, s1, 0
	s_add_u32 s38, s0, s51
	s_addc_u32 s39, s1, 0
	s_add_u32 s40, s0, s52
	s_addc_u32 s41, s1, 0
	s_add_u32 s42, s0, s53
	s_addc_u32 s43, s1, 0
	s_add_u32 s44, s0, s54
	s_addc_u32 s45, s1, 0
	s_add_u32 s46, s0, s55
	s_addc_u32 s47, s1, 0
	global_load_dwordx4 v[192:195], v240, s[32:33]
	global_load_dwordx4 v[196:199], v240, s[34:35]
	global_load_dwordx4 v[200:203], v240, s[36:37]
	global_load_dwordx4 v[204:207], v240, s[38:39]
	global_load_dwordx4 v[208:211], v240, s[40:41]
	global_load_dwordx4 v[212:215], v240, s[42:43]
	global_load_dwordx4 v[216:219], v240, s[44:45]
	global_load_dwordx4 v[220:223], v240, s[46:47]
	s_waitcnt vmcnt(8)
	v_cvt_pk_f32_fp8_e32 v[224:225], v160
	v_cvt_pk_f32_fp8_sdwa v[226:227], v160 src0_sel:WORD_1
	v_cvt_pk_f32_fp8_e32 v[228:229], v161
	v_cvt_pk_f32_fp8_sdwa v[230:231], v161 src0_sel:WORD_1
	v_cvt_pk_f32_fp8_e32 v[232:233], v162
	v_cvt_pk_f32_fp8_sdwa v[234:235], v162 src0_sel:WORD_1
	v_cvt_pk_f32_fp8_e32 v[236:237], v163
	v_cvt_pk_f32_fp8_sdwa v[238:239], v163 src0_sel:WORD_1
	v_pk_fma_f32 v[0:1], v[224:225], s[16:17], v[0:1] op_sel_hi:[1,0,1]
	v_pk_fma_f32 v[2:3], v[226:227], s[16:17], v[2:3] op_sel_hi:[1,0,1]
	v_pk_fma_f32 v[4:5], v[228:229], s[16:17], v[4:5] op_sel_hi:[1,0,1]
	v_pk_fma_f32 v[6:7], v[230:231], s[16:17], v[6:7] op_sel_hi:[1,0,1]
	v_pk_fma_f32 v[8:9], v[232:233], s[16:17], v[8:9] op_sel_hi:[1,0,1]
	v_pk_fma_f32 v[10:11], v[234:235], s[16:17], v[10:11] op_sel_hi:[1,0,1]
	v_pk_fma_f32 v[12:13], v[236:237], s[16:17], v[12:13] op_sel_hi:[1,0,1]
	v_pk_fma_f32 v[14:15], v[238:239], s[16:17], v[14:15] op_sel_hi:[1,0,1]
	v_cvt_pk_f32_fp8_e32 v[224:225], v164
	v_cvt_pk_f32_fp8_sdwa v[226:227], v164 src0_sel:WORD_1
	v_cvt_pk_f32_fp8_e32 v[228:229], v165
	v_cvt_pk_f32_fp8_sdwa v[230:231], v165 src0_sel:WORD_1
	v_cvt_pk_f32_fp8_e32 v[232:233], v166
	v_cvt_pk_f32_fp8_sdwa v[234:235], v166 src0_sel:WORD_1
	v_cvt_pk_f32_fp8_e32 v[236:237], v167
	v_cvt_pk_f32_fp8_sdwa v[238:239], v167 src0_sel:WORD_1
	v_pk_fma_f32 v[0:1], v[224:225], s[18:19], v[0:1] op_sel_hi:[1,0,1]
	v_pk_fma_f32 v[2:3], v[226:227], s[18:19], v[2:3] op_sel_hi:[1,0,1]
	v_pk_fma_f32 v[4:5], v[228:229], s[18:19], v[4:5] op_sel_hi:[1,0,1]
	v_pk_fma_f32 v[6:7], v[230:231], s[18:19], v[6:7] op_sel_hi:[1,0,1]
	v_pk_fma_f32 v[8:9], v[232:233], s[18:19], v[8:9] op_sel_hi:[1,0,1]
	v_pk_fma_f32 v[10:11], v[234:235], s[18:19], v[10:11] op_sel_hi:[1,0,1]
	v_pk_fma_f32 v[12:13], v[236:237], s[18:19], v[12:13] op_sel_hi:[1,0,1]
	v_pk_fma_f32 v[14:15], v[238:239], s[18:19], v[14:15] op_sel_hi:[1,0,1]
	v_cvt_pk_f32_fp8_e32 v[224:225], v168
	v_cvt_pk_f32_fp8_sdwa v[226:227], v168 src0_sel:WORD_1
	v_cvt_pk_f32_fp8_e32 v[228:229], v169
	v_cvt_pk_f32_fp8_sdwa v[230:231], v169 src0_sel:WORD_1
	v_cvt_pk_f32_fp8_e32 v[232:233], v170
	v_cvt_pk_f32_fp8_sdwa v[234:235], v170 src0_sel:WORD_1
	v_cvt_pk_f32_fp8_e32 v[236:237], v171
	v_cvt_pk_f32_fp8_sdwa v[238:239], v171 src0_sel:WORD_1
; DI void peer_item_v(const Params& p, int item) {
;     ...
;     V_ISSUE(vqa, 0)
; #pragma unroll 1
;     for (int g = 0; g < 16; g += 2) {
;       V_ISSUE(vqb, g + 1)
;       V_CONSUME(vqa, g)
;       if (g + 2 < 16) V_ISSUE(vqa, g + 2)
;       V_CONSUME(vqb, g + 1)
;     }
	v_pk_fma_f32 v[0:1], v[224:225], s[20:21], v[0:1] op_sel_hi:[1,0,1]
	v_pk_fma_f32 v[2:3], v[226:227], s[20:21], v[2:3] op_sel_hi:[1,0,1]
	v_pk_fma_f32 v[4:5], v[228:229], s[20:21], v[4:5] op_sel_hi:[1,0,1]
	v_pk_fma_f32 v[6:7], v[230:231], s[20:21], v[6:7] op_sel_hi:[1,0,1]
	v_pk_fma_f32 v[8:9], v[232:233], s[20:21], v[8:9] op_sel_hi:[1,0,1]
	v_pk_fma_f32 v[10:11], v[234:235], s[20:21], v[10:11] op_sel_hi:[1,0,1]
	v_pk_fma_f32 v[12:13], v[236:237], s[20:21], v[12:13] op_sel_hi:[1,0,1]
	v_pk_fma_f32 v[14:15], v[238:239], s[20:21], v[14:15] op_sel_hi:[1,0,1]
	v_cvt_pk_f32_fp8_e32 v[224:225], v172
	v_cvt_pk_f32_fp8_sdwa v[226:227], v172 src0_sel:WORD_1
	v_cvt_pk_f32_fp8_e32 v[228:229], v173
	v_cvt_pk_f32_fp8_sdwa v[230:231], v173 src0_sel:WORD_1
	v_cvt_pk_f32_fp8_e32 v[232:233], v174
	v_cvt_pk_f32_fp8_sdwa v[234:235], v174 src0_sel:WORD_1
	v_cvt_pk_f32_fp8_e32 v[236:237], v175
	v_cvt_pk_f32_fp8_sdwa v[238:239], v175 src0_sel:WORD_1
	v_pk_fma_f32 v[0:1], v[224:225], s[22:23], v[0:1] op_sel_hi:[1,0,1]
	v_pk_fma_f32 v[2:3], v[226:227], s[22:23], v[2:3] op_sel_hi:[1,0,1]
	v_pk_fma_f32 v[4:5], v[228:229], s[22:23], v[4:5] op_sel_hi:[1,0,1]
	v_pk_fma_f32 v[6:7], v[230:231], s[22:23], v[6:7] op_sel_hi:[1,0,1]
	v_pk_fma_f32 v[8:9], v[232:233], s[22:23], v[8:9] op_sel_hi:[1,0,1]
	v_pk_fma_f32 v[10:11], v[234:235], s[22:23], v[10:11] op_sel_hi:[1,0,1]
	v_pk_fma_f32 v[12:13], v[236:237], s[22:23], v[12:13] op_sel_hi:[1,0,1]
	v_pk_fma_f32 v[14:15], v[238:239], s[22:23], v[14:15] op_sel_hi:[1,0,1]
	v_cvt_pk_f32_fp8_e32 v[224:225], v176
	v_cvt_pk_f32_fp8_sdwa v[226:227], v176 src0_sel:WORD_1
	v_cvt_pk_f32_fp8_e32 v[228:229], v177
	v_cvt_pk_f32_fp8_sdwa v[230:231], v177 src0_sel:WORD_1
	v_cvt_pk_f32_fp8_e32 v[232:233], v178
	v_cvt_pk_f32_fp8_sdwa v[234:235], v178 src0_sel:WORD_1
	v_cvt_pk_f32_fp8_e32 v[236:237], v179
	v_cvt_pk_f32_fp8_sdwa v[238:239], v179 src0_sel:WORD_1
	v_pk_fma_f32 v[0:1], v[224:225], s[24:25], v[0:1] op_sel_hi:[1,0,1]
	v_pk_fma_f32 v[2:3], v[226:227], s[24:25], v[2:3] op_sel_hi:[1,0,1]
	v_pk_fma_f32 v[4:5], v[228:229], s[24:25], v[4:5] op_sel_hi:[1,0,1]
	v_pk_fma_f32 v[6:7], v[230:231], s[24:25], v[6:7] op_sel_hi:[1,0,1]
	v_pk_fma_f32 v[8:9], v[232:233], s[24:25], v[8:9] op_sel_hi:[1,0,1]
	v_pk_fma_f32 v[10:11], v[234:235], s[24:25], v[10:11] op_sel_hi:[1,0,1]
	v_pk_fma_f32 v[12:13], v[236:237], s[24:25], v[12:13] op_sel_hi:[1,0,1]
	v_pk_fma_f32 v[14:15], v[238:239], s[24:25], v[14:15] op_sel_hi:[1,0,1]
	v_cvt_pk_f32_fp8_e32 v[224:225], v180
	v_cvt_pk_f32_fp8_sdwa v[226:227], v180 src0_sel:WORD_1
	v_cvt_pk_f32_fp8_e32 v[228:229], v181
	v_cvt_pk_f32_fp8_sdwa v[230:231], v181 src0_sel:WORD_1
	v_cvt_pk_f32_fp8_e32 v[232:233], v182
	v_cvt_pk_f32_fp8_sdwa v[234:235], v182 src0_sel:WORD_1
	v_cvt_pk_f32_fp8_e32 v[236:237], v183
	v_cvt_pk_f32_fp8_sdwa v[238:239], v183 src0_sel:WORD_1
	v_pk_fma_f32 v[0:1], v[224:225], s[26:27], v[0:1] op_sel_hi:[1,0,1]
	v_pk_fma_f32 v[2:3], v[226:227], s[26:27], v[2:3] op_sel_hi:[1,0,1]
	v_pk_fma_f32 v[4:5], v[228:229], s[26:27], v[4:5] op_sel_hi:[1,0,1]
	v_pk_fma_f32 v[6:7], v[230:231], s[26:27], v[6:7] op_sel_hi:[1,0,1]
	v_pk_fma_f32 v[8:9], v[232:233], s[26:27], v[8:9] op_sel_hi:[1,0,1]
	v_pk_fma_f32 v[10:11], v[234:235], s[26:27], v[10:11] op_sel_hi:[1,0,1]
	v_pk_fma_f32 v[12:13], v[236:237], s[26:27], v[12:13] op_sel_hi:[1,0,1]
	v_pk_fma_f32 v[14:15], v[238:239], s[26:27], v[14:15] op_sel_hi:[1,0,1]
	v_cvt_pk_f32_fp8_e32 v[224:225], v184
	v_cvt_pk_f32_fp8_sdwa v[226:227], v184 src0_sel:WORD_1
	v_cvt_pk_f32_fp8_e32 v[228:229], v185
	v_cvt_pk_f32_fp8_sdwa v[230:231], v185 src0_sel:WORD_1
	v_cvt_pk_f32_fp8_e32 v[232:233], v186
	v_cvt_pk_f32_fp8_sdwa v[234:235], v186 src0_sel:WORD_1
	v_cvt_pk_f32_fp8_e32 v[236:237], v187
	v_cvt_pk_f32_fp8_sdwa v[238:239], v187 src0_sel:WORD_1
	v_pk_fma_f32 v[0:1], v[224:225], s[28:29], v[0:1] op_sel_hi:[1,0,1]
	v_pk_fma_f32 v[2:3], v[226:227], s[28:29], v[2:3] op_sel_hi:[1,0,1]
	v_pk_fma_f32 v[4:5], v[228:229], s[28:29], v[4:5] op_sel_hi:[1,0,1]
	v_pk_fma_f32 v[6:7], v[230:231], s[28:29], v[6:7] op_sel_hi:[1,0,1]
	v_pk_fma_f32 v[8:9], v[232:233], s[28:29], v[8:9] op_sel_hi:[1,0,1]
	v_pk_fma_f32 v[10:11], v[234:235], s[28:29], v[10:11] op_sel_hi:[1,0,1]
	v_pk_fma_f32 v[12:13], v[236:237], s[28:29], v[12:13] op_sel_hi:[1,0,1]
	v_pk_fma_f32 v[14:15], v[238:239], s[28:29], v[14:15] op_sel_hi:[1,0,1]
	v_cvt_pk_f32_fp8_e32 v[224:225], v188
	v_cvt_pk_f32_fp8_sdwa v[226:227], v188 src0_sel:WORD_1
	v_cvt_pk_f32_fp8_e32 v[228:229], v189
	v_cvt_pk_f32_fp8_sdwa v[230:231], v189 src0_sel:WORD_1
	v_cvt_pk_f32_fp8_e32 v[232:233], v190
	v_cvt_pk_f32_fp8_sdwa v[234:235], v190 src0_sel:WORD_1
	v_cvt_pk_f32_fp8_e32 v[236:237], v191
	v_cvt_pk_f32_fp8_sdwa v[238:239], v191 src0_sel:WORD_1
	v_pk_fma_f32 v[0:1], v[224:225], s[30:31], v[0:1] op_sel_hi:[1,0,1]
	v_pk_fma_f32 v[2:3], v[226:227], s[30:31], v[2:3] op_sel_hi:[1,0,1]
	v_pk_fma_f32 v[4:5], v[228:229], s[30:31], v[4:5] op_sel_hi:[1,0,1]
	v_pk_fma_f32 v[6:7], v[230:231], s[30:31], v[6:7] op_sel_hi:[1,0,1]
	v_pk_fma_f32 v[8:9], v[232:233], s[30:31], v[8:9] op_sel_hi:[1,0,1]
	v_pk_fma_f32 v[10:11], v[234:235], s[30:31], v[10:11] op_sel_hi:[1,0,1]
	v_pk_fma_f32 v[12:13], v[236:237], s[30:31], v[12:13] op_sel_hi:[1,0,1]
	v_pk_fma_f32 v[14:15], v[238:239], s[30:31], v[14:15] op_sel_hi:[1,0,1]
	v_readlane_b32 s16, v135, s72
	v_readlane_b32 s18, v135, s73
	v_readlane_b32 s20, v135, s74
	v_readlane_b32 s22, v135, s75
	v_readlane_b32 s24, v135, s76
	v_readlane_b32 s26, v135, s77
	v_readlane_b32 s28, v135, s78
	v_readlane_b32 s30, v135, s79
	v_readlane_b32 s48, v137, s72
	v_readlane_b32 s49, v137, s73
	v_readlane_b32 s50, v137, s74
	v_readlane_b32 s51, v137, s75
	v_readlane_b32 s52, v137, s76
	v_readlane_b32 s53, v137, s77
	v_readlane_b32 s54, v137, s78
	v_readlane_b32 s55, v137, s79
	s_add_u32 s32, s0, s48
	s_addc_u32 s33, s1, 0
	s_add_u32 s34, s0, s49
	s_addc_u32 s35, s1, 0
	s_add_u32 s36, s0, s50
	s_addc_u32 s37, s1, 0
	s_add_u32 s38, s0, s51
	s_addc_u32 s39, s1, 0
	s_add_u32 s40, s0, s52
	s_addc_u32 s41, s1, 0
	s_add_u32 s42, s0, s53
	s_addc_u32 s43, s1, 0
	s_add_u32 s44, s0, s54
	s_addc_u32 s45, s1, 0
	s_add_u32 s46, s0, s55
	s_addc_u32 s47, s1, 0
	global_load_dwordx4 v[160:163], v240, s[32:33]
	global_load_dwordx4 v[164:167], v240, s[34:35]
	global_load_dwordx4 v[168:171], v240, s[36:37]
	global_load_dwordx4 v[172:175], v240, s[38:39]
	global_load_dwordx4 v[176:179], v240, s[40:41]
	global_load_dwordx4 v[180:183], v240, s[42:43]
	global_load_dwordx4 v[184:187], v240, s[44:45]
	global_load_dwordx4 v[188:191], v240, s[46:47]
	s_waitcnt vmcnt(8)
	v_cvt_pk_f32_fp8_e32 v[224:225], v192
	v_cvt_pk_f32_fp8_sdwa v[226:227], v192 src0_sel:WORD_1
	v_cvt_pk_f32_fp8_e32 v[228:229], v193
	v_cvt_pk_f32_fp8_sdwa v[230:231], v193 src0_sel:WORD_1
	v_cvt_pk_f32_fp8_e32 v[232:233], v194
	v_cvt_pk_f32_fp8_sdwa v[234:235], v194 src0_sel:WORD_1
	v_cvt_pk_f32_fp8_e32 v[236:237], v195
	v_cvt_pk_f32_fp8_sdwa v[238:239], v195 src0_sel:WORD_1
	v_pk_fma_f32 v[16:17], v[224:225], s[16:17], v[16:17] op_sel_hi:[1,0,1]
	v_pk_fma_f32 v[18:19], v[226:227], s[16:17], v[18:19] op_sel_hi:[1,0,1]
	v_pk_fma_f32 v[20:21], v[228:229], s[16:17], v[20:21] op_sel_hi:[1,0,1]
	v_pk_fma_f32 v[22:23], v[230:231], s[16:17], v[22:23] op_sel_hi:[1,0,1]
	v_pk_fma_f32 v[24:25], v[232:233], s[16:17], v[24:25] op_sel_hi:[1,0,1]
	v_pk_fma_f32 v[26:27], v[234:235], s[16:17], v[26:27] op_sel_hi:[1,0,1]
	v_pk_fma_f32 v[28:29], v[236:237], s[16:17], v[28:29] op_sel_hi:[1,0,1]
	v_pk_fma_f32 v[30:31], v[238:239], s[16:17], v[30:31] op_sel_hi:[1,0,1]
	v_cvt_pk_f32_fp8_e32 v[224:225], v196
	v_cvt_pk_f32_fp8_sdwa v[226:227], v196 src0_sel:WORD_1
	v_cvt_pk_f32_fp8_e32 v[228:229], v197
	v_cvt_pk_f32_fp8_sdwa v[230:231], v197 src0_sel:WORD_1
	v_cvt_pk_f32_fp8_e32 v[232:233], v198
	v_cvt_pk_f32_fp8_sdwa v[234:235], v198 src0_sel:WORD_1
	v_cvt_pk_f32_fp8_e32 v[236:237], v199
	v_cvt_pk_f32_fp8_sdwa v[238:239], v199 src0_sel:WORD_1
	v_pk_fma_f32 v[16:17], v[224:225], s[18:19], v[16:17] op_sel_hi:[1,0,1]
	v_pk_fma_f32 v[18:19], v[226:227], s[18:19], v[18:19] op_sel_hi:[1,0,1]
	v_pk_fma_f32 v[20:21], v[228:229], s[18:19], v[20:21] op_sel_hi:[1,0,1]
	v_pk_fma_f32 v[22:23], v[230:231], s[18:19], v[22:23] op_sel_hi:[1,0,1]
	v_pk_fma_f32 v[24:25], v[232:233], s[18:19], v[24:25] op_sel_hi:[1,0,1]
	v_pk_fma_f32 v[26:27], v[234:235], s[18:19], v[26:27] op_sel_hi:[1,0,1]
	v_pk_fma_f32 v[28:29], v[236:237], s[18:19], v[28:29] op_sel_hi:[1,0,1]
	v_pk_fma_f32 v[30:31], v[238:239], s[18:19], v[30:31] op_sel_hi:[1,0,1]
	v_cvt_pk_f32_fp8_e32 v[224:225], v200
	v_cvt_pk_f32_fp8_sdwa v[226:227], v200 src0_sel:WORD_1
	v_cvt_pk_f32_fp8_e32 v[228:229], v201
	v_cvt_pk_f32_fp8_sdwa v[230:231], v201 src0_sel:WORD_1
	v_cvt_pk_f32_fp8_e32 v[232:233], v202
	v_cvt_pk_f32_fp8_sdwa v[234:235], v202 src0_sel:WORD_1
	v_cvt_pk_f32_fp8_e32 v[236:237], v203
	v_cvt_pk_f32_fp8_sdwa v[238:239], v203 src0_sel:WORD_1
	v_pk_fma_f32 v[16:17], v[224:225], s[20:21], v[16:17] op_sel_hi:[1,0,1]
	v_pk_fma_f32 v[18:19], v[226:227], s[20:21], v[18:19] op_sel_hi:[1,0,1]
	v_pk_fma_f32 v[20:21], v[228:229], s[20:21], v[20:21] op_sel_hi:[1,0,1]
	v_pk_fma_f32 v[22:23], v[230:231], s[20:21], v[22:23] op_sel_hi:[1,0,1]
	v_pk_fma_f32 v[24:25], v[232:233], s[20:21], v[24:25] op_sel_hi:[1,0,1]
	v_pk_fma_f32 v[26:27], v[234:235], s[20:21], v[26:27] op_sel_hi:[1,0,1]
	v_pk_fma_f32 v[28:29], v[236:237], s[20:21], v[28:29] op_sel_hi:[1,0,1]
	v_pk_fma_f32 v[30:31], v[238:239], s[20:21], v[30:31] op_sel_hi:[1,0,1]
	v_cvt_pk_f32_fp8_e32 v[224:225], v204
	v_cvt_pk_f32_fp8_sdwa v[226:227], v204 src0_sel:WORD_1
	v_cvt_pk_f32_fp8_e32 v[228:229], v205
	v_cvt_pk_f32_fp8_sdwa v[230:231], v205 src0_sel:WORD_1
	v_cvt_pk_f32_fp8_e32 v[232:233], v206
	v_cvt_pk_f32_fp8_sdwa v[234:235], v206 src0_sel:WORD_1
	v_cvt_pk_f32_fp8_e32 v[236:237], v207
	v_cvt_pk_f32_fp8_sdwa v[238:239], v207 src0_sel:WORD_1
	v_pk_fma_f32 v[16:17], v[224:225], s[22:23], v[16:17] op_sel_hi:[1,0,1]
	v_pk_fma_f32 v[18:19], v[226:227], s[22:23], v[18:19] op_sel_hi:[1,0,1]
	v_pk_fma_f32 v[20:21], v[228:229], s[22:23], v[20:21] op_sel_hi:[1,0,1]
	v_pk_fma_f32 v[22:23], v[230:231], s[22:23], v[22:23] op_sel_hi:[1,0,1]
	v_pk_fma_f32 v[24:25], v[232:233], s[22:23], v[24:25] op_sel_hi:[1,0,1]
	v_pk_fma_f32 v[26:27], v[234:235], s[22:23], v[26:27] op_sel_hi:[1,0,1]
	v_pk_fma_f32 v[28:29], v[236:237], s[22:23], v[28:29] op_sel_hi:[1,0,1]
	v_pk_fma_f32 v[30:31], v[238:239], s[22:23], v[30:31] op_sel_hi:[1,0,1]
	v_cvt_pk_f32_fp8_e32 v[224:225], v208
	v_cvt_pk_f32_fp8_sdwa v[226:227], v208 src0_sel:WORD_1
	v_cvt_pk_f32_fp8_e32 v[228:229], v209
	v_cvt_pk_f32_fp8_sdwa v[230:231], v209 src0_sel:WORD_1
	v_cvt_pk_f32_fp8_e32 v[232:233], v210
	v_cvt_pk_f32_fp8_sdwa v[234:235], v210 src0_sel:WORD_1
	v_cvt_pk_f32_fp8_e32 v[236:237], v211
	v_cvt_pk_f32_fp8_sdwa v[238:239], v211 src0_sel:WORD_1
	v_pk_fma_f32 v[16:17], v[224:225], s[24:25], v[16:17] op_sel_hi:[1,0,1]
	v_pk_fma_f32 v[18:19], v[226:227], s[24:25], v[18:19] op_sel_hi:[1,0,1]
	v_pk_fma_f32 v[20:21], v[228:229], s[24:25], v[20:21] op_sel_hi:[1,0,1]
	v_pk_fma_f32 v[22:23], v[230:231], s[24:25], v[22:23] op_sel_hi:[1,0,1]
	v_pk_fma_f32 v[24:25], v[232:233], s[24:25], v[24:25] op_sel_hi:[1,0,1]
	v_pk_fma_f32 v[26:27], v[234:235], s[24:25], v[26:27] op_sel_hi:[1,0,1]
	v_pk_fma_f32 v[28:29], v[236:237], s[24:25], v[28:29] op_sel_hi:[1,0,1]
	v_pk_fma_f32 v[30:31], v[238:239], s[24:25], v[30:31] op_sel_hi:[1,0,1]
	v_cvt_pk_f32_fp8_e32 v[224:225], v212
	v_cvt_pk_f32_fp8_sdwa v[226:227], v212 src0_sel:WORD_1
	v_cvt_pk_f32_fp8_e32 v[228:229], v213
	v_cvt_pk_f32_fp8_sdwa v[230:231], v213 src0_sel:WORD_1
	v_cvt_pk_f32_fp8_e32 v[232:233], v214
	v_cvt_pk_f32_fp8_sdwa v[234:235], v214 src0_sel:WORD_1
	v_cvt_pk_f32_fp8_e32 v[236:237], v215
	v_cvt_pk_f32_fp8_sdwa v[238:239], v215 src0_sel:WORD_1
	v_pk_fma_f32 v[16:17], v[224:225], s[26:27], v[16:17] op_sel_hi:[1,0,1]
	v_pk_fma_f32 v[18:19], v[226:227], s[26:27], v[18:19] op_sel_hi:[1,0,1]
	v_pk_fma_f32 v[20:21], v[228:229], s[26:27], v[20:21] op_sel_hi:[1,0,1]
	v_pk_fma_f32 v[22:23], v[230:231], s[26:27], v[22:23] op_sel_hi:[1,0,1]
	v_pk_fma_f32 v[24:25], v[232:233], s[26:27], v[24:25] op_sel_hi:[1,0,1]
	v_pk_fma_f32 v[26:27], v[234:235], s[26:27], v[26:27] op_sel_hi:[1,0,1]
; DI void peer_item_v(const Params& p, int item) {
;     ...
;     V_ISSUE(vqa, 0)
; #pragma unroll 1
;     for (int g = 0; g < 16; g += 2) {
;       V_ISSUE(vqb, g + 1)
;       V_CONSUME(vqa, g)
;       if (g + 2 < 16) V_ISSUE(vqa, g + 2)
;       V_CONSUME(vqb, g + 1)
;     }
	v_pk_fma_f32 v[28:29], v[236:237], s[26:27], v[28:29] op_sel_hi:[1,0,1]
	v_pk_fma_f32 v[30:31], v[238:239], s[26:27], v[30:31] op_sel_hi:[1,0,1]
	v_cvt_pk_f32_fp8_e32 v[224:225], v216
	v_cvt_pk_f32_fp8_sdwa v[226:227], v216 src0_sel:WORD_1
	v_cvt_pk_f32_fp8_e32 v[228:229], v217
	v_cvt_pk_f32_fp8_sdwa v[230:231], v217 src0_sel:WORD_1
	v_cvt_pk_f32_fp8_e32 v[232:233], v218
	v_cvt_pk_f32_fp8_sdwa v[234:235], v218 src0_sel:WORD_1
	v_cvt_pk_f32_fp8_e32 v[236:237], v219
	v_cvt_pk_f32_fp8_sdwa v[238:239], v219 src0_sel:WORD_1
	v_pk_fma_f32 v[16:17], v[224:225], s[28:29], v[16:17] op_sel_hi:[1,0,1]
	v_pk_fma_f32 v[18:19], v[226:227], s[28:29], v[18:19] op_sel_hi:[1,0,1]
	v_pk_fma_f32 v[20:21], v[228:229], s[28:29], v[20:21] op_sel_hi:[1,0,1]
	v_pk_fma_f32 v[22:23], v[230:231], s[28:29], v[22:23] op_sel_hi:[1,0,1]
	v_pk_fma_f32 v[24:25], v[232:233], s[28:29], v[24:25] op_sel_hi:[1,0,1]
	v_pk_fma_f32 v[26:27], v[234:235], s[28:29], v[26:27] op_sel_hi:[1,0,1]
	v_pk_fma_f32 v[28:29], v[236:237], s[28:29], v[28:29] op_sel_hi:[1,0,1]
	v_pk_fma_f32 v[30:31], v[238:239], s[28:29], v[30:31] op_sel_hi:[1,0,1]
	v_cvt_pk_f32_fp8_e32 v[224:225], v220
	v_cvt_pk_f32_fp8_sdwa v[226:227], v220 src0_sel:WORD_1
	v_cvt_pk_f32_fp8_e32 v[228:229], v221
	v_cvt_pk_f32_fp8_sdwa v[230:231], v221 src0_sel:WORD_1
	v_cvt_pk_f32_fp8_e32 v[232:233], v222
	v_cvt_pk_f32_fp8_sdwa v[234:235], v222 src0_sel:WORD_1
	v_cvt_pk_f32_fp8_e32 v[236:237], v223
	v_cvt_pk_f32_fp8_sdwa v[238:239], v223 src0_sel:WORD_1
	v_pk_fma_f32 v[16:17], v[224:225], s[30:31], v[16:17] op_sel_hi:[1,0,1]
	v_pk_fma_f32 v[18:19], v[226:227], s[30:31], v[18:19] op_sel_hi:[1,0,1]
	v_pk_fma_f32 v[20:21], v[228:229], s[30:31], v[20:21] op_sel_hi:[1,0,1]
	v_pk_fma_f32 v[22:23], v[230:231], s[30:31], v[22:23] op_sel_hi:[1,0,1]
	v_pk_fma_f32 v[24:25], v[232:233], s[30:31], v[24:25] op_sel_hi:[1,0,1]
	v_pk_fma_f32 v[26:27], v[234:235], s[30:31], v[26:27] op_sel_hi:[1,0,1]
	v_pk_fma_f32 v[28:29], v[236:237], s[30:31], v[28:29] op_sel_hi:[1,0,1]
	v_pk_fma_f32 v[30:31], v[238:239], s[30:31], v[30:31] op_sel_hi:[1,0,1]
	v_readlane_b32 s16, v139, s72
	v_readlane_b32 s18, v139, s73
	v_readlane_b32 s20, v139, s74
	v_readlane_b32 s22, v139, s75
	v_readlane_b32 s24, v139, s76
	v_readlane_b32 s26, v139, s77
	v_readlane_b32 s28, v139, s78
	v_readlane_b32 s30, v139, s79
	v_readlane_b32 s48, v141, s72
	v_readlane_b32 s49, v141, s73
	v_readlane_b32 s50, v141, s74
	v_readlane_b32 s51, v141, s75
	v_readlane_b32 s52, v141, s76
	v_readlane_b32 s53, v141, s77
	v_readlane_b32 s54, v141, s78
	v_readlane_b32 s55, v141, s79
	s_add_u32 s32, s0, s48
	s_addc_u32 s33, s1, 0
	s_add_u32 s34, s0, s49
	s_addc_u32 s35, s1, 0
	s_add_u32 s36, s0, s50
	s_addc_u32 s37, s1, 0
	s_add_u32 s38, s0, s51
	s_addc_u32 s39, s1, 0
	s_add_u32 s40, s0, s52
	s_addc_u32 s41, s1, 0
	s_add_u32 s42, s0, s53
	s_addc_u32 s43, s1, 0
	s_add_u32 s44, s0, s54
	s_addc_u32 s45, s1, 0
	s_add_u32 s46, s0, s55
	s_addc_u32 s47, s1, 0
	global_load_dwordx4 v[192:195], v240, s[32:33]
	global_load_dwordx4 v[196:199], v240, s[34:35]
	global_load_dwordx4 v[200:203], v240, s[36:37]
	global_load_dwordx4 v[204:207], v240, s[38:39]
	global_load_dwordx4 v[208:211], v240, s[40:41]
	global_load_dwordx4 v[212:215], v240, s[42:43]
	global_load_dwordx4 v[216:219], v240, s[44:45]
	global_load_dwordx4 v[220:223], v240, s[46:47]
	s_waitcnt vmcnt(8)
	v_cvt_pk_f32_fp8_e32 v[224:225], v160
	v_cvt_pk_f32_fp8_sdwa v[226:227], v160 src0_sel:WORD_1
	v_cvt_pk_f32_fp8_e32 v[228:229], v161
	v_cvt_pk_f32_fp8_sdwa v[230:231], v161 src0_sel:WORD_1
	v_cvt_pk_f32_fp8_e32 v[232:233], v162
	v_cvt_pk_f32_fp8_sdwa v[234:235], v162 src0_sel:WORD_1
	v_cvt_pk_f32_fp8_e32 v[236:237], v163
	v_cvt_pk_f32_fp8_sdwa v[238:239], v163 src0_sel:WORD_1
	v_pk_fma_f32 v[32:33], v[224:225], s[16:17], v[32:33] op_sel_hi:[1,0,1]
	v_pk_fma_f32 v[34:35], v[226:227], s[16:17], v[34:35] op_sel_hi:[1,0,1]
	v_pk_fma_f32 v[36:37], v[228:229], s[16:17], v[36:37] op_sel_hi:[1,0,1]
	v_pk_fma_f32 v[38:39], v[230:231], s[16:17], v[38:39] op_sel_hi:[1,0,1]
	v_pk_fma_f32 v[40:41], v[232:233], s[16:17], v[40:41] op_sel_hi:[1,0,1]
	v_pk_fma_f32 v[42:43], v[234:235], s[16:17], v[42:43] op_sel_hi:[1,0,1]
	v_pk_fma_f32 v[44:45], v[236:237], s[16:17], v[44:45] op_sel_hi:[1,0,1]
	v_pk_fma_f32 v[46:47], v[238:239], s[16:17], v[46:47] op_sel_hi:[1,0,1]
	v_cvt_pk_f32_fp8_e32 v[224:225], v164
	v_cvt_pk_f32_fp8_sdwa v[226:227], v164 src0_sel:WORD_1
	v_cvt_pk_f32_fp8_e32 v[228:229], v165
	v_cvt_pk_f32_fp8_sdwa v[230:231], v165 src0_sel:WORD_1
	v_cvt_pk_f32_fp8_e32 v[232:233], v166
	v_cvt_pk_f32_fp8_sdwa v[234:235], v166 src0_sel:WORD_1
	v_cvt_pk_f32_fp8_e32 v[236:237], v167
	v_cvt_pk_f32_fp8_sdwa v[238:239], v167 src0_sel:WORD_1
	v_pk_fma_f32 v[32:33], v[224:225], s[18:19], v[32:33] op_sel_hi:[1,0,1]
	v_pk_fma_f32 v[34:35], v[226:227], s[18:19], v[34:35] op_sel_hi:[1,0,1]
	v_pk_fma_f32 v[36:37], v[228:229], s[18:19], v[36:37] op_sel_hi:[1,0,1]
	v_pk_fma_f32 v[38:39], v[230:231], s[18:19], v[38:39] op_sel_hi:[1,0,1]
	v_pk_fma_f32 v[40:41], v[232:233], s[18:19], v[40:41] op_sel_hi:[1,0,1]
	v_pk_fma_f32 v[42:43], v[234:235], s[18:19], v[42:43] op_sel_hi:[1,0,1]
	v_pk_fma_f32 v[44:45], v[236:237], s[18:19], v[44:45] op_sel_hi:[1,0,1]
	v_pk_fma_f32 v[46:47], v[238:239], s[18:19], v[46:47] op_sel_hi:[1,0,1]
	v_cvt_pk_f32_fp8_e32 v[224:225], v168
	v_cvt_pk_f32_fp8_sdwa v[226:227], v168 src0_sel:WORD_1
	v_cvt_pk_f32_fp8_e32 v[228:229], v169
	v_cvt_pk_f32_fp8_sdwa v[230:231], v169 src0_sel:WORD_1
	v_cvt_pk_f32_fp8_e32 v[232:233], v170
	v_cvt_pk_f32_fp8_sdwa v[234:235], v170 src0_sel:WORD_1
	v_cvt_pk_f32_fp8_e32 v[236:237], v171
	v_cvt_pk_f32_fp8_sdwa v[238:239], v171 src0_sel:WORD_1
	v_pk_fma_f32 v[32:33], v[224:225], s[20:21], v[32:33] op_sel_hi:[1,0,1]
	v_pk_fma_f32 v[34:35], v[226:227], s[20:21], v[34:35] op_sel_hi:[1,0,1]
	v_pk_fma_f32 v[36:37], v[228:229], s[20:21], v[36:37] op_sel_hi:[1,0,1]
	v_pk_fma_f32 v[38:39], v[230:231], s[20:21], v[38:39] op_sel_hi:[1,0,1]
	v_pk_fma_f32 v[40:41], v[232:233], s[20:21], v[40:41] op_sel_hi:[1,0,1]
	v_pk_fma_f32 v[42:43], v[234:235], s[20:21], v[42:43] op_sel_hi:[1,0,1]
	v_pk_fma_f32 v[44:45], v[236:237], s[20:21], v[44:45] op_sel_hi:[1,0,1]
	v_pk_fma_f32 v[46:47], v[238:239], s[20:21], v[46:47] op_sel_hi:[1,0,1]
	v_cvt_pk_f32_fp8_e32 v[224:225], v172
	v_cvt_pk_f32_fp8_sdwa v[226:227], v172 src0_sel:WORD_1
	v_cvt_pk_f32_fp8_e32 v[228:229], v173
	v_cvt_pk_f32_fp8_sdwa v[230:231], v173 src0_sel:WORD_1
	v_cvt_pk_f32_fp8_e32 v[232:233], v174
	v_cvt_pk_f32_fp8_sdwa v[234:235], v174 src0_sel:WORD_1
	v_cvt_pk_f32_fp8_e32 v[236:237], v175
	v_cvt_pk_f32_fp8_sdwa v[238:239], v175 src0_sel:WORD_1
	v_pk_fma_f32 v[32:33], v[224:225], s[22:23], v[32:33] op_sel_hi:[1,0,1]
	v_pk_fma_f32 v[34:35], v[226:227], s[22:23], v[34:35] op_sel_hi:[1,0,1]
	v_pk_fma_f32 v[36:37], v[228:229], s[22:23], v[36:37] op_sel_hi:[1,0,1]
	v_pk_fma_f32 v[38:39], v[230:231], s[22:23], v[38:39] op_sel_hi:[1,0,1]
	v_pk_fma_f32 v[40:41], v[232:233], s[22:23], v[40:41] op_sel_hi:[1,0,1]
	v_pk_fma_f32 v[42:43], v[234:235], s[22:23], v[42:43] op_sel_hi:[1,0,1]
	v_pk_fma_f32 v[44:45], v[236:237], s[22:23], v[44:45] op_sel_hi:[1,0,1]
	v_pk_fma_f32 v[46:47], v[238:239], s[22:23], v[46:47] op_sel_hi:[1,0,1]
	v_cvt_pk_f32_fp8_e32 v[224:225], v176
	v_cvt_pk_f32_fp8_sdwa v[226:227], v176 src0_sel:WORD_1
	v_cvt_pk_f32_fp8_e32 v[228:229], v177
	v_cvt_pk_f32_fp8_sdwa v[230:231], v177 src0_sel:WORD_1
	v_cvt_pk_f32_fp8_e32 v[232:233], v178
	v_cvt_pk_f32_fp8_sdwa v[234:235], v178 src0_sel:WORD_1
	v_cvt_pk_f32_fp8_e32 v[236:237], v179
	v_cvt_pk_f32_fp8_sdwa v[238:239], v179 src0_sel:WORD_1
	v_pk_fma_f32 v[32:33], v[224:225], s[24:25], v[32:33] op_sel_hi:[1,0,1]
	v_pk_fma_f32 v[34:35], v[226:227], s[24:25], v[34:35] op_sel_hi:[1,0,1]
	v_pk_fma_f32 v[36:37], v[228:229], s[24:25], v[36:37] op_sel_hi:[1,0,1]
	v_pk_fma_f32 v[38:39], v[230:231], s[24:25], v[38:39] op_sel_hi:[1,0,1]
	v_pk_fma_f32 v[40:41], v[232:233], s[24:25], v[40:41] op_sel_hi:[1,0,1]
	v_pk_fma_f32 v[42:43], v[234:235], s[24:25], v[42:43] op_sel_hi:[1,0,1]
	v_pk_fma_f32 v[44:45], v[236:237], s[24:25], v[44:45] op_sel_hi:[1,0,1]
	v_pk_fma_f32 v[46:47], v[238:239], s[24:25], v[46:47] op_sel_hi:[1,0,1]
	v_cvt_pk_f32_fp8_e32 v[224:225], v180
	v_cvt_pk_f32_fp8_sdwa v[226:227], v180 src0_sel:WORD_1
	v_cvt_pk_f32_fp8_e32 v[228:229], v181
	v_cvt_pk_f32_fp8_sdwa v[230:231], v181 src0_sel:WORD_1
	v_cvt_pk_f32_fp8_e32 v[232:233], v182
	v_cvt_pk_f32_fp8_sdwa v[234:235], v182 src0_sel:WORD_1
	v_cvt_pk_f32_fp8_e32 v[236:237], v183
	v_cvt_pk_f32_fp8_sdwa v[238:239], v183 src0_sel:WORD_1
	v_pk_fma_f32 v[32:33], v[224:225], s[26:27], v[32:33] op_sel_hi:[1,0,1]
	v_pk_fma_f32 v[34:35], v[226:227], s[26:27], v[34:35] op_sel_hi:[1,0,1]
	v_pk_fma_f32 v[36:37], v[228:229], s[26:27], v[36:37] op_sel_hi:[1,0,1]
	v_pk_fma_f32 v[38:39], v[230:231], s[26:27], v[38:39] op_sel_hi:[1,0,1]
	v_pk_fma_f32 v[40:41], v[232:233], s[26:27], v[40:41] op_sel_hi:[1,0,1]
	v_pk_fma_f32 v[42:43], v[234:235], s[26:27], v[42:43] op_sel_hi:[1,0,1]
	v_pk_fma_f32 v[44:45], v[236:237], s[26:27], v[44:45] op_sel_hi:[1,0,1]
	v_pk_fma_f32 v[46:47], v[238:239], s[26:27], v[46:47] op_sel_hi:[1,0,1]
	v_cvt_pk_f32_fp8_e32 v[224:225], v184
	v_cvt_pk_f32_fp8_sdwa v[226:227], v184 src0_sel:WORD_1
	v_cvt_pk_f32_fp8_e32 v[228:229], v185
	v_cvt_pk_f32_fp8_sdwa v[230:231], v185 src0_sel:WORD_1
	v_cvt_pk_f32_fp8_e32 v[232:233], v186
	v_cvt_pk_f32_fp8_sdwa v[234:235], v186 src0_sel:WORD_1
	v_cvt_pk_f32_fp8_e32 v[236:237], v187
	v_cvt_pk_f32_fp8_sdwa v[238:239], v187 src0_sel:WORD_1
	v_pk_fma_f32 v[32:33], v[224:225], s[28:29], v[32:33] op_sel_hi:[1,0,1]
	v_pk_fma_f32 v[34:35], v[226:227], s[28:29], v[34:35] op_sel_hi:[1,0,1]
	v_pk_fma_f32 v[36:37], v[228:229], s[28:29], v[36:37] op_sel_hi:[1,0,1]
	v_pk_fma_f32 v[38:39], v[230:231], s[28:29], v[38:39] op_sel_hi:[1,0,1]
	v_pk_fma_f32 v[40:41], v[232:233], s[28:29], v[40:41] op_sel_hi:[1,0,1]
	v_pk_fma_f32 v[42:43], v[234:235], s[28:29], v[42:43] op_sel_hi:[1,0,1]
	v_pk_fma_f32 v[44:45], v[236:237], s[28:29], v[44:45] op_sel_hi:[1,0,1]
	v_pk_fma_f32 v[46:47], v[238:239], s[28:29], v[46:47] op_sel_hi:[1,0,1]
	v_cvt_pk_f32_fp8_e32 v[224:225], v188
	v_cvt_pk_f32_fp8_sdwa v[226:227], v188 src0_sel:WORD_1
	v_cvt_pk_f32_fp8_e32 v[228:229], v189
	v_cvt_pk_f32_fp8_sdwa v[230:231], v189 src0_sel:WORD_1
	v_cvt_pk_f32_fp8_e32 v[232:233], v190
	v_cvt_pk_f32_fp8_sdwa v[234:235], v190 src0_sel:WORD_1
	v_cvt_pk_f32_fp8_e32 v[236:237], v191
	v_cvt_pk_f32_fp8_sdwa v[238:239], v191 src0_sel:WORD_1
	v_pk_fma_f32 v[32:33], v[224:225], s[30:31], v[32:33] op_sel_hi:[1,0,1]
	v_pk_fma_f32 v[34:35], v[226:227], s[30:31], v[34:35] op_sel_hi:[1,0,1]
	v_pk_fma_f32 v[36:37], v[228:229], s[30:31], v[36:37] op_sel_hi:[1,0,1]
	v_pk_fma_f32 v[38:39], v[230:231], s[30:31], v[38:39] op_sel_hi:[1,0,1]
	v_pk_fma_f32 v[40:41], v[232:233], s[30:31], v[40:41] op_sel_hi:[1,0,1]
	v_pk_fma_f32 v[42:43], v[234:235], s[30:31], v[42:43] op_sel_hi:[1,0,1]
	v_pk_fma_f32 v[44:45], v[236:237], s[30:31], v[44:45] op_sel_hi:[1,0,1]
	v_pk_fma_f32 v[46:47], v[238:239], s[30:31], v[46:47] op_sel_hi:[1,0,1]
	v_readlane_b32 s16, v143, s72
	v_readlane_b32 s18, v143, s73
	v_readlane_b32 s20, v143, s74
	v_readlane_b32 s22, v143, s75
	v_readlane_b32 s24, v143, s76
	v_readlane_b32 s26, v143, s77
	v_readlane_b32 s28, v143, s78
	v_readlane_b32 s30, v143, s79
; DI void peer_item_v(const Params& p, int item) {
;     ...
;     V_ISSUE(vqa, 0)
; #pragma unroll 1
;     for (int g = 0; g < 16; g += 2) {
;       V_ISSUE(vqb, g + 1)
;       V_CONSUME(vqa, g)
;       if (g + 2 < 16) V_ISSUE(vqa, g + 2)
;       V_CONSUME(vqb, g + 1)
;     }
	s_add_u32 s72, s72, 8
	s_add_u32 s73, s73, 8
	s_add_u32 s74, s74, 8
	s_add_u32 s75, s75, 8
	s_add_u32 s76, s76, 8
	s_add_u32 s77, s77, 8
	s_add_u32 s78, s78, 8
	s_add_u32 s79, s79, 8
	s_and_b32 s72, s72, 63
	s_and_b32 s73, s73, 63
	s_and_b32 s74, s74, 63
	s_and_b32 s75, s75, 63
	s_and_b32 s76, s76, 63
	s_and_b32 s77, s77, 63
	s_and_b32 s78, s78, 63
	s_and_b32 s79, s79, 63
	v_readlane_b32 s48, v128, s72
	v_readlane_b32 s49, v128, s73
	v_readlane_b32 s50, v128, s74
	v_readlane_b32 s51, v128, s75
	v_readlane_b32 s52, v128, s76
	v_readlane_b32 s53, v128, s77
	v_readlane_b32 s54, v128, s78
	v_readlane_b32 s55, v128, s79
	s_add_u32 s32, s0, s48
	s_addc_u32 s33, s1, 0
	s_add_u32 s34, s0, s49
	s_addc_u32 s35, s1, 0
	s_add_u32 s36, s0, s50
	s_addc_u32 s37, s1, 0
	s_add_u32 s38, s0, s51
	s_addc_u32 s39, s1, 0
	s_add_u32 s40, s0, s52
	s_addc_u32 s41, s1, 0
	s_add_u32 s42, s0, s53
	s_addc_u32 s43, s1, 0
	s_add_u32 s44, s0, s54
	s_addc_u32 s45, s1, 0
	s_add_u32 s46, s0, s55
	s_addc_u32 s47, s1, 0
	global_load_dwordx4 v[160:163], v240, s[32:33]
	global_load_dwordx4 v[164:167], v240, s[34:35]
	global_load_dwordx4 v[168:171], v240, s[36:37]
	global_load_dwordx4 v[172:175], v240, s[38:39]
	global_load_dwordx4 v[176:179], v240, s[40:41]
	global_load_dwordx4 v[180:183], v240, s[42:43]
	global_load_dwordx4 v[184:187], v240, s[44:45]
	global_load_dwordx4 v[188:191], v240, s[46:47]
	s_waitcnt vmcnt(8)
	v_cvt_pk_f32_fp8_e32 v[224:225], v192
	v_cvt_pk_f32_fp8_sdwa v[226:227], v192 src0_sel:WORD_1
	v_cvt_pk_f32_fp8_e32 v[228:229], v193
	v_cvt_pk_f32_fp8_sdwa v[230:231], v193 src0_sel:WORD_1
	v_cvt_pk_f32_fp8_e32 v[232:233], v194
	v_cvt_pk_f32_fp8_sdwa v[234:235], v194 src0_sel:WORD_1
	v_cvt_pk_f32_fp8_e32 v[236:237], v195
	v_cvt_pk_f32_fp8_sdwa v[238:239], v195 src0_sel:WORD_1
	v_pk_fma_f32 v[48:49], v[224:225], s[16:17], v[48:49] op_sel_hi:[1,0,1]
	v_pk_fma_f32 v[50:51], v[226:227], s[16:17], v[50:51] op_sel_hi:[1,0,1]
	v_pk_fma_f32 v[52:53], v[228:229], s[16:17], v[52:53] op_sel_hi:[1,0,1]
	v_pk_fma_f32 v[54:55], v[230:231], s[16:17], v[54:55] op_sel_hi:[1,0,1]
	v_pk_fma_f32 v[56:57], v[232:233], s[16:17], v[56:57] op_sel_hi:[1,0,1]
	v_pk_fma_f32 v[58:59], v[234:235], s[16:17], v[58:59] op_sel_hi:[1,0,1]
	v_pk_fma_f32 v[60:61], v[236:237], s[16:17], v[60:61] op_sel_hi:[1,0,1]
	v_pk_fma_f32 v[62:63], v[238:239], s[16:17], v[62:63] op_sel_hi:[1,0,1]
	v_cvt_pk_f32_fp8_e32 v[224:225], v196
	v_cvt_pk_f32_fp8_sdwa v[226:227], v196 src0_sel:WORD_1
	v_cvt_pk_f32_fp8_e32 v[228:229], v197
	v_cvt_pk_f32_fp8_sdwa v[230:231], v197 src0_sel:WORD_1
	v_cvt_pk_f32_fp8_e32 v[232:233], v198
	v_cvt_pk_f32_fp8_sdwa v[234:235], v198 src0_sel:WORD_1
	v_cvt_pk_f32_fp8_e32 v[236:237], v199
	v_cvt_pk_f32_fp8_sdwa v[238:239], v199 src0_sel:WORD_1
	v_pk_fma_f32 v[48:49], v[224:225], s[18:19], v[48:49] op_sel_hi:[1,0,1]
	v_pk_fma_f32 v[50:51], v[226:227], s[18:19], v[50:51] op_sel_hi:[1,0,1]
	v_pk_fma_f32 v[52:53], v[228:229], s[18:19], v[52:53] op_sel_hi:[1,0,1]
	v_pk_fma_f32 v[54:55], v[230:231], s[18:19], v[54:55] op_sel_hi:[1,0,1]
	v_pk_fma_f32 v[56:57], v[232:233], s[18:19], v[56:57] op_sel_hi:[1,0,1]
	v_pk_fma_f32 v[58:59], v[234:235], s[18:19], v[58:59] op_sel_hi:[1,0,1]
	v_pk_fma_f32 v[60:61], v[236:237], s[18:19], v[60:61] op_sel_hi:[1,0,1]
	v_pk_fma_f32 v[62:63], v[238:239], s[18:19], v[62:63] op_sel_hi:[1,0,1]
	v_cvt_pk_f32_fp8_e32 v[224:225], v200
	v_cvt_pk_f32_fp8_sdwa v[226:227], v200 src0_sel:WORD_1
	v_cvt_pk_f32_fp8_e32 v[228:229], v201
	v_cvt_pk_f32_fp8_sdwa v[230:231], v201 src0_sel:WORD_1
	v_cvt_pk_f32_fp8_e32 v[232:233], v202
	v_cvt_pk_f32_fp8_sdwa v[234:235], v202 src0_sel:WORD_1
	v_cvt_pk_f32_fp8_e32 v[236:237], v203
	v_cvt_pk_f32_fp8_sdwa v[238:239], v203 src0_sel:WORD_1
	v_pk_fma_f32 v[48:49], v[224:225], s[20:21], v[48:49] op_sel_hi:[1,0,1]
	v_pk_fma_f32 v[50:51], v[226:227], s[20:21], v[50:51] op_sel_hi:[1,0,1]
	v_pk_fma_f32 v[52:53], v[228:229], s[20:21], v[52:53] op_sel_hi:[1,0,1]
	v_pk_fma_f32 v[54:55], v[230:231], s[20:21], v[54:55] op_sel_hi:[1,0,1]
	v_pk_fma_f32 v[56:57], v[232:233], s[20:21], v[56:57] op_sel_hi:[1,0,1]
	v_pk_fma_f32 v[58:59], v[234:235], s[20:21], v[58:59] op_sel_hi:[1,0,1]
	v_pk_fma_f32 v[60:61], v[236:237], s[20:21], v[60:61] op_sel_hi:[1,0,1]
	v_pk_fma_f32 v[62:63], v[238:239], s[20:21], v[62:63] op_sel_hi:[1,0,1]
	v_cvt_pk_f32_fp8_e32 v[224:225], v204
	v_cvt_pk_f32_fp8_sdwa v[226:227], v204 src0_sel:WORD_1
	v_cvt_pk_f32_fp8_e32 v[228:229], v205
	v_cvt_pk_f32_fp8_sdwa v[230:231], v205 src0_sel:WORD_1
	v_cvt_pk_f32_fp8_e32 v[232:233], v206
	v_cvt_pk_f32_fp8_sdwa v[234:235], v206 src0_sel:WORD_1
	v_cvt_pk_f32_fp8_e32 v[236:237], v207
	v_cvt_pk_f32_fp8_sdwa v[238:239], v207 src0_sel:WORD_1
	v_pk_fma_f32 v[48:49], v[224:225], s[22:23], v[48:49] op_sel_hi:[1,0,1]
	v_pk_fma_f32 v[50:51], v[226:227], s[22:23], v[50:51] op_sel_hi:[1,0,1]
	v_pk_fma_f32 v[52:53], v[228:229], s[22:23], v[52:53] op_sel_hi:[1,0,1]
	v_pk_fma_f32 v[54:55], v[230:231], s[22:23], v[54:55] op_sel_hi:[1,0,1]
	v_pk_fma_f32 v[56:57], v[232:233], s[22:23], v[56:57] op_sel_hi:[1,0,1]
	v_pk_fma_f32 v[58:59], v[234:235], s[22:23], v[58:59] op_sel_hi:[1,0,1]
	v_pk_fma_f32 v[60:61], v[236:237], s[22:23], v[60:61] op_sel_hi:[1,0,1]
	v_pk_fma_f32 v[62:63], v[238:239], s[22:23], v[62:63] op_sel_hi:[1,0,1]
	v_cvt_pk_f32_fp8_e32 v[224:225], v208
	v_cvt_pk_f32_fp8_sdwa v[226:227], v208 src0_sel:WORD_1
	v_cvt_pk_f32_fp8_e32 v[228:229], v209
	v_cvt_pk_f32_fp8_sdwa v[230:231], v209 src0_sel:WORD_1
	v_cvt_pk_f32_fp8_e32 v[232:233], v210
	v_cvt_pk_f32_fp8_sdwa v[234:235], v210 src0_sel:WORD_1
	v_cvt_pk_f32_fp8_e32 v[236:237], v211
	v_cvt_pk_f32_fp8_sdwa v[238:239], v211 src0_sel:WORD_1
; DI void peer_item_v(const Params& p, int item) {
;     ...
;     float out[16];
; #pragma unroll
;     for (int i = 0; i < 16; ++i) out[i] = 0.f;
;     u32x4 vqa[8], vqb[8];
;     ...
;     V_ISSUE(vqa, 0)
; #pragma unroll 1
;     for (int g = 0; g < 16; g += 2) {
;       V_ISSUE(vqb, g + 1)
;       V_CONSUME(vqa, g)
;       if (g + 2 < 16) V_ISSUE(vqa, g + 2)
;       V_CONSUME(vqb, g + 1)
;     }
;     ...
;     float* orow = p.out + tok * 1024 + lane * 4;
;     float4 y[4];
;     float ss = 0.f;
; #pragma unroll
;     for (int i = 0; i < 4; ++i) {
;       y[i] = *(const float4*)(orow + 256 * i);
;       y[i].x += out[4 * i]; y[i].y += out[4 * i + 1]; y[i].z += out[4 * i + 2]; y[i].w += out[4 * i + 3];
;       ss += y[i].x * y[i].x + y[i].y * y[i].y + y[i].z * y[i].z + y[i].w * y[i].w;
;     }
;     ss = wave_sum(ss);
;     ...
;       float4 g = *(const float4*)(p.g_final + 256 * i + lane * 4);
	v_pk_fma_f32 v[48:49], v[224:225], s[24:25], v[48:49] op_sel_hi:[1,0,1]
	v_pk_fma_f32 v[50:51], v[226:227], s[24:25], v[50:51] op_sel_hi:[1,0,1]
	v_pk_fma_f32 v[52:53], v[228:229], s[24:25], v[52:53] op_sel_hi:[1,0,1]
	v_pk_fma_f32 v[54:55], v[230:231], s[24:25], v[54:55] op_sel_hi:[1,0,1]
	v_pk_fma_f32 v[56:57], v[232:233], s[24:25], v[56:57] op_sel_hi:[1,0,1]
	v_pk_fma_f32 v[58:59], v[234:235], s[24:25], v[58:59] op_sel_hi:[1,0,1]
	v_pk_fma_f32 v[60:61], v[236:237], s[24:25], v[60:61] op_sel_hi:[1,0,1]
	v_pk_fma_f32 v[62:63], v[238:239], s[24:25], v[62:63] op_sel_hi:[1,0,1]
	v_cvt_pk_f32_fp8_e32 v[224:225], v212
	v_cvt_pk_f32_fp8_sdwa v[226:227], v212 src0_sel:WORD_1
	v_cvt_pk_f32_fp8_e32 v[228:229], v213
	v_cvt_pk_f32_fp8_sdwa v[230:231], v213 src0_sel:WORD_1
	v_cvt_pk_f32_fp8_e32 v[232:233], v214
	v_cvt_pk_f32_fp8_sdwa v[234:235], v214 src0_sel:WORD_1
	v_cvt_pk_f32_fp8_e32 v[236:237], v215
	v_cvt_pk_f32_fp8_sdwa v[238:239], v215 src0_sel:WORD_1
	v_pk_fma_f32 v[48:49], v[224:225], s[26:27], v[48:49] op_sel_hi:[1,0,1]
	v_pk_fma_f32 v[50:51], v[226:227], s[26:27], v[50:51] op_sel_hi:[1,0,1]
	v_pk_fma_f32 v[52:53], v[228:229], s[26:27], v[52:53] op_sel_hi:[1,0,1]
	v_pk_fma_f32 v[54:55], v[230:231], s[26:27], v[54:55] op_sel_hi:[1,0,1]
	v_pk_fma_f32 v[56:57], v[232:233], s[26:27], v[56:57] op_sel_hi:[1,0,1]
	v_pk_fma_f32 v[58:59], v[234:235], s[26:27], v[58:59] op_sel_hi:[1,0,1]
	v_pk_fma_f32 v[60:61], v[236:237], s[26:27], v[60:61] op_sel_hi:[1,0,1]
	v_pk_fma_f32 v[62:63], v[238:239], s[26:27], v[62:63] op_sel_hi:[1,0,1]
	v_cvt_pk_f32_fp8_e32 v[224:225], v216
	v_cvt_pk_f32_fp8_sdwa v[226:227], v216 src0_sel:WORD_1
	v_cvt_pk_f32_fp8_e32 v[228:229], v217
	v_cvt_pk_f32_fp8_sdwa v[230:231], v217 src0_sel:WORD_1
	v_cvt_pk_f32_fp8_e32 v[232:233], v218
	v_cvt_pk_f32_fp8_sdwa v[234:235], v218 src0_sel:WORD_1
	v_cvt_pk_f32_fp8_e32 v[236:237], v219
	v_cvt_pk_f32_fp8_sdwa v[238:239], v219 src0_sel:WORD_1
	v_pk_fma_f32 v[48:49], v[224:225], s[28:29], v[48:49] op_sel_hi:[1,0,1]
	v_pk_fma_f32 v[50:51], v[226:227], s[28:29], v[50:51] op_sel_hi:[1,0,1]
	v_pk_fma_f32 v[52:53], v[228:229], s[28:29], v[52:53] op_sel_hi:[1,0,1]
	v_pk_fma_f32 v[54:55], v[230:231], s[28:29], v[54:55] op_sel_hi:[1,0,1]
	v_pk_fma_f32 v[56:57], v[232:233], s[28:29], v[56:57] op_sel_hi:[1,0,1]
	v_pk_fma_f32 v[58:59], v[234:235], s[28:29], v[58:59] op_sel_hi:[1,0,1]
	v_pk_fma_f32 v[60:61], v[236:237], s[28:29], v[60:61] op_sel_hi:[1,0,1]
	v_pk_fma_f32 v[62:63], v[238:239], s[28:29], v[62:63] op_sel_hi:[1,0,1]
	v_cvt_pk_f32_fp8_e32 v[224:225], v220
	v_cvt_pk_f32_fp8_sdwa v[226:227], v220 src0_sel:WORD_1
	v_cvt_pk_f32_fp8_e32 v[228:229], v221
	v_cvt_pk_f32_fp8_sdwa v[230:231], v221 src0_sel:WORD_1
	v_cvt_pk_f32_fp8_e32 v[232:233], v222
	v_cvt_pk_f32_fp8_sdwa v[234:235], v222 src0_sel:WORD_1
	v_cvt_pk_f32_fp8_e32 v[236:237], v223
	v_cvt_pk_f32_fp8_sdwa v[238:239], v223 src0_sel:WORD_1
	v_pk_fma_f32 v[48:49], v[224:225], s[30:31], v[48:49] op_sel_hi:[1,0,1]
	v_pk_fma_f32 v[50:51], v[226:227], s[30:31], v[50:51] op_sel_hi:[1,0,1]
	v_pk_fma_f32 v[52:53], v[228:229], s[30:31], v[52:53] op_sel_hi:[1,0,1]
	v_pk_fma_f32 v[54:55], v[230:231], s[30:31], v[54:55] op_sel_hi:[1,0,1]
	v_pk_fma_f32 v[56:57], v[232:233], s[30:31], v[56:57] op_sel_hi:[1,0,1]
	v_pk_fma_f32 v[58:59], v[234:235], s[30:31], v[58:59] op_sel_hi:[1,0,1]
	v_pk_fma_f32 v[60:61], v[236:237], s[30:31], v[60:61] op_sel_hi:[1,0,1]
	v_pk_fma_f32 v[62:63], v[238:239], s[30:31], v[62:63] op_sel_hi:[1,0,1]
	s_add_u32 s12, s12, 1
	s_cmp_lt_u32 s12, 8
	s_cbranch_scc1 .Lvq_kA
	s_waitcnt vmcnt(0)
	global_load_dwordx4 v[128:131], v240, s[8:9]
	global_load_dwordx4 v[132:135], v240, s[8:9] offset:1024
	global_load_dwordx4 v[136:139], v240, s[8:9] offset:2048
	global_load_dwordx4 v[140:143], v240, s[8:9] offset:3072
	s_add_u32 s32, s62, 0
	s_addc_u32 s33, s63, 0
	s_add_u32 s34, s62, 4096
	s_addc_u32 s35, s63, 0
	s_add_u32 s36, s62, 8192
	s_addc_u32 s37, s63, 0
	s_add_u32 s38, s62, 12288
	s_addc_u32 s39, s63, 0
	s_waitcnt vmcnt(0)
	v_pk_add_f32 v[64:65], v[64:65], v[0:1]
	v_pk_add_f32 v[66:67], v[66:67], v[2:3]
	v_pk_add_f32 v[68:69], v[68:69], v[4:5]
	v_pk_add_f32 v[70:71], v[70:71], v[6:7]
	v_pk_add_f32 v[72:73], v[72:73], v[8:9]
	v_pk_add_f32 v[74:75], v[74:75], v[10:11]
	v_pk_add_f32 v[76:77], v[76:77], v[12:13]
	v_pk_add_f32 v[78:79], v[78:79], v[14:15]
	v_pk_mul_f32 v[224:225], v[64:65], v[64:65]
	v_pk_mul_f32 v[226:227], v[66:67], v[66:67]
	v_pk_fma_f32 v[224:225], v[68:69], v[68:69], v[224:225]
	v_pk_fma_f32 v[226:227], v[70:71], v[70:71], v[226:227]
	v_pk_fma_f32 v[224:225], v[72:73], v[72:73], v[224:225]
	v_pk_fma_f32 v[226:227], v[74:75], v[74:75], v[226:227]
	v_pk_fma_f32 v[224:225], v[76:77], v[76:77], v[224:225]
	v_pk_fma_f32 v[226:227], v[78:79], v[78:79], v[226:227]
	v_pk_add_f32 v[224:225], v[224:225], v[226:227]
	s_nop 0
	v_add_f32_e32 v224, v224, v225
	ds_bpermute_b32 v225, v242, v224
	s_waitcnt lgkmcnt(0)
	v_add_f32_e32 v224, v224, v225
	ds_bpermute_b32 v225, v243, v224
	s_waitcnt lgkmcnt(0)
	v_add_f32_e32 v224, v224, v225
	ds_bpermute_b32 v225, v244, v224
	s_waitcnt lgkmcnt(0)
	v_add_f32_e32 v224, v224, v225
	ds_bpermute_b32 v225, v245, v224
	s_waitcnt lgkmcnt(0)
	v_add_f32_e32 v224, v224, v225
	ds_bpermute_b32 v225, v246, v224
	s_waitcnt lgkmcnt(0)
	v_add_f32_e32 v224, v224, v225
	ds_bpermute_b32 v225, v247, v224
	s_waitcnt lgkmcnt(0)
; DI void peer_item_v(const Params& p, int item) {
;     ...
;     for (int i = 0; i < 4; ++i) {
;       y[i] = *(const float4*)(orow + 256 * i);
;       y[i].x += out[4 * i]; y[i].y += out[4 * i + 1]; y[i].z += out[4 * i + 2]; y[i].w += out[4 * i + 3];
;       ss += y[i].x * y[i].x + y[i].y * y[i].y + y[i].z * y[i].z + y[i].w * y[i].w;
;     }
;     ss = wave_sum(ss);
;     const float r = rsqrtf(ss * (1.f / 1024.f) + 1e-6f);
; #pragma unroll
;     for (int i = 0; i < 4; ++i) {
;       float4 g = *(const float4*)(p.g_final + 256 * i + lane * 4);
;       y[i].x *= r * g.x; y[i].y *= r * g.y; y[i].z *= r * g.z; y[i].w *= r * g.w;
;       *(float4*)(orow + 256 * i) = y[i];
	v_add_f32_e32 v224, v224, v225
	v_fmamk_f32 v224, v224, 0x3a800000, v248
	v_rsq_f32_e32 v224, v224
	s_nop 1
	v_pk_mul_f32 v[226:227], v[128:129], v[224:225] op_sel_hi:[1,0]
	v_pk_mul_f32 v[64:65], v[64:65], v[226:227]
	v_pk_mul_f32 v[228:229], v[130:131], v[224:225] op_sel_hi:[1,0]
	v_pk_mul_f32 v[66:67], v[66:67], v[228:229]
	v_pk_mul_f32 v[230:231], v[132:133], v[224:225] op_sel_hi:[1,0]
	v_pk_mul_f32 v[68:69], v[68:69], v[230:231]
	v_pk_mul_f32 v[232:233], v[134:135], v[224:225] op_sel_hi:[1,0]
	v_pk_mul_f32 v[70:71], v[70:71], v[232:233]
	v_pk_mul_f32 v[226:227], v[136:137], v[224:225] op_sel_hi:[1,0]
	v_pk_mul_f32 v[72:73], v[72:73], v[226:227]
	v_pk_mul_f32 v[228:229], v[138:139], v[224:225] op_sel_hi:[1,0]
	v_pk_mul_f32 v[74:75], v[74:75], v[228:229]
	v_pk_mul_f32 v[230:231], v[140:141], v[224:225] op_sel_hi:[1,0]
	v_pk_mul_f32 v[76:77], v[76:77], v[230:231]
	v_pk_mul_f32 v[232:233], v[142:143], v[224:225] op_sel_hi:[1,0]
	v_pk_mul_f32 v[78:79], v[78:79], v[232:233]
	v_pk_add_f32 v[80:81], v[80:81], v[16:17]
	v_pk_add_f32 v[82:83], v[82:83], v[18:19]
	v_pk_add_f32 v[84:85], v[84:85], v[20:21]
	v_pk_add_f32 v[86:87], v[86:87], v[22:23]
	v_pk_add_f32 v[88:89], v[88:89], v[24:25]
	v_pk_add_f32 v[90:91], v[90:91], v[26:27]
	v_pk_add_f32 v[92:93], v[92:93], v[28:29]
	v_pk_add_f32 v[94:95], v[94:95], v[30:31]
	v_pk_mul_f32 v[224:225], v[80:81], v[80:81]
	v_pk_mul_f32 v[226:227], v[82:83], v[82:83]
	v_pk_fma_f32 v[224:225], v[84:85], v[84:85], v[224:225]
	v_pk_fma_f32 v[226:227], v[86:87], v[86:87], v[226:227]
	v_pk_fma_f32 v[224:225], v[88:89], v[88:89], v[224:225]
	v_pk_fma_f32 v[226:227], v[90:91], v[90:91], v[226:227]
	v_pk_fma_f32 v[224:225], v[92:93], v[92:93], v[224:225]
	v_pk_fma_f32 v[226:227], v[94:95], v[94:95], v[226:227]
	v_pk_add_f32 v[224:225], v[224:225], v[226:227]
	s_nop 0
	v_add_f32_e32 v224, v224, v225
	ds_bpermute_b32 v225, v242, v224
	s_waitcnt lgkmcnt(0)
	v_add_f32_e32 v224, v224, v225
	ds_bpermute_b32 v225, v243, v224
	s_waitcnt lgkmcnt(0)
	v_add_f32_e32 v224, v224, v225
	ds_bpermute_b32 v225, v244, v224
	s_waitcnt lgkmcnt(0)
	v_add_f32_e32 v224, v224, v225
	ds_bpermute_b32 v225, v245, v224
	s_waitcnt lgkmcnt(0)
	v_add_f32_e32 v224, v224, v225
	ds_bpermute_b32 v225, v246, v224
	s_waitcnt lgkmcnt(0)
	v_add_f32_e32 v224, v224, v225
	ds_bpermute_b32 v225, v247, v224
	s_waitcnt lgkmcnt(0)
	v_add_f32_e32 v224, v224, v225
	v_fmamk_f32 v224, v224, 0x3a800000, v248
	v_rsq_f32_e32 v224, v224
	s_nop 1
	v_pk_mul_f32 v[226:227], v[128:129], v[224:225] op_sel_hi:[1,0]
	v_pk_mul_f32 v[80:81], v[80:81], v[226:227]
	v_pk_mul_f32 v[228:229], v[130:131], v[224:225] op_sel_hi:[1,0]
	v_pk_mul_f32 v[82:83], v[82:83], v[228:229]
	v_pk_mul_f32 v[230:231], v[132:133], v[224:225] op_sel_hi:[1,0]
	v_pk_mul_f32 v[84:85], v[84:85], v[230:231]
	v_pk_mul_f32 v[232:233], v[134:135], v[224:225] op_sel_hi:[1,0]
	v_pk_mul_f32 v[86:87], v[86:87], v[232:233]
	v_pk_mul_f32 v[226:227], v[136:137], v[224:225] op_sel_hi:[1,0]
	v_pk_mul_f32 v[88:89], v[88:89], v[226:227]
	v_pk_mul_f32 v[228:229], v[138:139], v[224:225] op_sel_hi:[1,0]
	v_pk_mul_f32 v[90:91], v[90:91], v[228:229]
	v_pk_mul_f32 v[230:231], v[140:141], v[224:225] op_sel_hi:[1,0]
	v_pk_mul_f32 v[92:93], v[92:93], v[230:231]
	v_pk_mul_f32 v[232:233], v[142:143], v[224:225] op_sel_hi:[1,0]
	v_pk_mul_f32 v[94:95], v[94:95], v[232:233]
	v_pk_add_f32 v[96:97], v[96:97], v[32:33]
	v_pk_add_f32 v[98:99], v[98:99], v[34:35]
	v_pk_add_f32 v[100:101], v[100:101], v[36:37]
	v_pk_add_f32 v[102:103], v[102:103], v[38:39]
	v_pk_add_f32 v[104:105], v[104:105], v[40:41]
	v_pk_add_f32 v[106:107], v[106:107], v[42:43]
	v_pk_add_f32 v[108:109], v[108:109], v[44:45]
	v_pk_add_f32 v[110:111], v[110:111], v[46:47]
	v_pk_mul_f32 v[224:225], v[96:97], v[96:97]
	v_pk_mul_f32 v[226:227], v[98:99], v[98:99]
	v_pk_fma_f32 v[224:225], v[100:101], v[100:101], v[224:225]
	v_pk_fma_f32 v[226:227], v[102:103], v[102:103], v[226:227]
	v_pk_fma_f32 v[224:225], v[104:105], v[104:105], v[224:225]
	v_pk_fma_f32 v[226:227], v[106:107], v[106:107], v[226:227]
	v_pk_fma_f32 v[224:225], v[108:109], v[108:109], v[224:225]
	v_pk_fma_f32 v[226:227], v[110:111], v[110:111], v[226:227]
	v_pk_add_f32 v[224:225], v[224:225], v[226:227]
	s_nop 0
	v_add_f32_e32 v224, v224, v225
	ds_bpermute_b32 v225, v242, v224
	s_waitcnt lgkmcnt(0)
	v_add_f32_e32 v224, v224, v225
	ds_bpermute_b32 v225, v243, v224
	s_waitcnt lgkmcnt(0)
	v_add_f32_e32 v224, v224, v225
	ds_bpermute_b32 v225, v244, v224
	s_waitcnt lgkmcnt(0)
	v_add_f32_e32 v224, v224, v225
	ds_bpermute_b32 v225, v245, v224
	s_waitcnt lgkmcnt(0)
	v_add_f32_e32 v224, v224, v225
	ds_bpermute_b32 v225, v246, v224
	s_waitcnt lgkmcnt(0)
	v_add_f32_e32 v224, v224, v225
	ds_bpermute_b32 v225, v247, v224
	s_waitcnt lgkmcnt(0)
; DI void peer_item_v(const Params& p, int item) {
;     ...
;     float out[16];
; #pragma unroll
;     for (int i = 0; i < 16; ++i) out[i] = 0.f;
;     ...
;     const float r = rsqrtf(ss * (1.f / 1024.f) + 1e-6f);
; #pragma unroll
;     for (int i = 0; i < 4; ++i) {
;       float4 g = *(const float4*)(p.g_final + 256 * i + lane * 4);
;       y[i].x *= r * g.x; y[i].y *= r * g.y; y[i].z *= r * g.z; y[i].w *= r * g.w;
;       *(float4*)(orow + 256 * i) = y[i];
	v_add_f32_e32 v224, v224, v225
	v_fmamk_f32 v224, v224, 0x3a800000, v248
	v_rsq_f32_e32 v224, v224
	s_nop 1
	v_pk_mul_f32 v[226:227], v[128:129], v[224:225] op_sel_hi:[1,0]
	v_pk_mul_f32 v[96:97], v[96:97], v[226:227]
	v_pk_mul_f32 v[228:229], v[130:131], v[224:225] op_sel_hi:[1,0]
	v_pk_mul_f32 v[98:99], v[98:99], v[228:229]
	v_pk_mul_f32 v[230:231], v[132:133], v[224:225] op_sel_hi:[1,0]
	v_pk_mul_f32 v[100:101], v[100:101], v[230:231]
	v_pk_mul_f32 v[232:233], v[134:135], v[224:225] op_sel_hi:[1,0]
	v_pk_mul_f32 v[102:103], v[102:103], v[232:233]
	v_pk_mul_f32 v[226:227], v[136:137], v[224:225] op_sel_hi:[1,0]
	v_pk_mul_f32 v[104:105], v[104:105], v[226:227]
	v_pk_mul_f32 v[228:229], v[138:139], v[224:225] op_sel_hi:[1,0]
	v_pk_mul_f32 v[106:107], v[106:107], v[228:229]
	v_pk_mul_f32 v[230:231], v[140:141], v[224:225] op_sel_hi:[1,0]
	v_pk_mul_f32 v[108:109], v[108:109], v[230:231]
	v_pk_mul_f32 v[232:233], v[142:143], v[224:225] op_sel_hi:[1,0]
	v_pk_mul_f32 v[110:111], v[110:111], v[232:233]
	v_pk_add_f32 v[112:113], v[112:113], v[48:49]
	v_pk_add_f32 v[114:115], v[114:115], v[50:51]
	v_pk_add_f32 v[116:117], v[116:117], v[52:53]
	v_pk_add_f32 v[118:119], v[118:119], v[54:55]
	v_pk_add_f32 v[120:121], v[120:121], v[56:57]
	v_pk_add_f32 v[122:123], v[122:123], v[58:59]
	v_pk_add_f32 v[124:125], v[124:125], v[60:61]
	v_pk_add_f32 v[126:127], v[126:127], v[62:63]
	v_pk_mul_f32 v[224:225], v[112:113], v[112:113]
	v_pk_mul_f32 v[226:227], v[114:115], v[114:115]
	v_pk_fma_f32 v[224:225], v[116:117], v[116:117], v[224:225]
	v_pk_fma_f32 v[226:227], v[118:119], v[118:119], v[226:227]
	v_pk_fma_f32 v[224:225], v[120:121], v[120:121], v[224:225]
	v_pk_fma_f32 v[226:227], v[122:123], v[122:123], v[226:227]
	v_pk_fma_f32 v[224:225], v[124:125], v[124:125], v[224:225]
	v_pk_fma_f32 v[226:227], v[126:127], v[126:127], v[226:227]
	v_pk_add_f32 v[224:225], v[224:225], v[226:227]
	s_nop 0
	v_add_f32_e32 v224, v224, v225
	ds_bpermute_b32 v225, v242, v224
	s_waitcnt lgkmcnt(0)
	v_add_f32_e32 v224, v224, v225
	ds_bpermute_b32 v225, v243, v224
	s_waitcnt lgkmcnt(0)
	v_add_f32_e32 v224, v224, v225
	ds_bpermute_b32 v225, v244, v224
	s_waitcnt lgkmcnt(0)
	v_add_f32_e32 v224, v224, v225
	ds_bpermute_b32 v225, v245, v224
	s_waitcnt lgkmcnt(0)
	v_add_f32_e32 v224, v224, v225
	ds_bpermute_b32 v225, v246, v224
	s_waitcnt lgkmcnt(0)
	v_add_f32_e32 v224, v224, v225
	ds_bpermute_b32 v225, v247, v224
	s_waitcnt lgkmcnt(0)
	v_add_f32_e32 v224, v224, v225
	v_fmamk_f32 v224, v224, 0x3a800000, v248
	v_rsq_f32_e32 v224, v224
	s_nop 1
	v_pk_mul_f32 v[226:227], v[128:129], v[224:225] op_sel_hi:[1,0]
	v_pk_mul_f32 v[112:113], v[112:113], v[226:227]
	v_pk_mul_f32 v[228:229], v[130:131], v[224:225] op_sel_hi:[1,0]
	v_pk_mul_f32 v[114:115], v[114:115], v[228:229]
	v_pk_mul_f32 v[230:231], v[132:133], v[224:225] op_sel_hi:[1,0]
	v_pk_mul_f32 v[116:117], v[116:117], v[230:231]
	v_pk_mul_f32 v[232:233], v[134:135], v[224:225] op_sel_hi:[1,0]
	v_pk_mul_f32 v[118:119], v[118:119], v[232:233]
	v_pk_mul_f32 v[226:227], v[136:137], v[224:225] op_sel_hi:[1,0]
	v_pk_mul_f32 v[120:121], v[120:121], v[226:227]
	v_pk_mul_f32 v[228:229], v[138:139], v[224:225] op_sel_hi:[1,0]
	v_pk_mul_f32 v[122:123], v[122:123], v[228:229]
	v_pk_mul_f32 v[230:231], v[140:141], v[224:225] op_sel_hi:[1,0]
	v_pk_mul_f32 v[124:125], v[124:125], v[230:231]
	v_pk_mul_f32 v[232:233], v[142:143], v[224:225] op_sel_hi:[1,0]
	v_pk_mul_f32 v[126:127], v[126:127], v[232:233]
	global_store_dwordx4 v240, v[64:67], s[32:33]
	global_store_dwordx4 v240, v[68:71], s[32:33] offset:1024
	global_store_dwordx4 v240, v[72:75], s[32:33] offset:2048
	global_store_dwordx4 v240, v[76:79], s[32:33] offset:3072
	global_store_dwordx4 v240, v[80:83], s[34:35]
	global_store_dwordx4 v240, v[84:87], s[34:35] offset:1024
	global_store_dwordx4 v240, v[88:91], s[34:35] offset:2048
	global_store_dwordx4 v240, v[92:95], s[34:35] offset:3072
	global_store_dwordx4 v240, v[96:99], s[36:37]
	global_store_dwordx4 v240, v[100:103], s[36:37] offset:1024
	global_store_dwordx4 v240, v[104:107], s[36:37] offset:2048
	global_store_dwordx4 v240, v[108:111], s[36:37] offset:3072
	global_store_dwordx4 v240, v[112:115], s[38:39]
	global_store_dwordx4 v240, v[116:119], s[38:39] offset:1024
	global_store_dwordx4 v240, v[120:123], s[38:39] offset:2048
	global_store_dwordx4 v240, v[124:127], s[38:39] offset:3072
	s_nop 1
	v_mov_b32_e32 v64, 0
	v_mov_b32_e32 v65, 0
	v_mov_b32_e32 v66, 0
	v_mov_b32_e32 v67, 0
	v_mov_b32_e32 v68, 0
	v_mov_b32_e32 v69, 0
	v_mov_b32_e32 v70, 0
	v_mov_b32_e32 v71, 0
	v_mov_b32_e32 v72, 0
	v_mov_b32_e32 v73, 0
	v_mov_b32_e32 v74, 0
	v_mov_b32_e32 v75, 0
	v_mov_b32_e32 v76, 0
	v_mov_b32_e32 v77, 0
	v_mov_b32_e32 v78, 0
	v_mov_b32_e32 v79, 0
	v_mov_b32_e32 v80, 0
	v_mov_b32_e32 v81, 0
	v_mov_b32_e32 v82, 0
	v_mov_b32_e32 v83, 0
	v_mov_b32_e32 v84, 0
	v_mov_b32_e32 v85, 0
	v_mov_b32_e32 v86, 0
	v_mov_b32_e32 v87, 0
	v_mov_b32_e32 v88, 0
	v_mov_b32_e32 v89, 0
	v_mov_b32_e32 v90, 0
	v_mov_b32_e32 v91, 0
	v_mov_b32_e32 v92, 0
	v_mov_b32_e32 v93, 0
	v_mov_b32_e32 v94, 0
	v_mov_b32_e32 v95, 0
	v_mov_b32_e32 v96, 0
	v_mov_b32_e32 v97, 0
	v_mov_b32_e32 v98, 0
	v_mov_b32_e32 v99, 0
	v_mov_b32_e32 v100, 0
	v_mov_b32_e32 v101, 0
	v_mov_b32_e32 v102, 0
	v_mov_b32_e32 v103, 0
	v_mov_b32_e32 v104, 0
	v_mov_b32_e32 v105, 0
	v_mov_b32_e32 v106, 0
	v_mov_b32_e32 v107, 0
	v_mov_b32_e32 v108, 0
	v_mov_b32_e32 v109, 0
	v_mov_b32_e32 v110, 0
	v_mov_b32_e32 v111, 0
	v_mov_b32_e32 v112, 0
	v_mov_b32_e32 v113, 0
	v_mov_b32_e32 v114, 0
	v_mov_b32_e32 v115, 0
	v_mov_b32_e32 v116, 0
	v_mov_b32_e32 v117, 0
	v_mov_b32_e32 v118, 0
	v_mov_b32_e32 v119, 0
; DI void peer_item_v(const Params& p, int item) {
;     ...
;     float out[16];
; #pragma unroll
;     for (int i = 0; i < 16; ++i) out[i] = 0.f;
;     u32x4 vqa[8], vqb[8];
;     ...
;     V_ISSUE(vqa, 0)
; #pragma unroll 1
;     for (int g = 0; g < 16; g += 2) {
;       V_ISSUE(vqb, g + 1)
;       V_CONSUME(vqa, g)
;       if (g + 2 < 16) V_ISSUE(vqa, g + 2)
;       V_CONSUME(vqb, g + 1)
;     }
	v_mov_b32_e32 v120, 0
	v_mov_b32_e32 v121, 0
	v_mov_b32_e32 v122, 0
	v_mov_b32_e32 v123, 0
	v_mov_b32_e32 v124, 0
	v_mov_b32_e32 v125, 0
	v_mov_b32_e32 v126, 0
	v_mov_b32_e32 v127, 0
	s_add_u32 s32, s62, 16384
	s_addc_u32 s33, s63, 0
	s_add_u32 s34, s62, 20480
	s_addc_u32 s35, s63, 0
	s_add_u32 s36, s62, 24576
	s_addc_u32 s37, s63, 0
	s_add_u32 s38, s62, 28672
	s_addc_u32 s39, s63, 0
	global_load_dwordx4 v[0:3], v240, s[32:33]
	global_load_dwordx4 v[4:7], v240, s[32:33] offset:1024
	global_load_dwordx4 v[8:11], v240, s[32:33] offset:2048
	global_load_dwordx4 v[12:15], v240, s[32:33] offset:3072
	global_load_dwordx4 v[16:19], v240, s[34:35]
	global_load_dwordx4 v[20:23], v240, s[34:35] offset:1024
	global_load_dwordx4 v[24:27], v240, s[34:35] offset:2048
	global_load_dwordx4 v[28:31], v240, s[34:35] offset:3072
	global_load_dwordx4 v[32:35], v240, s[36:37]
	global_load_dwordx4 v[36:39], v240, s[36:37] offset:1024
	global_load_dwordx4 v[40:43], v240, s[36:37] offset:2048
	global_load_dwordx4 v[44:47], v240, s[36:37] offset:3072
	global_load_dwordx4 v[48:51], v240, s[38:39]
	global_load_dwordx4 v[52:55], v240, s[38:39] offset:1024
	global_load_dwordx4 v[56:59], v240, s[38:39] offset:2048
	global_load_dwordx4 v[60:63], v240, s[38:39] offset:3072
	s_mov_b32 s72, 0
	s_mov_b32 s73, 1
	s_mov_b32 s74, 2
	s_mov_b32 s75, 3
	s_mov_b32 s76, 4
	s_mov_b32 s77, 5
	s_mov_b32 s78, 6
	s_mov_b32 s79, 7
	s_nop 0
	v_readlane_b32 s48, v144, s72
	v_readlane_b32 s49, v144, s73
	v_readlane_b32 s50, v144, s74
	v_readlane_b32 s51, v144, s75
	v_readlane_b32 s52, v144, s76
	v_readlane_b32 s53, v144, s77
	v_readlane_b32 s54, v144, s78
	v_readlane_b32 s55, v144, s79
	s_add_u32 s32, s0, s48
	s_addc_u32 s33, s1, 0
	s_add_u32 s34, s0, s49
	s_addc_u32 s35, s1, 0
	s_add_u32 s36, s0, s50
	s_addc_u32 s37, s1, 0
	s_add_u32 s38, s0, s51
	s_addc_u32 s39, s1, 0
	s_add_u32 s40, s0, s52
	s_addc_u32 s41, s1, 0
	s_add_u32 s42, s0, s53
	s_addc_u32 s43, s1, 0
	s_add_u32 s44, s0, s54
	s_addc_u32 s45, s1, 0
	s_add_u32 s46, s0, s55
	s_addc_u32 s47, s1, 0
	global_load_dwordx4 v[160:163], v240, s[32:33]
	global_load_dwordx4 v[164:167], v240, s[34:35]
	global_load_dwordx4 v[168:171], v240, s[36:37]
	global_load_dwordx4 v[172:175], v240, s[38:39]
	global_load_dwordx4 v[176:179], v240, s[40:41]
	global_load_dwordx4 v[180:183], v240, s[42:43]
	global_load_dwordx4 v[184:187], v240, s[44:45]
	global_load_dwordx4 v[188:191], v240, s[46:47]
	s_mov_b32 s12, 0
.Lvq_kB:
	v_readlane_b32 s16, v146, s72
	v_readlane_b32 s18, v146, s73
	v_readlane_b32 s20, v146, s74
	v_readlane_b32 s22, v146, s75
	v_readlane_b32 s24, v146, s76
	v_readlane_b32 s26, v146, s77
	v_readlane_b32 s28, v146, s78
	v_readlane_b32 s30, v146, s79
	v_readlane_b32 s48, v148, s72
	v_readlane_b32 s49, v148, s73
	v_readlane_b32 s50, v148, s74
	v_readlane_b32 s51, v148, s75
	v_readlane_b32 s52, v148, s76
	v_readlane_b32 s53, v148, s77
	v_readlane_b32 s54, v148, s78
	v_readlane_b32 s55, v148, s79
	s_add_u32 s32, s0, s48
	s_addc_u32 s33, s1, 0
	s_add_u32 s34, s0, s49
	s_addc_u32 s35, s1, 0
	s_add_u32 s36, s0, s50
	s_addc_u32 s37, s1, 0
	s_add_u32 s38, s0, s51
	s_addc_u32 s39, s1, 0
	s_add_u32 s40, s0, s52
	s_addc_u32 s41, s1, 0
	s_add_u32 s42, s0, s53
	s_addc_u32 s43, s1, 0
	s_add_u32 s44, s0, s54
	s_addc_u32 s45, s1, 0
	s_add_u32 s46, s0, s55
	s_addc_u32 s47, s1, 0
	global_load_dwordx4 v[192:195], v240, s[32:33]
	global_load_dwordx4 v[196:199], v240, s[34:35]
	global_load_dwordx4 v[200:203], v240, s[36:37]
	global_load_dwordx4 v[204:207], v240, s[38:39]
	global_load_dwordx4 v[208:211], v240, s[40:41]
	global_load_dwordx4 v[212:215], v240, s[42:43]
	global_load_dwordx4 v[216:219], v240, s[44:45]
	global_load_dwordx4 v[220:223], v240, s[46:47]
	s_waitcnt vmcnt(8)
	v_cvt_pk_f32_fp8_e32 v[224:225], v160
	v_cvt_pk_f32_fp8_sdwa v[226:227], v160 src0_sel:WORD_1
	v_cvt_pk_f32_fp8_e32 v[228:229], v161
	v_cvt_pk_f32_fp8_sdwa v[230:231], v161 src0_sel:WORD_1
	v_cvt_pk_f32_fp8_e32 v[232:233], v162
	v_cvt_pk_f32_fp8_sdwa v[234:235], v162 src0_sel:WORD_1
	v_cvt_pk_f32_fp8_e32 v[236:237], v163
	v_cvt_pk_f32_fp8_sdwa v[238:239], v163 src0_sel:WORD_1
	v_pk_fma_f32 v[64:65], v[224:225], s[16:17], v[64:65] op_sel_hi:[1,0,1]
	v_pk_fma_f32 v[66:67], v[226:227], s[16:17], v[66:67] op_sel_hi:[1,0,1]
	v_pk_fma_f32 v[68:69], v[228:229], s[16:17], v[68:69] op_sel_hi:[1,0,1]
	v_pk_fma_f32 v[70:71], v[230:231], s[16:17], v[70:71] op_sel_hi:[1,0,1]
	v_pk_fma_f32 v[72:73], v[232:233], s[16:17], v[72:73] op_sel_hi:[1,0,1]
	v_pk_fma_f32 v[74:75], v[234:235], s[16:17], v[74:75] op_sel_hi:[1,0,1]
	v_pk_fma_f32 v[76:77], v[236:237], s[16:17], v[76:77] op_sel_hi:[1,0,1]
	v_pk_fma_f32 v[78:79], v[238:239], s[16:17], v[78:79] op_sel_hi:[1,0,1]
	v_cvt_pk_f32_fp8_e32 v[224:225], v164
	v_cvt_pk_f32_fp8_sdwa v[226:227], v164 src0_sel:WORD_1
	v_cvt_pk_f32_fp8_e32 v[228:229], v165
	v_cvt_pk_f32_fp8_sdwa v[230:231], v165 src0_sel:WORD_1
	v_cvt_pk_f32_fp8_e32 v[232:233], v166
	v_cvt_pk_f32_fp8_sdwa v[234:235], v166 src0_sel:WORD_1
	v_cvt_pk_f32_fp8_e32 v[236:237], v167
	v_cvt_pk_f32_fp8_sdwa v[238:239], v167 src0_sel:WORD_1
	v_pk_fma_f32 v[64:65], v[224:225], s[18:19], v[64:65] op_sel_hi:[1,0,1]
	v_pk_fma_f32 v[66:67], v[226:227], s[18:19], v[66:67] op_sel_hi:[1,0,1]
	v_pk_fma_f32 v[68:69], v[228:229], s[18:19], v[68:69] op_sel_hi:[1,0,1]
	v_pk_fma_f32 v[70:71], v[230:231], s[18:19], v[70:71] op_sel_hi:[1,0,1]
	v_pk_fma_f32 v[72:73], v[232:233], s[18:19], v[72:73] op_sel_hi:[1,0,1]
	v_pk_fma_f32 v[74:75], v[234:235], s[18:19], v[74:75] op_sel_hi:[1,0,1]
	v_pk_fma_f32 v[76:77], v[236:237], s[18:19], v[76:77] op_sel_hi:[1,0,1]
	v_pk_fma_f32 v[78:79], v[238:239], s[18:19], v[78:79] op_sel_hi:[1,0,1]
	v_cvt_pk_f32_fp8_e32 v[224:225], v168
	v_cvt_pk_f32_fp8_sdwa v[226:227], v168 src0_sel:WORD_1
	v_cvt_pk_f32_fp8_e32 v[228:229], v169
	v_cvt_pk_f32_fp8_sdwa v[230:231], v169 src0_sel:WORD_1
	v_cvt_pk_f32_fp8_e32 v[232:233], v170
	v_cvt_pk_f32_fp8_sdwa v[234:235], v170 src0_sel:WORD_1
	v_cvt_pk_f32_fp8_e32 v[236:237], v171
	v_cvt_pk_f32_fp8_sdwa v[238:239], v171 src0_sel:WORD_1
	v_pk_fma_f32 v[64:65], v[224:225], s[20:21], v[64:65] op_sel_hi:[1,0,1]
	v_pk_fma_f32 v[66:67], v[226:227], s[20:21], v[66:67] op_sel_hi:[1,0,1]
	v_pk_fma_f32 v[68:69], v[228:229], s[20:21], v[68:69] op_sel_hi:[1,0,1]
	v_pk_fma_f32 v[70:71], v[230:231], s[20:21], v[70:71] op_sel_hi:[1,0,1]
	v_pk_fma_f32 v[72:73], v[232:233], s[20:21], v[72:73] op_sel_hi:[1,0,1]
	v_pk_fma_f32 v[74:75], v[234:235], s[20:21], v[74:75] op_sel_hi:[1,0,1]
	v_pk_fma_f32 v[76:77], v[236:237], s[20:21], v[76:77] op_sel_hi:[1,0,1]
	v_pk_fma_f32 v[78:79], v[238:239], s[20:21], v[78:79] op_sel_hi:[1,0,1]
	v_cvt_pk_f32_fp8_e32 v[224:225], v172
	v_cvt_pk_f32_fp8_sdwa v[226:227], v172 src0_sel:WORD_1
	v_cvt_pk_f32_fp8_e32 v[228:229], v173
	v_cvt_pk_f32_fp8_sdwa v[230:231], v173 src0_sel:WORD_1
	v_cvt_pk_f32_fp8_e32 v[232:233], v174
	v_cvt_pk_f32_fp8_sdwa v[234:235], v174 src0_sel:WORD_1
	v_cvt_pk_f32_fp8_e32 v[236:237], v175
	v_cvt_pk_f32_fp8_sdwa v[238:239], v175 src0_sel:WORD_1
	v_pk_fma_f32 v[64:65], v[224:225], s[22:23], v[64:65] op_sel_hi:[1,0,1]
	v_pk_fma_f32 v[66:67], v[226:227], s[22:23], v[66:67] op_sel_hi:[1,0,1]
	v_pk_fma_f32 v[68:69], v[228:229], s[22:23], v[68:69] op_sel_hi:[1,0,1]
	v_pk_fma_f32 v[70:71], v[230:231], s[22:23], v[70:71] op_sel_hi:[1,0,1]
	v_pk_fma_f32 v[72:73], v[232:233], s[22:23], v[72:73] op_sel_hi:[1,0,1]
	v_pk_fma_f32 v[74:75], v[234:235], s[22:23], v[74:75] op_sel_hi:[1,0,1]
	v_pk_fma_f32 v[76:77], v[236:237], s[22:23], v[76:77] op_sel_hi:[1,0,1]
	v_pk_fma_f32 v[78:79], v[238:239], s[22:23], v[78:79] op_sel_hi:[1,0,1]
	v_cvt_pk_f32_fp8_e32 v[224:225], v176
	v_cvt_pk_f32_fp8_sdwa v[226:227], v176 src0_sel:WORD_1
	v_cvt_pk_f32_fp8_e32 v[228:229], v177
	v_cvt_pk_f32_fp8_sdwa v[230:231], v177 src0_sel:WORD_1
	v_cvt_pk_f32_fp8_e32 v[232:233], v178
	v_cvt_pk_f32_fp8_sdwa v[234:235], v178 src0_sel:WORD_1
	v_cvt_pk_f32_fp8_e32 v[236:237], v179
	v_cvt_pk_f32_fp8_sdwa v[238:239], v179 src0_sel:WORD_1
	v_pk_fma_f32 v[64:65], v[224:225], s[24:25], v[64:65] op_sel_hi:[1,0,1]
	v_pk_fma_f32 v[66:67], v[226:227], s[24:25], v[66:67] op_sel_hi:[1,0,1]
	v_pk_fma_f32 v[68:69], v[228:229], s[24:25], v[68:69] op_sel_hi:[1,0,1]
	v_pk_fma_f32 v[70:71], v[230:231], s[24:25], v[70:71] op_sel_hi:[1,0,1]
	v_pk_fma_f32 v[72:73], v[232:233], s[24:25], v[72:73] op_sel_hi:[1,0,1]
	v_pk_fma_f32 v[74:75], v[234:235], s[24:25], v[74:75] op_sel_hi:[1,0,1]
	v_pk_fma_f32 v[76:77], v[236:237], s[24:25], v[76:77] op_sel_hi:[1,0,1]
	v_pk_fma_f32 v[78:79], v[238:239], s[24:25], v[78:79] op_sel_hi:[1,0,1]
	v_cvt_pk_f32_fp8_e32 v[224:225], v180
	v_cvt_pk_f32_fp8_sdwa v[226:227], v180 src0_sel:WORD_1
	v_cvt_pk_f32_fp8_e32 v[228:229], v181
	v_cvt_pk_f32_fp8_sdwa v[230:231], v181 src0_sel:WORD_1
	v_cvt_pk_f32_fp8_e32 v[232:233], v182
	v_cvt_pk_f32_fp8_sdwa v[234:235], v182 src0_sel:WORD_1
	v_cvt_pk_f32_fp8_e32 v[236:237], v183
	v_cvt_pk_f32_fp8_sdwa v[238:239], v183 src0_sel:WORD_1
	v_pk_fma_f32 v[64:65], v[224:225], s[26:27], v[64:65] op_sel_hi:[1,0,1]
	v_pk_fma_f32 v[66:67], v[226:227], s[26:27], v[66:67] op_sel_hi:[1,0,1]
	v_pk_fma_f32 v[68:69], v[228:229], s[26:27], v[68:69] op_sel_hi:[1,0,1]
	v_pk_fma_f32 v[70:71], v[230:231], s[26:27], v[70:71] op_sel_hi:[1,0,1]
	v_pk_fma_f32 v[72:73], v[232:233], s[26:27], v[72:73] op_sel_hi:[1,0,1]
	v_pk_fma_f32 v[74:75], v[234:235], s[26:27], v[74:75] op_sel_hi:[1,0,1]
	v_pk_fma_f32 v[76:77], v[236:237], s[26:27], v[76:77] op_sel_hi:[1,0,1]
	v_pk_fma_f32 v[78:79], v[238:239], s[26:27], v[78:79] op_sel_hi:[1,0,1]
	v_cvt_pk_f32_fp8_e32 v[224:225], v184
	v_cvt_pk_f32_fp8_sdwa v[226:227], v184 src0_sel:WORD_1
	v_cvt_pk_f32_fp8_e32 v[228:229], v185
	v_cvt_pk_f32_fp8_sdwa v[230:231], v185 src0_sel:WORD_1
	v_cvt_pk_f32_fp8_e32 v[232:233], v186
	v_cvt_pk_f32_fp8_sdwa v[234:235], v186 src0_sel:WORD_1
	v_cvt_pk_f32_fp8_e32 v[236:237], v187
	v_cvt_pk_f32_fp8_sdwa v[238:239], v187 src0_sel:WORD_1
	v_pk_fma_f32 v[64:65], v[224:225], s[28:29], v[64:65] op_sel_hi:[1,0,1]
	v_pk_fma_f32 v[66:67], v[226:227], s[28:29], v[66:67] op_sel_hi:[1,0,1]
	v_pk_fma_f32 v[68:69], v[228:229], s[28:29], v[68:69] op_sel_hi:[1,0,1]
	v_pk_fma_f32 v[70:71], v[230:231], s[28:29], v[70:71] op_sel_hi:[1,0,1]
	v_pk_fma_f32 v[72:73], v[232:233], s[28:29], v[72:73] op_sel_hi:[1,0,1]
	v_pk_fma_f32 v[74:75], v[234:235], s[28:29], v[74:75] op_sel_hi:[1,0,1]
	v_pk_fma_f32 v[76:77], v[236:237], s[28:29], v[76:77] op_sel_hi:[1,0,1]
	v_pk_fma_f32 v[78:79], v[238:239], s[28:29], v[78:79] op_sel_hi:[1,0,1]
	v_cvt_pk_f32_fp8_e32 v[224:225], v188
	v_cvt_pk_f32_fp8_sdwa v[226:227], v188 src0_sel:WORD_1
	v_cvt_pk_f32_fp8_e32 v[228:229], v189
	v_cvt_pk_f32_fp8_sdwa v[230:231], v189 src0_sel:WORD_1
	v_cvt_pk_f32_fp8_e32 v[232:233], v190
	v_cvt_pk_f32_fp8_sdwa v[234:235], v190 src0_sel:WORD_1
	v_cvt_pk_f32_fp8_e32 v[236:237], v191
	v_cvt_pk_f32_fp8_sdwa v[238:239], v191 src0_sel:WORD_1
	v_pk_fma_f32 v[64:65], v[224:225], s[30:31], v[64:65] op_sel_hi:[1,0,1]
	v_pk_fma_f32 v[66:67], v[226:227], s[30:31], v[66:67] op_sel_hi:[1,0,1]
	v_pk_fma_f32 v[68:69], v[228:229], s[30:31], v[68:69] op_sel_hi:[1,0,1]
	v_pk_fma_f32 v[70:71], v[230:231], s[30:31], v[70:71] op_sel_hi:[1,0,1]
	v_pk_fma_f32 v[72:73], v[232:233], s[30:31], v[72:73] op_sel_hi:[1,0,1]
	v_pk_fma_f32 v[74:75], v[234:235], s[30:31], v[74:75] op_sel_hi:[1,0,1]
; DI void peer_item_v(const Params& p, int item) {
;     ...
;     V_ISSUE(vqa, 0)
; #pragma unroll 1
;     for (int g = 0; g < 16; g += 2) {
;       V_ISSUE(vqb, g + 1)
;       V_CONSUME(vqa, g)
;       if (g + 2 < 16) V_ISSUE(vqa, g + 2)
;       V_CONSUME(vqb, g + 1)
;     }
	v_pk_fma_f32 v[76:77], v[236:237], s[30:31], v[76:77] op_sel_hi:[1,0,1]
	v_pk_fma_f32 v[78:79], v[238:239], s[30:31], v[78:79] op_sel_hi:[1,0,1]
	v_readlane_b32 s16, v150, s72
	v_readlane_b32 s18, v150, s73
	v_readlane_b32 s20, v150, s74
	v_readlane_b32 s22, v150, s75
	v_readlane_b32 s24, v150, s76
	v_readlane_b32 s26, v150, s77
	v_readlane_b32 s28, v150, s78
	v_readlane_b32 s30, v150, s79
	v_readlane_b32 s48, v152, s72
	v_readlane_b32 s49, v152, s73
	v_readlane_b32 s50, v152, s74
	v_readlane_b32 s51, v152, s75
	v_readlane_b32 s52, v152, s76
	v_readlane_b32 s53, v152, s77
	v_readlane_b32 s54, v152, s78
	v_readlane_b32 s55, v152, s79
	s_add_u32 s32, s0, s48
	s_addc_u32 s33, s1, 0
	s_add_u32 s34, s0, s49
	s_addc_u32 s35, s1, 0
	s_add_u32 s36, s0, s50
	s_addc_u32 s37, s1, 0
	s_add_u32 s38, s0, s51
	s_addc_u32 s39, s1, 0
	s_add_u32 s40, s0, s52
	s_addc_u32 s41, s1, 0
	s_add_u32 s42, s0, s53
	s_addc_u32 s43, s1, 0
	s_add_u32 s44, s0, s54
	s_addc_u32 s45, s1, 0
	s_add_u32 s46, s0, s55
	s_addc_u32 s47, s1, 0
	global_load_dwordx4 v[160:163], v240, s[32:33]
	global_load_dwordx4 v[164:167], v240, s[34:35]
	global_load_dwordx4 v[168:171], v240, s[36:37]
	global_load_dwordx4 v[172:175], v240, s[38:39]
	global_load_dwordx4 v[176:179], v240, s[40:41]
	global_load_dwordx4 v[180:183], v240, s[42:43]
	global_load_dwordx4 v[184:187], v240, s[44:45]
	global_load_dwordx4 v[188:191], v240, s[46:47]
	s_waitcnt vmcnt(8)
	v_cvt_pk_f32_fp8_e32 v[224:225], v192
	v_cvt_pk_f32_fp8_sdwa v[226:227], v192 src0_sel:WORD_1
	v_cvt_pk_f32_fp8_e32 v[228:229], v193
	v_cvt_pk_f32_fp8_sdwa v[230:231], v193 src0_sel:WORD_1
	v_cvt_pk_f32_fp8_e32 v[232:233], v194
	v_cvt_pk_f32_fp8_sdwa v[234:235], v194 src0_sel:WORD_1
	v_cvt_pk_f32_fp8_e32 v[236:237], v195
	v_cvt_pk_f32_fp8_sdwa v[238:239], v195 src0_sel:WORD_1
	v_pk_fma_f32 v[80:81], v[224:225], s[16:17], v[80:81] op_sel_hi:[1,0,1]
	v_pk_fma_f32 v[82:83], v[226:227], s[16:17], v[82:83] op_sel_hi:[1,0,1]
	v_pk_fma_f32 v[84:85], v[228:229], s[16:17], v[84:85] op_sel_hi:[1,0,1]
	v_pk_fma_f32 v[86:87], v[230:231], s[16:17], v[86:87] op_sel_hi:[1,0,1]
	v_pk_fma_f32 v[88:89], v[232:233], s[16:17], v[88:89] op_sel_hi:[1,0,1]
	v_pk_fma_f32 v[90:91], v[234:235], s[16:17], v[90:91] op_sel_hi:[1,0,1]
	v_pk_fma_f32 v[92:93], v[236:237], s[16:17], v[92:93] op_sel_hi:[1,0,1]
	v_pk_fma_f32 v[94:95], v[238:239], s[16:17], v[94:95] op_sel_hi:[1,0,1]
	v_cvt_pk_f32_fp8_e32 v[224:225], v196
	v_cvt_pk_f32_fp8_sdwa v[226:227], v196 src0_sel:WORD_1
	v_cvt_pk_f32_fp8_e32 v[228:229], v197
	v_cvt_pk_f32_fp8_sdwa v[230:231], v197 src0_sel:WORD_1
	v_cvt_pk_f32_fp8_e32 v[232:233], v198
	v_cvt_pk_f32_fp8_sdwa v[234:235], v198 src0_sel:WORD_1
	v_cvt_pk_f32_fp8_e32 v[236:237], v199
	v_cvt_pk_f32_fp8_sdwa v[238:239], v199 src0_sel:WORD_1
	v_pk_fma_f32 v[80:81], v[224:225], s[18:19], v[80:81] op_sel_hi:[1,0,1]
	v_pk_fma_f32 v[82:83], v[226:227], s[18:19], v[82:83] op_sel_hi:[1,0,1]
	v_pk_fma_f32 v[84:85], v[228:229], s[18:19], v[84:85] op_sel_hi:[1,0,1]
	v_pk_fma_f32 v[86:87], v[230:231], s[18:19], v[86:87] op_sel_hi:[1,0,1]
	v_pk_fma_f32 v[88:89], v[232:233], s[18:19], v[88:89] op_sel_hi:[1,0,1]
	v_pk_fma_f32 v[90:91], v[234:235], s[18:19], v[90:91] op_sel_hi:[1,0,1]
	v_pk_fma_f32 v[92:93], v[236:237], s[18:19], v[92:93] op_sel_hi:[1,0,1]
	v_pk_fma_f32 v[94:95], v[238:239], s[18:19], v[94:95] op_sel_hi:[1,0,1]
	v_cvt_pk_f32_fp8_e32 v[224:225], v200
	v_cvt_pk_f32_fp8_sdwa v[226:227], v200 src0_sel:WORD_1
	v_cvt_pk_f32_fp8_e32 v[228:229], v201
	v_cvt_pk_f32_fp8_sdwa v[230:231], v201 src0_sel:WORD_1
	v_cvt_pk_f32_fp8_e32 v[232:233], v202
	v_cvt_pk_f32_fp8_sdwa v[234:235], v202 src0_sel:WORD_1
	v_cvt_pk_f32_fp8_e32 v[236:237], v203
	v_cvt_pk_f32_fp8_sdwa v[238:239], v203 src0_sel:WORD_1
	v_pk_fma_f32 v[80:81], v[224:225], s[20:21], v[80:81] op_sel_hi:[1,0,1]
	v_pk_fma_f32 v[82:83], v[226:227], s[20:21], v[82:83] op_sel_hi:[1,0,1]
	v_pk_fma_f32 v[84:85], v[228:229], s[20:21], v[84:85] op_sel_hi:[1,0,1]
	v_pk_fma_f32 v[86:87], v[230:231], s[20:21], v[86:87] op_sel_hi:[1,0,1]
	v_pk_fma_f32 v[88:89], v[232:233], s[20:21], v[88:89] op_sel_hi:[1,0,1]
	v_pk_fma_f32 v[90:91], v[234:235], s[20:21], v[90:91] op_sel_hi:[1,0,1]
	v_pk_fma_f32 v[92:93], v[236:237], s[20:21], v[92:93] op_sel_hi:[1,0,1]
	v_pk_fma_f32 v[94:95], v[238:239], s[20:21], v[94:95] op_sel_hi:[1,0,1]
	v_cvt_pk_f32_fp8_e32 v[224:225], v204
	v_cvt_pk_f32_fp8_sdwa v[226:227], v204 src0_sel:WORD_1
	v_cvt_pk_f32_fp8_e32 v[228:229], v205
	v_cvt_pk_f32_fp8_sdwa v[230:231], v205 src0_sel:WORD_1
	v_cvt_pk_f32_fp8_e32 v[232:233], v206
	v_cvt_pk_f32_fp8_sdwa v[234:235], v206 src0_sel:WORD_1
	v_cvt_pk_f32_fp8_e32 v[236:237], v207
	v_cvt_pk_f32_fp8_sdwa v[238:239], v207 src0_sel:WORD_1
	v_pk_fma_f32 v[80:81], v[224:225], s[22:23], v[80:81] op_sel_hi:[1,0,1]
	v_pk_fma_f32 v[82:83], v[226:227], s[22:23], v[82:83] op_sel_hi:[1,0,1]
	v_pk_fma_f32 v[84:85], v[228:229], s[22:23], v[84:85] op_sel_hi:[1,0,1]
	v_pk_fma_f32 v[86:87], v[230:231], s[22:23], v[86:87] op_sel_hi:[1,0,1]
	v_pk_fma_f32 v[88:89], v[232:233], s[22:23], v[88:89] op_sel_hi:[1,0,1]
	v_pk_fma_f32 v[90:91], v[234:235], s[22:23], v[90:91] op_sel_hi:[1,0,1]
	v_pk_fma_f32 v[92:93], v[236:237], s[22:23], v[92:93] op_sel_hi:[1,0,1]
	v_pk_fma_f32 v[94:95], v[238:239], s[22:23], v[94:95] op_sel_hi:[1,0,1]
	v_cvt_pk_f32_fp8_e32 v[224:225], v208
	v_cvt_pk_f32_fp8_sdwa v[226:227], v208 src0_sel:WORD_1
	v_cvt_pk_f32_fp8_e32 v[228:229], v209
	v_cvt_pk_f32_fp8_sdwa v[230:231], v209 src0_sel:WORD_1
	v_cvt_pk_f32_fp8_e32 v[232:233], v210
	v_cvt_pk_f32_fp8_sdwa v[234:235], v210 src0_sel:WORD_1
	v_cvt_pk_f32_fp8_e32 v[236:237], v211
	v_cvt_pk_f32_fp8_sdwa v[238:239], v211 src0_sel:WORD_1
; DI void peer_item_v(const Params& p, int item) {
;     ...
;     V_ISSUE(vqa, 0)
; #pragma unroll 1
;     for (int g = 0; g < 16; g += 2) {
;       V_ISSUE(vqb, g + 1)
;       V_CONSUME(vqa, g)
;       if (g + 2 < 16) V_ISSUE(vqa, g + 2)
;       V_CONSUME(vqb, g + 1)
;     }
	v_pk_fma_f32 v[80:81], v[224:225], s[24:25], v[80:81] op_sel_hi:[1,0,1]
	v_pk_fma_f32 v[82:83], v[226:227], s[24:25], v[82:83] op_sel_hi:[1,0,1]
	v_pk_fma_f32 v[84:85], v[228:229], s[24:25], v[84:85] op_sel_hi:[1,0,1]
	v_pk_fma_f32 v[86:87], v[230:231], s[24:25], v[86:87] op_sel_hi:[1,0,1]
	v_pk_fma_f32 v[88:89], v[232:233], s[24:25], v[88:89] op_sel_hi:[1,0,1]
	v_pk_fma_f32 v[90:91], v[234:235], s[24:25], v[90:91] op_sel_hi:[1,0,1]
	v_pk_fma_f32 v[92:93], v[236:237], s[24:25], v[92:93] op_sel_hi:[1,0,1]
	v_pk_fma_f32 v[94:95], v[238:239], s[24:25], v[94:95] op_sel_hi:[1,0,1]
	v_cvt_pk_f32_fp8_e32 v[224:225], v212
	v_cvt_pk_f32_fp8_sdwa v[226:227], v212 src0_sel:WORD_1
	v_cvt_pk_f32_fp8_e32 v[228:229], v213
	v_cvt_pk_f32_fp8_sdwa v[230:231], v213 src0_sel:WORD_1
	v_cvt_pk_f32_fp8_e32 v[232:233], v214
	v_cvt_pk_f32_fp8_sdwa v[234:235], v214 src0_sel:WORD_1
	v_cvt_pk_f32_fp8_e32 v[236:237], v215
	v_cvt_pk_f32_fp8_sdwa v[238:239], v215 src0_sel:WORD_1
	v_pk_fma_f32 v[80:81], v[224:225], s[26:27], v[80:81] op_sel_hi:[1,0,1]
	v_pk_fma_f32 v[82:83], v[226:227], s[26:27], v[82:83] op_sel_hi:[1,0,1]
	v_pk_fma_f32 v[84:85], v[228:229], s[26:27], v[84:85] op_sel_hi:[1,0,1]
	v_pk_fma_f32 v[86:87], v[230:231], s[26:27], v[86:87] op_sel_hi:[1,0,1]
	v_pk_fma_f32 v[88:89], v[232:233], s[26:27], v[88:89] op_sel_hi:[1,0,1]
	v_pk_fma_f32 v[90:91], v[234:235], s[26:27], v[90:91] op_sel_hi:[1,0,1]
	v_pk_fma_f32 v[92:93], v[236:237], s[26:27], v[92:93] op_sel_hi:[1,0,1]
	v_pk_fma_f32 v[94:95], v[238:239], s[26:27], v[94:95] op_sel_hi:[1,0,1]
	v_cvt_pk_f32_fp8_e32 v[224:225], v216
	v_cvt_pk_f32_fp8_sdwa v[226:227], v216 src0_sel:WORD_1
	v_cvt_pk_f32_fp8_e32 v[228:229], v217
	v_cvt_pk_f32_fp8_sdwa v[230:231], v217 src0_sel:WORD_1
	v_cvt_pk_f32_fp8_e32 v[232:233], v218
	v_cvt_pk_f32_fp8_sdwa v[234:235], v218 src0_sel:WORD_1
	v_cvt_pk_f32_fp8_e32 v[236:237], v219
	v_cvt_pk_f32_fp8_sdwa v[238:239], v219 src0_sel:WORD_1
	v_pk_fma_f32 v[80:81], v[224:225], s[28:29], v[80:81] op_sel_hi:[1,0,1]
	v_pk_fma_f32 v[82:83], v[226:227], s[28:29], v[82:83] op_sel_hi:[1,0,1]
	v_pk_fma_f32 v[84:85], v[228:229], s[28:29], v[84:85] op_sel_hi:[1,0,1]
	v_pk_fma_f32 v[86:87], v[230:231], s[28:29], v[86:87] op_sel_hi:[1,0,1]
	v_pk_fma_f32 v[88:89], v[232:233], s[28:29], v[88:89] op_sel_hi:[1,0,1]
	v_pk_fma_f32 v[90:91], v[234:235], s[28:29], v[90:91] op_sel_hi:[1,0,1]
	v_pk_fma_f32 v[92:93], v[236:237], s[28:29], v[92:93] op_sel_hi:[1,0,1]
	v_pk_fma_f32 v[94:95], v[238:239], s[28:29], v[94:95] op_sel_hi:[1,0,1]
	v_cvt_pk_f32_fp8_e32 v[224:225], v220
	v_cvt_pk_f32_fp8_sdwa v[226:227], v220 src0_sel:WORD_1
	v_cvt_pk_f32_fp8_e32 v[228:229], v221
	v_cvt_pk_f32_fp8_sdwa v[230:231], v221 src0_sel:WORD_1
	v_cvt_pk_f32_fp8_e32 v[232:233], v222
	v_cvt_pk_f32_fp8_sdwa v[234:235], v222 src0_sel:WORD_1
	v_cvt_pk_f32_fp8_e32 v[236:237], v223
	v_cvt_pk_f32_fp8_sdwa v[238:239], v223 src0_sel:WORD_1
	v_pk_fma_f32 v[80:81], v[224:225], s[30:31], v[80:81] op_sel_hi:[1,0,1]
	v_pk_fma_f32 v[82:83], v[226:227], s[30:31], v[82:83] op_sel_hi:[1,0,1]
	v_pk_fma_f32 v[84:85], v[228:229], s[30:31], v[84:85] op_sel_hi:[1,0,1]
	v_pk_fma_f32 v[86:87], v[230:231], s[30:31], v[86:87] op_sel_hi:[1,0,1]
	v_pk_fma_f32 v[88:89], v[232:233], s[30:31], v[88:89] op_sel_hi:[1,0,1]
	v_pk_fma_f32 v[90:91], v[234:235], s[30:31], v[90:91] op_sel_hi:[1,0,1]
	v_pk_fma_f32 v[92:93], v[236:237], s[30:31], v[92:93] op_sel_hi:[1,0,1]
	v_pk_fma_f32 v[94:95], v[238:239], s[30:31], v[94:95] op_sel_hi:[1,0,1]
	v_readlane_b32 s16, v154, s72
	v_readlane_b32 s18, v154, s73
	v_readlane_b32 s20, v154, s74
	v_readlane_b32 s22, v154, s75
	v_readlane_b32 s24, v154, s76
	v_readlane_b32 s26, v154, s77
	v_readlane_b32 s28, v154, s78
	v_readlane_b32 s30, v154, s79
	v_readlane_b32 s48, v156, s72
	v_readlane_b32 s49, v156, s73
	v_readlane_b32 s50, v156, s74
	v_readlane_b32 s51, v156, s75
	v_readlane_b32 s52, v156, s76
	v_readlane_b32 s53, v156, s77
	v_readlane_b32 s54, v156, s78
	v_readlane_b32 s55, v156, s79
	s_add_u32 s32, s0, s48
	s_addc_u32 s33, s1, 0
	s_add_u32 s34, s0, s49
	s_addc_u32 s35, s1, 0
	s_add_u32 s36, s0, s50
	s_addc_u32 s37, s1, 0
	s_add_u32 s38, s0, s51
	s_addc_u32 s39, s1, 0
	s_add_u32 s40, s0, s52
	s_addc_u32 s41, s1, 0
	s_add_u32 s42, s0, s53
	s_addc_u32 s43, s1, 0
	s_add_u32 s44, s0, s54
	s_addc_u32 s45, s1, 0
	s_add_u32 s46, s0, s55
	s_addc_u32 s47, s1, 0
	global_load_dwordx4 v[192:195], v240, s[32:33]
	global_load_dwordx4 v[196:199], v240, s[34:35]
	global_load_dwordx4 v[200:203], v240, s[36:37]
	global_load_dwordx4 v[204:207], v240, s[38:39]
	global_load_dwordx4 v[208:211], v240, s[40:41]
	global_load_dwordx4 v[212:215], v240, s[42:43]
	global_load_dwordx4 v[216:219], v240, s[44:45]
	global_load_dwordx4 v[220:223], v240, s[46:47]
	s_waitcnt vmcnt(8)
	v_cvt_pk_f32_fp8_e32 v[224:225], v160
	v_cvt_pk_f32_fp8_sdwa v[226:227], v160 src0_sel:WORD_1
	v_cvt_pk_f32_fp8_e32 v[228:229], v161
	v_cvt_pk_f32_fp8_sdwa v[230:231], v161 src0_sel:WORD_1
	v_cvt_pk_f32_fp8_e32 v[232:233], v162
	v_cvt_pk_f32_fp8_sdwa v[234:235], v162 src0_sel:WORD_1
	v_cvt_pk_f32_fp8_e32 v[236:237], v163
	v_cvt_pk_f32_fp8_sdwa v[238:239], v163 src0_sel:WORD_1
	v_pk_fma_f32 v[96:97], v[224:225], s[16:17], v[96:97] op_sel_hi:[1,0,1]
	v_pk_fma_f32 v[98:99], v[226:227], s[16:17], v[98:99] op_sel_hi:[1,0,1]
	v_pk_fma_f32 v[100:101], v[228:229], s[16:17], v[100:101] op_sel_hi:[1,0,1]
	v_pk_fma_f32 v[102:103], v[230:231], s[16:17], v[102:103] op_sel_hi:[1,0,1]
	v_pk_fma_f32 v[104:105], v[232:233], s[16:17], v[104:105] op_sel_hi:[1,0,1]
	v_pk_fma_f32 v[106:107], v[234:235], s[16:17], v[106:107] op_sel_hi:[1,0,1]
	v_pk_fma_f32 v[108:109], v[236:237], s[16:17], v[108:109] op_sel_hi:[1,0,1]
	v_pk_fma_f32 v[110:111], v[238:239], s[16:17], v[110:111] op_sel_hi:[1,0,1]
	v_cvt_pk_f32_fp8_e32 v[224:225], v164
	v_cvt_pk_f32_fp8_sdwa v[226:227], v164 src0_sel:WORD_1
	v_cvt_pk_f32_fp8_e32 v[228:229], v165
	v_cvt_pk_f32_fp8_sdwa v[230:231], v165 src0_sel:WORD_1
	v_cvt_pk_f32_fp8_e32 v[232:233], v166
	v_cvt_pk_f32_fp8_sdwa v[234:235], v166 src0_sel:WORD_1
	v_cvt_pk_f32_fp8_e32 v[236:237], v167
	v_cvt_pk_f32_fp8_sdwa v[238:239], v167 src0_sel:WORD_1
	v_pk_fma_f32 v[96:97], v[224:225], s[18:19], v[96:97] op_sel_hi:[1,0,1]
	v_pk_fma_f32 v[98:99], v[226:227], s[18:19], v[98:99] op_sel_hi:[1,0,1]
	v_pk_fma_f32 v[100:101], v[228:229], s[18:19], v[100:101] op_sel_hi:[1,0,1]
	v_pk_fma_f32 v[102:103], v[230:231], s[18:19], v[102:103] op_sel_hi:[1,0,1]
	v_pk_fma_f32 v[104:105], v[232:233], s[18:19], v[104:105] op_sel_hi:[1,0,1]
	v_pk_fma_f32 v[106:107], v[234:235], s[18:19], v[106:107] op_sel_hi:[1,0,1]
	v_pk_fma_f32 v[108:109], v[236:237], s[18:19], v[108:109] op_sel_hi:[1,0,1]
	v_pk_fma_f32 v[110:111], v[238:239], s[18:19], v[110:111] op_sel_hi:[1,0,1]
	v_cvt_pk_f32_fp8_e32 v[224:225], v168
	v_cvt_pk_f32_fp8_sdwa v[226:227], v168 src0_sel:WORD_1
	v_cvt_pk_f32_fp8_e32 v[228:229], v169
	v_cvt_pk_f32_fp8_sdwa v[230:231], v169 src0_sel:WORD_1
	v_cvt_pk_f32_fp8_e32 v[232:233], v170
	v_cvt_pk_f32_fp8_sdwa v[234:235], v170 src0_sel:WORD_1
	v_cvt_pk_f32_fp8_e32 v[236:237], v171
	v_cvt_pk_f32_fp8_sdwa v[238:239], v171 src0_sel:WORD_1
	v_pk_fma_f32 v[96:97], v[224:225], s[20:21], v[96:97] op_sel_hi:[1,0,1]
	v_pk_fma_f32 v[98:99], v[226:227], s[20:21], v[98:99] op_sel_hi:[1,0,1]
	v_pk_fma_f32 v[100:101], v[228:229], s[20:21], v[100:101] op_sel_hi:[1,0,1]
	v_pk_fma_f32 v[102:103], v[230:231], s[20:21], v[102:103] op_sel_hi:[1,0,1]
	v_pk_fma_f32 v[104:105], v[232:233], s[20:21], v[104:105] op_sel_hi:[1,0,1]
	v_pk_fma_f32 v[106:107], v[234:235], s[20:21], v[106:107] op_sel_hi:[1,0,1]
	v_pk_fma_f32 v[108:109], v[236:237], s[20:21], v[108:109] op_sel_hi:[1,0,1]
	v_pk_fma_f32 v[110:111], v[238:239], s[20:21], v[110:111] op_sel_hi:[1,0,1]
	v_cvt_pk_f32_fp8_e32 v[224:225], v172
	v_cvt_pk_f32_fp8_sdwa v[226:227], v172 src0_sel:WORD_1
	v_cvt_pk_f32_fp8_e32 v[228:229], v173
	v_cvt_pk_f32_fp8_sdwa v[230:231], v173 src0_sel:WORD_1
	v_cvt_pk_f32_fp8_e32 v[232:233], v174
	v_cvt_pk_f32_fp8_sdwa v[234:235], v174 src0_sel:WORD_1
	v_cvt_pk_f32_fp8_e32 v[236:237], v175
	v_cvt_pk_f32_fp8_sdwa v[238:239], v175 src0_sel:WORD_1
	v_pk_fma_f32 v[96:97], v[224:225], s[22:23], v[96:97] op_sel_hi:[1,0,1]
	v_pk_fma_f32 v[98:99], v[226:227], s[22:23], v[98:99] op_sel_hi:[1,0,1]
	v_pk_fma_f32 v[100:101], v[228:229], s[22:23], v[100:101] op_sel_hi:[1,0,1]
	v_pk_fma_f32 v[102:103], v[230:231], s[22:23], v[102:103] op_sel_hi:[1,0,1]
	v_pk_fma_f32 v[104:105], v[232:233], s[22:23], v[104:105] op_sel_hi:[1,0,1]
	v_pk_fma_f32 v[106:107], v[234:235], s[22:23], v[106:107] op_sel_hi:[1,0,1]
	v_pk_fma_f32 v[108:109], v[236:237], s[22:23], v[108:109] op_sel_hi:[1,0,1]
	v_pk_fma_f32 v[110:111], v[238:239], s[22:23], v[110:111] op_sel_hi:[1,0,1]
	v_cvt_pk_f32_fp8_e32 v[224:225], v176
	v_cvt_pk_f32_fp8_sdwa v[226:227], v176 src0_sel:WORD_1
	v_cvt_pk_f32_fp8_e32 v[228:229], v177
	v_cvt_pk_f32_fp8_sdwa v[230:231], v177 src0_sel:WORD_1
	v_cvt_pk_f32_fp8_e32 v[232:233], v178
	v_cvt_pk_f32_fp8_sdwa v[234:235], v178 src0_sel:WORD_1
	v_cvt_pk_f32_fp8_e32 v[236:237], v179
	v_cvt_pk_f32_fp8_sdwa v[238:239], v179 src0_sel:WORD_1
	v_pk_fma_f32 v[96:97], v[224:225], s[24:25], v[96:97] op_sel_hi:[1,0,1]
	v_pk_fma_f32 v[98:99], v[226:227], s[24:25], v[98:99] op_sel_hi:[1,0,1]
	v_pk_fma_f32 v[100:101], v[228:229], s[24:25], v[100:101] op_sel_hi:[1,0,1]
	v_pk_fma_f32 v[102:103], v[230:231], s[24:25], v[102:103] op_sel_hi:[1,0,1]
	v_pk_fma_f32 v[104:105], v[232:233], s[24:25], v[104:105] op_sel_hi:[1,0,1]
	v_pk_fma_f32 v[106:107], v[234:235], s[24:25], v[106:107] op_sel_hi:[1,0,1]
	v_pk_fma_f32 v[108:109], v[236:237], s[24:25], v[108:109] op_sel_hi:[1,0,1]
	v_pk_fma_f32 v[110:111], v[238:239], s[24:25], v[110:111] op_sel_hi:[1,0,1]
	v_cvt_pk_f32_fp8_e32 v[224:225], v180
	v_cvt_pk_f32_fp8_sdwa v[226:227], v180 src0_sel:WORD_1
	v_cvt_pk_f32_fp8_e32 v[228:229], v181
	v_cvt_pk_f32_fp8_sdwa v[230:231], v181 src0_sel:WORD_1
	v_cvt_pk_f32_fp8_e32 v[232:233], v182
	v_cvt_pk_f32_fp8_sdwa v[234:235], v182 src0_sel:WORD_1
	v_cvt_pk_f32_fp8_e32 v[236:237], v183
	v_cvt_pk_f32_fp8_sdwa v[238:239], v183 src0_sel:WORD_1
	v_pk_fma_f32 v[96:97], v[224:225], s[26:27], v[96:97] op_sel_hi:[1,0,1]
	v_pk_fma_f32 v[98:99], v[226:227], s[26:27], v[98:99] op_sel_hi:[1,0,1]
	v_pk_fma_f32 v[100:101], v[228:229], s[26:27], v[100:101] op_sel_hi:[1,0,1]
	v_pk_fma_f32 v[102:103], v[230:231], s[26:27], v[102:103] op_sel_hi:[1,0,1]
; DI void peer_item_v(const Params& p, int item) {
;     ...
;     V_ISSUE(vqa, 0)
; #pragma unroll 1
;     for (int g = 0; g < 16; g += 2) {
;       V_ISSUE(vqb, g + 1)
;       V_CONSUME(vqa, g)
;       if (g + 2 < 16) V_ISSUE(vqa, g + 2)
;       V_CONSUME(vqb, g + 1)
;     }
	v_pk_fma_f32 v[104:105], v[232:233], s[26:27], v[104:105] op_sel_hi:[1,0,1]
	v_pk_fma_f32 v[106:107], v[234:235], s[26:27], v[106:107] op_sel_hi:[1,0,1]
	v_pk_fma_f32 v[108:109], v[236:237], s[26:27], v[108:109] op_sel_hi:[1,0,1]
	v_pk_fma_f32 v[110:111], v[238:239], s[26:27], v[110:111] op_sel_hi:[1,0,1]
	v_cvt_pk_f32_fp8_e32 v[224:225], v184
	v_cvt_pk_f32_fp8_sdwa v[226:227], v184 src0_sel:WORD_1
	v_cvt_pk_f32_fp8_e32 v[228:229], v185
	v_cvt_pk_f32_fp8_sdwa v[230:231], v185 src0_sel:WORD_1
	v_cvt_pk_f32_fp8_e32 v[232:233], v186
	v_cvt_pk_f32_fp8_sdwa v[234:235], v186 src0_sel:WORD_1
	v_cvt_pk_f32_fp8_e32 v[236:237], v187
	v_cvt_pk_f32_fp8_sdwa v[238:239], v187 src0_sel:WORD_1
	v_pk_fma_f32 v[96:97], v[224:225], s[28:29], v[96:97] op_sel_hi:[1,0,1]
	v_pk_fma_f32 v[98:99], v[226:227], s[28:29], v[98:99] op_sel_hi:[1,0,1]
	v_pk_fma_f32 v[100:101], v[228:229], s[28:29], v[100:101] op_sel_hi:[1,0,1]
	v_pk_fma_f32 v[102:103], v[230:231], s[28:29], v[102:103] op_sel_hi:[1,0,1]
	v_pk_fma_f32 v[104:105], v[232:233], s[28:29], v[104:105] op_sel_hi:[1,0,1]
	v_pk_fma_f32 v[106:107], v[234:235], s[28:29], v[106:107] op_sel_hi:[1,0,1]
	v_pk_fma_f32 v[108:109], v[236:237], s[28:29], v[108:109] op_sel_hi:[1,0,1]
	v_pk_fma_f32 v[110:111], v[238:239], s[28:29], v[110:111] op_sel_hi:[1,0,1]
	v_cvt_pk_f32_fp8_e32 v[224:225], v188
	v_cvt_pk_f32_fp8_sdwa v[226:227], v188 src0_sel:WORD_1
	v_cvt_pk_f32_fp8_e32 v[228:229], v189
	v_cvt_pk_f32_fp8_sdwa v[230:231], v189 src0_sel:WORD_1
	v_cvt_pk_f32_fp8_e32 v[232:233], v190
	v_cvt_pk_f32_fp8_sdwa v[234:235], v190 src0_sel:WORD_1
	v_cvt_pk_f32_fp8_e32 v[236:237], v191
	v_cvt_pk_f32_fp8_sdwa v[238:239], v191 src0_sel:WORD_1
	v_pk_fma_f32 v[96:97], v[224:225], s[30:31], v[96:97] op_sel_hi:[1,0,1]
	v_pk_fma_f32 v[98:99], v[226:227], s[30:31], v[98:99] op_sel_hi:[1,0,1]
	v_pk_fma_f32 v[100:101], v[228:229], s[30:31], v[100:101] op_sel_hi:[1,0,1]
	v_pk_fma_f32 v[102:103], v[230:231], s[30:31], v[102:103] op_sel_hi:[1,0,1]
	v_pk_fma_f32 v[104:105], v[232:233], s[30:31], v[104:105] op_sel_hi:[1,0,1]
	v_pk_fma_f32 v[106:107], v[234:235], s[30:31], v[106:107] op_sel_hi:[1,0,1]
	v_pk_fma_f32 v[108:109], v[236:237], s[30:31], v[108:109] op_sel_hi:[1,0,1]
	v_pk_fma_f32 v[110:111], v[238:239], s[30:31], v[110:111] op_sel_hi:[1,0,1]
	v_readlane_b32 s16, v158, s72
	v_readlane_b32 s18, v158, s73
	v_readlane_b32 s20, v158, s74
	v_readlane_b32 s22, v158, s75
	v_readlane_b32 s24, v158, s76
	v_readlane_b32 s26, v158, s77
	v_readlane_b32 s28, v158, s78
	v_readlane_b32 s30, v158, s79
	v_readlane_b32 s48, v145, s72
	v_readlane_b32 s49, v145, s73
	v_readlane_b32 s50, v145, s74
	v_readlane_b32 s51, v145, s75
	v_readlane_b32 s52, v145, s76
	v_readlane_b32 s53, v145, s77
	v_readlane_b32 s54, v145, s78
	v_readlane_b32 s55, v145, s79
	s_add_u32 s32, s0, s48
	s_addc_u32 s33, s1, 0
	s_add_u32 s34, s0, s49
	s_addc_u32 s35, s1, 0
	s_add_u32 s36, s0, s50
	s_addc_u32 s37, s1, 0
	s_add_u32 s38, s0, s51
	s_addc_u32 s39, s1, 0
	s_add_u32 s40, s0, s52
	s_addc_u32 s41, s1, 0
	s_add_u32 s42, s0, s53
	s_addc_u32 s43, s1, 0
	s_add_u32 s44, s0, s54
	s_addc_u32 s45, s1, 0
	s_add_u32 s46, s0, s55
	s_addc_u32 s47, s1, 0
	global_load_dwordx4 v[160:163], v240, s[32:33]
	global_load_dwordx4 v[164:167], v240, s[34:35]
	global_load_dwordx4 v[168:171], v240, s[36:37]
	global_load_dwordx4 v[172:175], v240, s[38:39]
	global_load_dwordx4 v[176:179], v240, s[40:41]
	global_load_dwordx4 v[180:183], v240, s[42:43]
	global_load_dwordx4 v[184:187], v240, s[44:45]
	global_load_dwordx4 v[188:191], v240, s[46:47]
	s_waitcnt vmcnt(8)
	v_cvt_pk_f32_fp8_e32 v[224:225], v192
	v_cvt_pk_f32_fp8_sdwa v[226:227], v192 src0_sel:WORD_1
	v_cvt_pk_f32_fp8_e32 v[228:229], v193
	v_cvt_pk_f32_fp8_sdwa v[230:231], v193 src0_sel:WORD_1
	v_cvt_pk_f32_fp8_e32 v[232:233], v194
	v_cvt_pk_f32_fp8_sdwa v[234:235], v194 src0_sel:WORD_1
	v_cvt_pk_f32_fp8_e32 v[236:237], v195
	v_cvt_pk_f32_fp8_sdwa v[238:239], v195 src0_sel:WORD_1
	v_pk_fma_f32 v[112:113], v[224:225], s[16:17], v[112:113] op_sel_hi:[1,0,1]
	v_pk_fma_f32 v[114:115], v[226:227], s[16:17], v[114:115] op_sel_hi:[1,0,1]
	v_pk_fma_f32 v[116:117], v[228:229], s[16:17], v[116:117] op_sel_hi:[1,0,1]
	v_pk_fma_f32 v[118:119], v[230:231], s[16:17], v[118:119] op_sel_hi:[1,0,1]
	v_pk_fma_f32 v[120:121], v[232:233], s[16:17], v[120:121] op_sel_hi:[1,0,1]
	v_pk_fma_f32 v[122:123], v[234:235], s[16:17], v[122:123] op_sel_hi:[1,0,1]
	v_pk_fma_f32 v[124:125], v[236:237], s[16:17], v[124:125] op_sel_hi:[1,0,1]
	v_pk_fma_f32 v[126:127], v[238:239], s[16:17], v[126:127] op_sel_hi:[1,0,1]
	v_cvt_pk_f32_fp8_e32 v[224:225], v196
	v_cvt_pk_f32_fp8_sdwa v[226:227], v196 src0_sel:WORD_1
	v_cvt_pk_f32_fp8_e32 v[228:229], v197
	v_cvt_pk_f32_fp8_sdwa v[230:231], v197 src0_sel:WORD_1
	v_cvt_pk_f32_fp8_e32 v[232:233], v198
	v_cvt_pk_f32_fp8_sdwa v[234:235], v198 src0_sel:WORD_1
	v_cvt_pk_f32_fp8_e32 v[236:237], v199
	v_cvt_pk_f32_fp8_sdwa v[238:239], v199 src0_sel:WORD_1
	v_pk_fma_f32 v[112:113], v[224:225], s[18:19], v[112:113] op_sel_hi:[1,0,1]
	v_pk_fma_f32 v[114:115], v[226:227], s[18:19], v[114:115] op_sel_hi:[1,0,1]
	v_pk_fma_f32 v[116:117], v[228:229], s[18:19], v[116:117] op_sel_hi:[1,0,1]
	v_pk_fma_f32 v[118:119], v[230:231], s[18:19], v[118:119] op_sel_hi:[1,0,1]
	v_pk_fma_f32 v[120:121], v[232:233], s[18:19], v[120:121] op_sel_hi:[1,0,1]
	v_pk_fma_f32 v[122:123], v[234:235], s[18:19], v[122:123] op_sel_hi:[1,0,1]
	v_pk_fma_f32 v[124:125], v[236:237], s[18:19], v[124:125] op_sel_hi:[1,0,1]
	v_pk_fma_f32 v[126:127], v[238:239], s[18:19], v[126:127] op_sel_hi:[1,0,1]
	v_cvt_pk_f32_fp8_e32 v[224:225], v200
	v_cvt_pk_f32_fp8_sdwa v[226:227], v200 src0_sel:WORD_1
	v_cvt_pk_f32_fp8_e32 v[228:229], v201
	v_cvt_pk_f32_fp8_sdwa v[230:231], v201 src0_sel:WORD_1
	v_cvt_pk_f32_fp8_e32 v[232:233], v202
	v_cvt_pk_f32_fp8_sdwa v[234:235], v202 src0_sel:WORD_1
	v_cvt_pk_f32_fp8_e32 v[236:237], v203
	v_cvt_pk_f32_fp8_sdwa v[238:239], v203 src0_sel:WORD_1
	v_pk_fma_f32 v[112:113], v[224:225], s[20:21], v[112:113] op_sel_hi:[1,0,1]
	v_pk_fma_f32 v[114:115], v[226:227], s[20:21], v[114:115] op_sel_hi:[1,0,1]
	v_pk_fma_f32 v[116:117], v[228:229], s[20:21], v[116:117] op_sel_hi:[1,0,1]
	v_pk_fma_f32 v[118:119], v[230:231], s[20:21], v[118:119] op_sel_hi:[1,0,1]
	v_pk_fma_f32 v[120:121], v[232:233], s[20:21], v[120:121] op_sel_hi:[1,0,1]
	v_pk_fma_f32 v[122:123], v[234:235], s[20:21], v[122:123] op_sel_hi:[1,0,1]
	v_pk_fma_f32 v[124:125], v[236:237], s[20:21], v[124:125] op_sel_hi:[1,0,1]
	v_pk_fma_f32 v[126:127], v[238:239], s[20:21], v[126:127] op_sel_hi:[1,0,1]
	v_cvt_pk_f32_fp8_e32 v[224:225], v204
	v_cvt_pk_f32_fp8_sdwa v[226:227], v204 src0_sel:WORD_1
	v_cvt_pk_f32_fp8_e32 v[228:229], v205
	v_cvt_pk_f32_fp8_sdwa v[230:231], v205 src0_sel:WORD_1
	v_cvt_pk_f32_fp8_e32 v[232:233], v206
	v_cvt_pk_f32_fp8_sdwa v[234:235], v206 src0_sel:WORD_1
	v_cvt_pk_f32_fp8_e32 v[236:237], v207
	v_cvt_pk_f32_fp8_sdwa v[238:239], v207 src0_sel:WORD_1
	v_pk_fma_f32 v[112:113], v[224:225], s[22:23], v[112:113] op_sel_hi:[1,0,1]
	v_pk_fma_f32 v[114:115], v[226:227], s[22:23], v[114:115] op_sel_hi:[1,0,1]
	v_pk_fma_f32 v[116:117], v[228:229], s[22:23], v[116:117] op_sel_hi:[1,0,1]
	v_pk_fma_f32 v[118:119], v[230:231], s[22:23], v[118:119] op_sel_hi:[1,0,1]
	v_pk_fma_f32 v[120:121], v[232:233], s[22:23], v[120:121] op_sel_hi:[1,0,1]
	v_pk_fma_f32 v[122:123], v[234:235], s[22:23], v[122:123] op_sel_hi:[1,0,1]
	v_pk_fma_f32 v[124:125], v[236:237], s[22:23], v[124:125] op_sel_hi:[1,0,1]
	v_pk_fma_f32 v[126:127], v[238:239], s[22:23], v[126:127] op_sel_hi:[1,0,1]
	v_cvt_pk_f32_fp8_e32 v[224:225], v208
	v_cvt_pk_f32_fp8_sdwa v[226:227], v208 src0_sel:WORD_1
	v_cvt_pk_f32_fp8_e32 v[228:229], v209
	v_cvt_pk_f32_fp8_sdwa v[230:231], v209 src0_sel:WORD_1
	v_cvt_pk_f32_fp8_e32 v[232:233], v210
	v_cvt_pk_f32_fp8_sdwa v[234:235], v210 src0_sel:WORD_1
	v_cvt_pk_f32_fp8_e32 v[236:237], v211
	v_cvt_pk_f32_fp8_sdwa v[238:239], v211 src0_sel:WORD_1
	v_pk_fma_f32 v[112:113], v[224:225], s[24:25], v[112:113] op_sel_hi:[1,0,1]
	v_pk_fma_f32 v[114:115], v[226:227], s[24:25], v[114:115] op_sel_hi:[1,0,1]
	v_pk_fma_f32 v[116:117], v[228:229], s[24:25], v[116:117] op_sel_hi:[1,0,1]
	v_pk_fma_f32 v[118:119], v[230:231], s[24:25], v[118:119] op_sel_hi:[1,0,1]
	v_pk_fma_f32 v[120:121], v[232:233], s[24:25], v[120:121] op_sel_hi:[1,0,1]
	v_pk_fma_f32 v[122:123], v[234:235], s[24:25], v[122:123] op_sel_hi:[1,0,1]
	v_pk_fma_f32 v[124:125], v[236:237], s[24:25], v[124:125] op_sel_hi:[1,0,1]
	v_pk_fma_f32 v[126:127], v[238:239], s[24:25], v[126:127] op_sel_hi:[1,0,1]
	v_cvt_pk_f32_fp8_e32 v[224:225], v212
	v_cvt_pk_f32_fp8_sdwa v[226:227], v212 src0_sel:WORD_1
	v_cvt_pk_f32_fp8_e32 v[228:229], v213
	v_cvt_pk_f32_fp8_sdwa v[230:231], v213 src0_sel:WORD_1
	v_cvt_pk_f32_fp8_e32 v[232:233], v214
	v_cvt_pk_f32_fp8_sdwa v[234:235], v214 src0_sel:WORD_1
	v_cvt_pk_f32_fp8_e32 v[236:237], v215
	v_cvt_pk_f32_fp8_sdwa v[238:239], v215 src0_sel:WORD_1
	v_pk_fma_f32 v[112:113], v[224:225], s[26:27], v[112:113] op_sel_hi:[1,0,1]
	v_pk_fma_f32 v[114:115], v[226:227], s[26:27], v[114:115] op_sel_hi:[1,0,1]
	v_pk_fma_f32 v[116:117], v[228:229], s[26:27], v[116:117] op_sel_hi:[1,0,1]
	v_pk_fma_f32 v[118:119], v[230:231], s[26:27], v[118:119] op_sel_hi:[1,0,1]
	v_pk_fma_f32 v[120:121], v[232:233], s[26:27], v[120:121] op_sel_hi:[1,0,1]
	v_pk_fma_f32 v[122:123], v[234:235], s[26:27], v[122:123] op_sel_hi:[1,0,1]
	v_pk_fma_f32 v[124:125], v[236:237], s[26:27], v[124:125] op_sel_hi:[1,0,1]
	v_pk_fma_f32 v[126:127], v[238:239], s[26:27], v[126:127] op_sel_hi:[1,0,1]
	v_cvt_pk_f32_fp8_e32 v[224:225], v216
	v_cvt_pk_f32_fp8_sdwa v[226:227], v216 src0_sel:WORD_1
	v_cvt_pk_f32_fp8_e32 v[228:229], v217
	v_cvt_pk_f32_fp8_sdwa v[230:231], v217 src0_sel:WORD_1
	v_cvt_pk_f32_fp8_e32 v[232:233], v218
	v_cvt_pk_f32_fp8_sdwa v[234:235], v218 src0_sel:WORD_1
	v_cvt_pk_f32_fp8_e32 v[236:237], v219
	v_cvt_pk_f32_fp8_sdwa v[238:239], v219 src0_sel:WORD_1
	v_pk_fma_f32 v[112:113], v[224:225], s[28:29], v[112:113] op_sel_hi:[1,0,1]
	v_pk_fma_f32 v[114:115], v[226:227], s[28:29], v[114:115] op_sel_hi:[1,0,1]
	v_pk_fma_f32 v[116:117], v[228:229], s[28:29], v[116:117] op_sel_hi:[1,0,1]
	v_pk_fma_f32 v[118:119], v[230:231], s[28:29], v[118:119] op_sel_hi:[1,0,1]
	v_pk_fma_f32 v[120:121], v[232:233], s[28:29], v[120:121] op_sel_hi:[1,0,1]
	v_pk_fma_f32 v[122:123], v[234:235], s[28:29], v[122:123] op_sel_hi:[1,0,1]
	v_pk_fma_f32 v[124:125], v[236:237], s[28:29], v[124:125] op_sel_hi:[1,0,1]
	v_pk_fma_f32 v[126:127], v[238:239], s[28:29], v[126:127] op_sel_hi:[1,0,1]
	v_cvt_pk_f32_fp8_e32 v[224:225], v220
	v_cvt_pk_f32_fp8_sdwa v[226:227], v220 src0_sel:WORD_1
	v_cvt_pk_f32_fp8_e32 v[228:229], v221
	v_cvt_pk_f32_fp8_sdwa v[230:231], v221 src0_sel:WORD_1
	v_cvt_pk_f32_fp8_e32 v[232:233], v222
	v_cvt_pk_f32_fp8_sdwa v[234:235], v222 src0_sel:WORD_1
	v_cvt_pk_f32_fp8_e32 v[236:237], v223
	v_cvt_pk_f32_fp8_sdwa v[238:239], v223 src0_sel:WORD_1
	v_pk_fma_f32 v[112:113], v[224:225], s[30:31], v[112:113] op_sel_hi:[1,0,1]
	v_pk_fma_f32 v[114:115], v[226:227], s[30:31], v[114:115] op_sel_hi:[1,0,1]
	v_pk_fma_f32 v[116:117], v[228:229], s[30:31], v[116:117] op_sel_hi:[1,0,1]
	v_pk_fma_f32 v[118:119], v[230:231], s[30:31], v[118:119] op_sel_hi:[1,0,1]
	v_pk_fma_f32 v[120:121], v[232:233], s[30:31], v[120:121] op_sel_hi:[1,0,1]
; DI void peer_item_v(const Params& p, int item) {
;     ...
;     V_ISSUE(vqa, 0)
; #pragma unroll 1
;     for (int g = 0; g < 16; g += 2) {
;       V_ISSUE(vqb, g + 1)
;       V_CONSUME(vqa, g)
;       if (g + 2 < 16) V_ISSUE(vqa, g + 2)
;       V_CONSUME(vqb, g + 1)
;     }
	v_pk_fma_f32 v[122:123], v[234:235], s[30:31], v[122:123] op_sel_hi:[1,0,1]
	v_pk_fma_f32 v[124:125], v[236:237], s[30:31], v[124:125] op_sel_hi:[1,0,1]
	v_pk_fma_f32 v[126:127], v[238:239], s[30:31], v[126:127] op_sel_hi:[1,0,1]
	v_readlane_b32 s16, v147, s72
	v_readlane_b32 s18, v147, s73
	v_readlane_b32 s20, v147, s74
	v_readlane_b32 s22, v147, s75
	v_readlane_b32 s24, v147, s76
	v_readlane_b32 s26, v147, s77
	v_readlane_b32 s28, v147, s78
	v_readlane_b32 s30, v147, s79
	v_readlane_b32 s48, v149, s72
	v_readlane_b32 s49, v149, s73
	v_readlane_b32 s50, v149, s74
	v_readlane_b32 s51, v149, s75
	v_readlane_b32 s52, v149, s76
	v_readlane_b32 s53, v149, s77
	v_readlane_b32 s54, v149, s78
	v_readlane_b32 s55, v149, s79
	s_add_u32 s32, s0, s48
	s_addc_u32 s33, s1, 0
	s_add_u32 s34, s0, s49
	s_addc_u32 s35, s1, 0
	s_add_u32 s36, s0, s50
	s_addc_u32 s37, s1, 0
	s_add_u32 s38, s0, s51
	s_addc_u32 s39, s1, 0
	s_add_u32 s40, s0, s52
	s_addc_u32 s41, s1, 0
	s_add_u32 s42, s0, s53
	s_addc_u32 s43, s1, 0
	s_add_u32 s44, s0, s54
	s_addc_u32 s45, s1, 0
	s_add_u32 s46, s0, s55
	s_addc_u32 s47, s1, 0
	global_load_dwordx4 v[192:195], v240, s[32:33]
	global_load_dwordx4 v[196:199], v240, s[34:35]
	global_load_dwordx4 v[200:203], v240, s[36:37]
	global_load_dwordx4 v[204:207], v240, s[38:39]
	global_load_dwordx4 v[208:211], v240, s[40:41]
	global_load_dwordx4 v[212:215], v240, s[42:43]
	global_load_dwordx4 v[216:219], v240, s[44:45]
	global_load_dwordx4 v[220:223], v240, s[46:47]
	s_waitcnt vmcnt(8)
	v_cvt_pk_f32_fp8_e32 v[224:225], v160
	v_cvt_pk_f32_fp8_sdwa v[226:227], v160 src0_sel:WORD_1
	v_cvt_pk_f32_fp8_e32 v[228:229], v161
	v_cvt_pk_f32_fp8_sdwa v[230:231], v161 src0_sel:WORD_1
	v_cvt_pk_f32_fp8_e32 v[232:233], v162
	v_cvt_pk_f32_fp8_sdwa v[234:235], v162 src0_sel:WORD_1
	v_cvt_pk_f32_fp8_e32 v[236:237], v163
	v_cvt_pk_f32_fp8_sdwa v[238:239], v163 src0_sel:WORD_1
	v_pk_fma_f32 v[64:65], v[224:225], s[16:17], v[64:65] op_sel_hi:[1,0,1]
	v_pk_fma_f32 v[66:67], v[226:227], s[16:17], v[66:67] op_sel_hi:[1,0,1]
	v_pk_fma_f32 v[68:69], v[228:229], s[16:17], v[68:69] op_sel_hi:[1,0,1]
	v_pk_fma_f32 v[70:71], v[230:231], s[16:17], v[70:71] op_sel_hi:[1,0,1]
	v_pk_fma_f32 v[72:73], v[232:233], s[16:17], v[72:73] op_sel_hi:[1,0,1]
	v_pk_fma_f32 v[74:75], v[234:235], s[16:17], v[74:75] op_sel_hi:[1,0,1]
	v_pk_fma_f32 v[76:77], v[236:237], s[16:17], v[76:77] op_sel_hi:[1,0,1]
	v_pk_fma_f32 v[78:79], v[238:239], s[16:17], v[78:79] op_sel_hi:[1,0,1]
	v_cvt_pk_f32_fp8_e32 v[224:225], v164
	v_cvt_pk_f32_fp8_sdwa v[226:227], v164 src0_sel:WORD_1
	v_cvt_pk_f32_fp8_e32 v[228:229], v165
	v_cvt_pk_f32_fp8_sdwa v[230:231], v165 src0_sel:WORD_1
	v_cvt_pk_f32_fp8_e32 v[232:233], v166
	v_cvt_pk_f32_fp8_sdwa v[234:235], v166 src0_sel:WORD_1
	v_cvt_pk_f32_fp8_e32 v[236:237], v167
	v_cvt_pk_f32_fp8_sdwa v[238:239], v167 src0_sel:WORD_1
	v_pk_fma_f32 v[64:65], v[224:225], s[18:19], v[64:65] op_sel_hi:[1,0,1]
	v_pk_fma_f32 v[66:67], v[226:227], s[18:19], v[66:67] op_sel_hi:[1,0,1]
	v_pk_fma_f32 v[68:69], v[228:229], s[18:19], v[68:69] op_sel_hi:[1,0,1]
	v_pk_fma_f32 v[70:71], v[230:231], s[18:19], v[70:71] op_sel_hi:[1,0,1]
	v_pk_fma_f32 v[72:73], v[232:233], s[18:19], v[72:73] op_sel_hi:[1,0,1]
	v_pk_fma_f32 v[74:75], v[234:235], s[18:19], v[74:75] op_sel_hi:[1,0,1]
	v_pk_fma_f32 v[76:77], v[236:237], s[18:19], v[76:77] op_sel_hi:[1,0,1]
	v_pk_fma_f32 v[78:79], v[238:239], s[18:19], v[78:79] op_sel_hi:[1,0,1]
	v_cvt_pk_f32_fp8_e32 v[224:225], v168
	v_cvt_pk_f32_fp8_sdwa v[226:227], v168 src0_sel:WORD_1
	v_cvt_pk_f32_fp8_e32 v[228:229], v169
	v_cvt_pk_f32_fp8_sdwa v[230:231], v169 src0_sel:WORD_1
	v_cvt_pk_f32_fp8_e32 v[232:233], v170
	v_cvt_pk_f32_fp8_sdwa v[234:235], v170 src0_sel:WORD_1
	v_cvt_pk_f32_fp8_e32 v[236:237], v171
	v_cvt_pk_f32_fp8_sdwa v[238:239], v171 src0_sel:WORD_1
	v_pk_fma_f32 v[64:65], v[224:225], s[20:21], v[64:65] op_sel_hi:[1,0,1]
	v_pk_fma_f32 v[66:67], v[226:227], s[20:21], v[66:67] op_sel_hi:[1,0,1]
	v_pk_fma_f32 v[68:69], v[228:229], s[20:21], v[68:69] op_sel_hi:[1,0,1]
	v_pk_fma_f32 v[70:71], v[230:231], s[20:21], v[70:71] op_sel_hi:[1,0,1]
	v_pk_fma_f32 v[72:73], v[232:233], s[20:21], v[72:73] op_sel_hi:[1,0,1]
	v_pk_fma_f32 v[74:75], v[234:235], s[20:21], v[74:75] op_sel_hi:[1,0,1]
	v_pk_fma_f32 v[76:77], v[236:237], s[20:21], v[76:77] op_sel_hi:[1,0,1]
	v_pk_fma_f32 v[78:79], v[238:239], s[20:21], v[78:79] op_sel_hi:[1,0,1]
	v_cvt_pk_f32_fp8_e32 v[224:225], v172
	v_cvt_pk_f32_fp8_sdwa v[226:227], v172 src0_sel:WORD_1
	v_cvt_pk_f32_fp8_e32 v[228:229], v173
	v_cvt_pk_f32_fp8_sdwa v[230:231], v173 src0_sel:WORD_1
	v_cvt_pk_f32_fp8_e32 v[232:233], v174
	v_cvt_pk_f32_fp8_sdwa v[234:235], v174 src0_sel:WORD_1
	v_cvt_pk_f32_fp8_e32 v[236:237], v175
	v_cvt_pk_f32_fp8_sdwa v[238:239], v175 src0_sel:WORD_1
	v_pk_fma_f32 v[64:65], v[224:225], s[22:23], v[64:65] op_sel_hi:[1,0,1]
	v_pk_fma_f32 v[66:67], v[226:227], s[22:23], v[66:67] op_sel_hi:[1,0,1]
	v_pk_fma_f32 v[68:69], v[228:229], s[22:23], v[68:69] op_sel_hi:[1,0,1]
	v_pk_fma_f32 v[70:71], v[230:231], s[22:23], v[70:71] op_sel_hi:[1,0,1]
	v_pk_fma_f32 v[72:73], v[232:233], s[22:23], v[72:73] op_sel_hi:[1,0,1]
	v_pk_fma_f32 v[74:75], v[234:235], s[22:23], v[74:75] op_sel_hi:[1,0,1]
	v_pk_fma_f32 v[76:77], v[236:237], s[22:23], v[76:77] op_sel_hi:[1,0,1]
	v_pk_fma_f32 v[78:79], v[238:239], s[22:23], v[78:79] op_sel_hi:[1,0,1]
	v_cvt_pk_f32_fp8_e32 v[224:225], v176
	v_cvt_pk_f32_fp8_sdwa v[226:227], v176 src0_sel:WORD_1
	v_cvt_pk_f32_fp8_e32 v[228:229], v177
	v_cvt_pk_f32_fp8_sdwa v[230:231], v177 src0_sel:WORD_1
	v_cvt_pk_f32_fp8_e32 v[232:233], v178
	v_cvt_pk_f32_fp8_sdwa v[234:235], v178 src0_sel:WORD_1
	v_cvt_pk_f32_fp8_e32 v[236:237], v179
	v_cvt_pk_f32_fp8_sdwa v[238:239], v179 src0_sel:WORD_1
	v_pk_fma_f32 v[64:65], v[224:225], s[24:25], v[64:65] op_sel_hi:[1,0,1]
	v_pk_fma_f32 v[66:67], v[226:227], s[24:25], v[66:67] op_sel_hi:[1,0,1]
	v_pk_fma_f32 v[68:69], v[228:229], s[24:25], v[68:69] op_sel_hi:[1,0,1]
	v_pk_fma_f32 v[70:71], v[230:231], s[24:25], v[70:71] op_sel_hi:[1,0,1]
	v_pk_fma_f32 v[72:73], v[232:233], s[24:25], v[72:73] op_sel_hi:[1,0,1]
	v_pk_fma_f32 v[74:75], v[234:235], s[24:25], v[74:75] op_sel_hi:[1,0,1]
	v_pk_fma_f32 v[76:77], v[236:237], s[24:25], v[76:77] op_sel_hi:[1,0,1]
	v_pk_fma_f32 v[78:79], v[238:239], s[24:25], v[78:79] op_sel_hi:[1,0,1]
	v_cvt_pk_f32_fp8_e32 v[224:225], v180
	v_cvt_pk_f32_fp8_sdwa v[226:227], v180 src0_sel:WORD_1
	v_cvt_pk_f32_fp8_e32 v[228:229], v181
	v_cvt_pk_f32_fp8_sdwa v[230:231], v181 src0_sel:WORD_1
	v_cvt_pk_f32_fp8_e32 v[232:233], v182
	v_cvt_pk_f32_fp8_sdwa v[234:235], v182 src0_sel:WORD_1
	v_cvt_pk_f32_fp8_e32 v[236:237], v183
	v_cvt_pk_f32_fp8_sdwa v[238:239], v183 src0_sel:WORD_1
	v_pk_fma_f32 v[64:65], v[224:225], s[26:27], v[64:65] op_sel_hi:[1,0,1]
	v_pk_fma_f32 v[66:67], v[226:227], s[26:27], v[66:67] op_sel_hi:[1,0,1]
	v_pk_fma_f32 v[68:69], v[228:229], s[26:27], v[68:69] op_sel_hi:[1,0,1]
	v_pk_fma_f32 v[70:71], v[230:231], s[26:27], v[70:71] op_sel_hi:[1,0,1]
	v_pk_fma_f32 v[72:73], v[232:233], s[26:27], v[72:73] op_sel_hi:[1,0,1]
	v_pk_fma_f32 v[74:75], v[234:235], s[26:27], v[74:75] op_sel_hi:[1,0,1]
	v_pk_fma_f32 v[76:77], v[236:237], s[26:27], v[76:77] op_sel_hi:[1,0,1]
	v_pk_fma_f32 v[78:79], v[238:239], s[26:27], v[78:79] op_sel_hi:[1,0,1]
	v_cvt_pk_f32_fp8_e32 v[224:225], v184
	v_cvt_pk_f32_fp8_sdwa v[226:227], v184 src0_sel:WORD_1
	v_cvt_pk_f32_fp8_e32 v[228:229], v185
	v_cvt_pk_f32_fp8_sdwa v[230:231], v185 src0_sel:WORD_1
	v_cvt_pk_f32_fp8_e32 v[232:233], v186
	v_cvt_pk_f32_fp8_sdwa v[234:235], v186 src0_sel:WORD_1
	v_cvt_pk_f32_fp8_e32 v[236:237], v187
	v_cvt_pk_f32_fp8_sdwa v[238:239], v187 src0_sel:WORD_1
	v_pk_fma_f32 v[64:65], v[224:225], s[28:29], v[64:65] op_sel_hi:[1,0,1]
	v_pk_fma_f32 v[66:67], v[226:227], s[28:29], v[66:67] op_sel_hi:[1,0,1]
	v_pk_fma_f32 v[68:69], v[228:229], s[28:29], v[68:69] op_sel_hi:[1,0,1]
	v_pk_fma_f32 v[70:71], v[230:231], s[28:29], v[70:71] op_sel_hi:[1,0,1]
	v_pk_fma_f32 v[72:73], v[232:233], s[28:29], v[72:73] op_sel_hi:[1,0,1]
	v_pk_fma_f32 v[74:75], v[234:235], s[28:29], v[74:75] op_sel_hi:[1,0,1]
	v_pk_fma_f32 v[76:77], v[236:237], s[28:29], v[76:77] op_sel_hi:[1,0,1]
	v_pk_fma_f32 v[78:79], v[238:239], s[28:29], v[78:79] op_sel_hi:[1,0,1]
	v_cvt_pk_f32_fp8_e32 v[224:225], v188
	v_cvt_pk_f32_fp8_sdwa v[226:227], v188 src0_sel:WORD_1
	v_cvt_pk_f32_fp8_e32 v[228:229], v189
	v_cvt_pk_f32_fp8_sdwa v[230:231], v189 src0_sel:WORD_1
	v_cvt_pk_f32_fp8_e32 v[232:233], v190
	v_cvt_pk_f32_fp8_sdwa v[234:235], v190 src0_sel:WORD_1
	v_cvt_pk_f32_fp8_e32 v[236:237], v191
	v_cvt_pk_f32_fp8_sdwa v[238:239], v191 src0_sel:WORD_1
	v_pk_fma_f32 v[64:65], v[224:225], s[30:31], v[64:65] op_sel_hi:[1,0,1]
	v_pk_fma_f32 v[66:67], v[226:227], s[30:31], v[66:67] op_sel_hi:[1,0,1]
	v_pk_fma_f32 v[68:69], v[228:229], s[30:31], v[68:69] op_sel_hi:[1,0,1]
	v_pk_fma_f32 v[70:71], v[230:231], s[30:31], v[70:71] op_sel_hi:[1,0,1]
	v_pk_fma_f32 v[72:73], v[232:233], s[30:31], v[72:73] op_sel_hi:[1,0,1]
	v_pk_fma_f32 v[74:75], v[234:235], s[30:31], v[74:75] op_sel_hi:[1,0,1]
	v_pk_fma_f32 v[76:77], v[236:237], s[30:31], v[76:77] op_sel_hi:[1,0,1]
	v_pk_fma_f32 v[78:79], v[238:239], s[30:31], v[78:79] op_sel_hi:[1,0,1]
	v_readlane_b32 s16, v151, s72
	v_readlane_b32 s18, v151, s73
	v_readlane_b32 s20, v151, s74
	v_readlane_b32 s22, v151, s75
	v_readlane_b32 s24, v151, s76
	v_readlane_b32 s26, v151, s77
	v_readlane_b32 s28, v151, s78
	v_readlane_b32 s30, v151, s79
	v_readlane_b32 s48, v153, s72
	v_readlane_b32 s49, v153, s73
	v_readlane_b32 s50, v153, s74
	v_readlane_b32 s51, v153, s75
	v_readlane_b32 s52, v153, s76
	v_readlane_b32 s53, v153, s77
	v_readlane_b32 s54, v153, s78
	v_readlane_b32 s55, v153, s79
	s_add_u32 s32, s0, s48
	s_addc_u32 s33, s1, 0
	s_add_u32 s34, s0, s49
	s_addc_u32 s35, s1, 0
	s_add_u32 s36, s0, s50
	s_addc_u32 s37, s1, 0
	s_add_u32 s38, s0, s51
	s_addc_u32 s39, s1, 0
	s_add_u32 s40, s0, s52
	s_addc_u32 s41, s1, 0
	s_add_u32 s42, s0, s53
	s_addc_u32 s43, s1, 0
	s_add_u32 s44, s0, s54
	s_addc_u32 s45, s1, 0
	s_add_u32 s46, s0, s55
	s_addc_u32 s47, s1, 0
	global_load_dwordx4 v[160:163], v240, s[32:33]
	global_load_dwordx4 v[164:167], v240, s[34:35]
	global_load_dwordx4 v[168:171], v240, s[36:37]
	global_load_dwordx4 v[172:175], v240, s[38:39]
	global_load_dwordx4 v[176:179], v240, s[40:41]
	global_load_dwordx4 v[180:183], v240, s[42:43]
	global_load_dwordx4 v[184:187], v240, s[44:45]
	global_load_dwordx4 v[188:191], v240, s[46:47]
	s_waitcnt vmcnt(8)
	v_cvt_pk_f32_fp8_e32 v[224:225], v192
	v_cvt_pk_f32_fp8_sdwa v[226:227], v192 src0_sel:WORD_1
	v_cvt_pk_f32_fp8_e32 v[228:229], v193
	v_cvt_pk_f32_fp8_sdwa v[230:231], v193 src0_sel:WORD_1
	v_cvt_pk_f32_fp8_e32 v[232:233], v194
	v_cvt_pk_f32_fp8_sdwa v[234:235], v194 src0_sel:WORD_1
	v_cvt_pk_f32_fp8_e32 v[236:237], v195
	v_cvt_pk_f32_fp8_sdwa v[238:239], v195 src0_sel:WORD_1
	v_pk_fma_f32 v[80:81], v[224:225], s[16:17], v[80:81] op_sel_hi:[1,0,1]
	v_pk_fma_f32 v[82:83], v[226:227], s[16:17], v[82:83] op_sel_hi:[1,0,1]
	v_pk_fma_f32 v[84:85], v[228:229], s[16:17], v[84:85] op_sel_hi:[1,0,1]
	v_pk_fma_f32 v[86:87], v[230:231], s[16:17], v[86:87] op_sel_hi:[1,0,1]
	v_pk_fma_f32 v[88:89], v[232:233], s[16:17], v[88:89] op_sel_hi:[1,0,1]
	v_pk_fma_f32 v[90:91], v[234:235], s[16:17], v[90:91] op_sel_hi:[1,0,1]
	v_pk_fma_f32 v[92:93], v[236:237], s[16:17], v[92:93] op_sel_hi:[1,0,1]
	v_pk_fma_f32 v[94:95], v[238:239], s[16:17], v[94:95] op_sel_hi:[1,0,1]
	v_cvt_pk_f32_fp8_e32 v[224:225], v196
	v_cvt_pk_f32_fp8_sdwa v[226:227], v196 src0_sel:WORD_1
	v_cvt_pk_f32_fp8_e32 v[228:229], v197
	v_cvt_pk_f32_fp8_sdwa v[230:231], v197 src0_sel:WORD_1
	v_cvt_pk_f32_fp8_e32 v[232:233], v198
	v_cvt_pk_f32_fp8_sdwa v[234:235], v198 src0_sel:WORD_1
	v_cvt_pk_f32_fp8_e32 v[236:237], v199
	v_cvt_pk_f32_fp8_sdwa v[238:239], v199 src0_sel:WORD_1
	v_pk_fma_f32 v[80:81], v[224:225], s[18:19], v[80:81] op_sel_hi:[1,0,1]
	v_pk_fma_f32 v[82:83], v[226:227], s[18:19], v[82:83] op_sel_hi:[1,0,1]
	v_pk_fma_f32 v[84:85], v[228:229], s[18:19], v[84:85] op_sel_hi:[1,0,1]
	v_pk_fma_f32 v[86:87], v[230:231], s[18:19], v[86:87] op_sel_hi:[1,0,1]
	v_pk_fma_f32 v[88:89], v[232:233], s[18:19], v[88:89] op_sel_hi:[1,0,1]
	v_pk_fma_f32 v[90:91], v[234:235], s[18:19], v[90:91] op_sel_hi:[1,0,1]
	v_pk_fma_f32 v[92:93], v[236:237], s[18:19], v[92:93] op_sel_hi:[1,0,1]
	v_pk_fma_f32 v[94:95], v[238:239], s[18:19], v[94:95] op_sel_hi:[1,0,1]
	v_cvt_pk_f32_fp8_e32 v[224:225], v200
	v_cvt_pk_f32_fp8_sdwa v[226:227], v200 src0_sel:WORD_1
	v_cvt_pk_f32_fp8_e32 v[228:229], v201
	v_cvt_pk_f32_fp8_sdwa v[230:231], v201 src0_sel:WORD_1
	v_cvt_pk_f32_fp8_e32 v[232:233], v202
	v_cvt_pk_f32_fp8_sdwa v[234:235], v202 src0_sel:WORD_1
	v_cvt_pk_f32_fp8_e32 v[236:237], v203
	v_cvt_pk_f32_fp8_sdwa v[238:239], v203 src0_sel:WORD_1
	v_pk_fma_f32 v[80:81], v[224:225], s[20:21], v[80:81] op_sel_hi:[1,0,1]
	v_pk_fma_f32 v[82:83], v[226:227], s[20:21], v[82:83] op_sel_hi:[1,0,1]
	v_pk_fma_f32 v[84:85], v[228:229], s[20:21], v[84:85] op_sel_hi:[1,0,1]
	v_pk_fma_f32 v[86:87], v[230:231], s[20:21], v[86:87] op_sel_hi:[1,0,1]
	v_pk_fma_f32 v[88:89], v[232:233], s[20:21], v[88:89] op_sel_hi:[1,0,1]
	v_pk_fma_f32 v[90:91], v[234:235], s[20:21], v[90:91] op_sel_hi:[1,0,1]
	v_pk_fma_f32 v[92:93], v[236:237], s[20:21], v[92:93] op_sel_hi:[1,0,1]
	v_pk_fma_f32 v[94:95], v[238:239], s[20:21], v[94:95] op_sel_hi:[1,0,1]
	v_cvt_pk_f32_fp8_e32 v[224:225], v204
	v_cvt_pk_f32_fp8_sdwa v[226:227], v204 src0_sel:WORD_1
	v_cvt_pk_f32_fp8_e32 v[228:229], v205
	v_cvt_pk_f32_fp8_sdwa v[230:231], v205 src0_sel:WORD_1
	v_cvt_pk_f32_fp8_e32 v[232:233], v206
	v_cvt_pk_f32_fp8_sdwa v[234:235], v206 src0_sel:WORD_1
	v_cvt_pk_f32_fp8_e32 v[236:237], v207
	v_cvt_pk_f32_fp8_sdwa v[238:239], v207 src0_sel:WORD_1
	v_pk_fma_f32 v[80:81], v[224:225], s[22:23], v[80:81] op_sel_hi:[1,0,1]
	v_pk_fma_f32 v[82:83], v[226:227], s[22:23], v[82:83] op_sel_hi:[1,0,1]
	v_pk_fma_f32 v[84:85], v[228:229], s[22:23], v[84:85] op_sel_hi:[1,0,1]
	v_pk_fma_f32 v[86:87], v[230:231], s[22:23], v[86:87] op_sel_hi:[1,0,1]
	v_pk_fma_f32 v[88:89], v[232:233], s[22:23], v[88:89] op_sel_hi:[1,0,1]
	v_pk_fma_f32 v[90:91], v[234:235], s[22:23], v[90:91] op_sel_hi:[1,0,1]
	v_pk_fma_f32 v[92:93], v[236:237], s[22:23], v[92:93] op_sel_hi:[1,0,1]
	v_pk_fma_f32 v[94:95], v[238:239], s[22:23], v[94:95] op_sel_hi:[1,0,1]
	v_cvt_pk_f32_fp8_e32 v[224:225], v208
	v_cvt_pk_f32_fp8_sdwa v[226:227], v208 src0_sel:WORD_1
	v_cvt_pk_f32_fp8_e32 v[228:229], v209
	v_cvt_pk_f32_fp8_sdwa v[230:231], v209 src0_sel:WORD_1
	v_cvt_pk_f32_fp8_e32 v[232:233], v210
	v_cvt_pk_f32_fp8_sdwa v[234:235], v210 src0_sel:WORD_1
	v_cvt_pk_f32_fp8_e32 v[236:237], v211
	v_cvt_pk_f32_fp8_sdwa v[238:239], v211 src0_sel:WORD_1
	v_pk_fma_f32 v[80:81], v[224:225], s[24:25], v[80:81] op_sel_hi:[1,0,1]
	v_pk_fma_f32 v[82:83], v[226:227], s[24:25], v[82:83] op_sel_hi:[1,0,1]
	v_pk_fma_f32 v[84:85], v[228:229], s[24:25], v[84:85] op_sel_hi:[1,0,1]
	v_pk_fma_f32 v[86:87], v[230:231], s[24:25], v[86:87] op_sel_hi:[1,0,1]
	v_pk_fma_f32 v[88:89], v[232:233], s[24:25], v[88:89] op_sel_hi:[1,0,1]
	v_pk_fma_f32 v[90:91], v[234:235], s[24:25], v[90:91] op_sel_hi:[1,0,1]
	v_pk_fma_f32 v[92:93], v[236:237], s[24:25], v[92:93] op_sel_hi:[1,0,1]
	v_pk_fma_f32 v[94:95], v[238:239], s[24:25], v[94:95] op_sel_hi:[1,0,1]
	v_cvt_pk_f32_fp8_e32 v[224:225], v212
	v_cvt_pk_f32_fp8_sdwa v[226:227], v212 src0_sel:WORD_1
	v_cvt_pk_f32_fp8_e32 v[228:229], v213
	v_cvt_pk_f32_fp8_sdwa v[230:231], v213 src0_sel:WORD_1
	v_cvt_pk_f32_fp8_e32 v[232:233], v214
	v_cvt_pk_f32_fp8_sdwa v[234:235], v214 src0_sel:WORD_1
	v_cvt_pk_f32_fp8_e32 v[236:237], v215
	v_cvt_pk_f32_fp8_sdwa v[238:239], v215 src0_sel:WORD_1
	v_pk_fma_f32 v[80:81], v[224:225], s[26:27], v[80:81] op_sel_hi:[1,0,1]
	v_pk_fma_f32 v[82:83], v[226:227], s[26:27], v[82:83] op_sel_hi:[1,0,1]
	v_pk_fma_f32 v[84:85], v[228:229], s[26:27], v[84:85] op_sel_hi:[1,0,1]
	v_pk_fma_f32 v[86:87], v[230:231], s[26:27], v[86:87] op_sel_hi:[1,0,1]
	v_pk_fma_f32 v[88:89], v[232:233], s[26:27], v[88:89] op_sel_hi:[1,0,1]
	v_pk_fma_f32 v[90:91], v[234:235], s[26:27], v[90:91] op_sel_hi:[1,0,1]
	v_pk_fma_f32 v[92:93], v[236:237], s[26:27], v[92:93] op_sel_hi:[1,0,1]
	v_pk_fma_f32 v[94:95], v[238:239], s[26:27], v[94:95] op_sel_hi:[1,0,1]
	v_cvt_pk_f32_fp8_e32 v[224:225], v216
	v_cvt_pk_f32_fp8_sdwa v[226:227], v216 src0_sel:WORD_1
	v_cvt_pk_f32_fp8_e32 v[228:229], v217
	v_cvt_pk_f32_fp8_sdwa v[230:231], v217 src0_sel:WORD_1
	v_cvt_pk_f32_fp8_e32 v[232:233], v218
	v_cvt_pk_f32_fp8_sdwa v[234:235], v218 src0_sel:WORD_1
	v_cvt_pk_f32_fp8_e32 v[236:237], v219
	v_cvt_pk_f32_fp8_sdwa v[238:239], v219 src0_sel:WORD_1
	v_pk_fma_f32 v[80:81], v[224:225], s[28:29], v[80:81] op_sel_hi:[1,0,1]
	v_pk_fma_f32 v[82:83], v[226:227], s[28:29], v[82:83] op_sel_hi:[1,0,1]
	v_pk_fma_f32 v[84:85], v[228:229], s[28:29], v[84:85] op_sel_hi:[1,0,1]
	v_pk_fma_f32 v[86:87], v[230:231], s[28:29], v[86:87] op_sel_hi:[1,0,1]
	v_pk_fma_f32 v[88:89], v[232:233], s[28:29], v[88:89] op_sel_hi:[1,0,1]
	v_pk_fma_f32 v[90:91], v[234:235], s[28:29], v[90:91] op_sel_hi:[1,0,1]
	v_pk_fma_f32 v[92:93], v[236:237], s[28:29], v[92:93] op_sel_hi:[1,0,1]
	v_pk_fma_f32 v[94:95], v[238:239], s[28:29], v[94:95] op_sel_hi:[1,0,1]
	v_cvt_pk_f32_fp8_e32 v[224:225], v220
	v_cvt_pk_f32_fp8_sdwa v[226:227], v220 src0_sel:WORD_1
	v_cvt_pk_f32_fp8_e32 v[228:229], v221
	v_cvt_pk_f32_fp8_sdwa v[230:231], v221 src0_sel:WORD_1
	v_cvt_pk_f32_fp8_e32 v[232:233], v222
	v_cvt_pk_f32_fp8_sdwa v[234:235], v222 src0_sel:WORD_1
	v_cvt_pk_f32_fp8_e32 v[236:237], v223
	v_cvt_pk_f32_fp8_sdwa v[238:239], v223 src0_sel:WORD_1
	v_pk_fma_f32 v[80:81], v[224:225], s[30:31], v[80:81] op_sel_hi:[1,0,1]
	v_pk_fma_f32 v[82:83], v[226:227], s[30:31], v[82:83] op_sel_hi:[1,0,1]
	v_pk_fma_f32 v[84:85], v[228:229], s[30:31], v[84:85] op_sel_hi:[1,0,1]
	v_pk_fma_f32 v[86:87], v[230:231], s[30:31], v[86:87] op_sel_hi:[1,0,1]
	v_pk_fma_f32 v[88:89], v[232:233], s[30:31], v[88:89] op_sel_hi:[1,0,1]
	v_pk_fma_f32 v[90:91], v[234:235], s[30:31], v[90:91] op_sel_hi:[1,0,1]
	v_pk_fma_f32 v[92:93], v[236:237], s[30:31], v[92:93] op_sel_hi:[1,0,1]
	v_pk_fma_f32 v[94:95], v[238:239], s[30:31], v[94:95] op_sel_hi:[1,0,1]
	v_readlane_b32 s16, v155, s72
	v_readlane_b32 s18, v155, s73
	v_readlane_b32 s20, v155, s74
	v_readlane_b32 s22, v155, s75
	v_readlane_b32 s24, v155, s76
	v_readlane_b32 s26, v155, s77
	v_readlane_b32 s28, v155, s78
	v_readlane_b32 s30, v155, s79
	v_readlane_b32 s48, v157, s72
	v_readlane_b32 s49, v157, s73
	v_readlane_b32 s50, v157, s74
	v_readlane_b32 s51, v157, s75
	v_readlane_b32 s52, v157, s76
	v_readlane_b32 s53, v157, s77
	v_readlane_b32 s54, v157, s78
	v_readlane_b32 s55, v157, s79
	s_add_u32 s32, s0, s48
	s_addc_u32 s33, s1, 0
	s_add_u32 s34, s0, s49
	s_addc_u32 s35, s1, 0
	s_add_u32 s36, s0, s50
	s_addc_u32 s37, s1, 0
	s_add_u32 s38, s0, s51
	s_addc_u32 s39, s1, 0
	s_add_u32 s40, s0, s52
	s_addc_u32 s41, s1, 0
	s_add_u32 s42, s0, s53
	s_addc_u32 s43, s1, 0
	s_add_u32 s44, s0, s54
	s_addc_u32 s45, s1, 0
	s_add_u32 s46, s0, s55
	s_addc_u32 s47, s1, 0
	global_load_dwordx4 v[192:195], v240, s[32:33]
	global_load_dwordx4 v[196:199], v240, s[34:35]
	global_load_dwordx4 v[200:203], v240, s[36:37]
	global_load_dwordx4 v[204:207], v240, s[38:39]
	global_load_dwordx4 v[208:211], v240, s[40:41]
	global_load_dwordx4 v[212:215], v240, s[42:43]
	global_load_dwordx4 v[216:219], v240, s[44:45]
	global_load_dwordx4 v[220:223], v240, s[46:47]
	s_waitcnt vmcnt(8)
	v_cvt_pk_f32_fp8_e32 v[224:225], v160
	v_cvt_pk_f32_fp8_sdwa v[226:227], v160 src0_sel:WORD_1
	v_cvt_pk_f32_fp8_e32 v[228:229], v161
	v_cvt_pk_f32_fp8_sdwa v[230:231], v161 src0_sel:WORD_1
	v_cvt_pk_f32_fp8_e32 v[232:233], v162
	v_cvt_pk_f32_fp8_sdwa v[234:235], v162 src0_sel:WORD_1
	v_cvt_pk_f32_fp8_e32 v[236:237], v163
	v_cvt_pk_f32_fp8_sdwa v[238:239], v163 src0_sel:WORD_1
	v_pk_fma_f32 v[96:97], v[224:225], s[16:17], v[96:97] op_sel_hi:[1,0,1]
	v_pk_fma_f32 v[98:99], v[226:227], s[16:17], v[98:99] op_sel_hi:[1,0,1]
	v_pk_fma_f32 v[100:101], v[228:229], s[16:17], v[100:101] op_sel_hi:[1,0,1]
	v_pk_fma_f32 v[102:103], v[230:231], s[16:17], v[102:103] op_sel_hi:[1,0,1]
	v_pk_fma_f32 v[104:105], v[232:233], s[16:17], v[104:105] op_sel_hi:[1,0,1]
	v_pk_fma_f32 v[106:107], v[234:235], s[16:17], v[106:107] op_sel_hi:[1,0,1]
	v_pk_fma_f32 v[108:109], v[236:237], s[16:17], v[108:109] op_sel_hi:[1,0,1]
	v_pk_fma_f32 v[110:111], v[238:239], s[16:17], v[110:111] op_sel_hi:[1,0,1]
	v_cvt_pk_f32_fp8_e32 v[224:225], v164
	v_cvt_pk_f32_fp8_sdwa v[226:227], v164 src0_sel:WORD_1
	v_cvt_pk_f32_fp8_e32 v[228:229], v165
	v_cvt_pk_f32_fp8_sdwa v[230:231], v165 src0_sel:WORD_1
	v_cvt_pk_f32_fp8_e32 v[232:233], v166
	v_cvt_pk_f32_fp8_sdwa v[234:235], v166 src0_sel:WORD_1
	v_cvt_pk_f32_fp8_e32 v[236:237], v167
	v_cvt_pk_f32_fp8_sdwa v[238:239], v167 src0_sel:WORD_1
	v_pk_fma_f32 v[96:97], v[224:225], s[18:19], v[96:97] op_sel_hi:[1,0,1]
	v_pk_fma_f32 v[98:99], v[226:227], s[18:19], v[98:99] op_sel_hi:[1,0,1]
	v_pk_fma_f32 v[100:101], v[228:229], s[18:19], v[100:101] op_sel_hi:[1,0,1]
	v_pk_fma_f32 v[102:103], v[230:231], s[18:19], v[102:103] op_sel_hi:[1,0,1]
	v_pk_fma_f32 v[104:105], v[232:233], s[18:19], v[104:105] op_sel_hi:[1,0,1]
	v_pk_fma_f32 v[106:107], v[234:235], s[18:19], v[106:107] op_sel_hi:[1,0,1]
	v_pk_fma_f32 v[108:109], v[236:237], s[18:19], v[108:109] op_sel_hi:[1,0,1]
	v_pk_fma_f32 v[110:111], v[238:239], s[18:19], v[110:111] op_sel_hi:[1,0,1]
	v_cvt_pk_f32_fp8_e32 v[224:225], v168
	v_cvt_pk_f32_fp8_sdwa v[226:227], v168 src0_sel:WORD_1
	v_cvt_pk_f32_fp8_e32 v[228:229], v169
	v_cvt_pk_f32_fp8_sdwa v[230:231], v169 src0_sel:WORD_1
	v_cvt_pk_f32_fp8_e32 v[232:233], v170
	v_cvt_pk_f32_fp8_sdwa v[234:235], v170 src0_sel:WORD_1
	v_cvt_pk_f32_fp8_e32 v[236:237], v171
	v_cvt_pk_f32_fp8_sdwa v[238:239], v171 src0_sel:WORD_1
	v_pk_fma_f32 v[96:97], v[224:225], s[20:21], v[96:97] op_sel_hi:[1,0,1]
	v_pk_fma_f32 v[98:99], v[226:227], s[20:21], v[98:99] op_sel_hi:[1,0,1]
	v_pk_fma_f32 v[100:101], v[228:229], s[20:21], v[100:101] op_sel_hi:[1,0,1]
	v_pk_fma_f32 v[102:103], v[230:231], s[20:21], v[102:103] op_sel_hi:[1,0,1]
	v_pk_fma_f32 v[104:105], v[232:233], s[20:21], v[104:105] op_sel_hi:[1,0,1]
	v_pk_fma_f32 v[106:107], v[234:235], s[20:21], v[106:107] op_sel_hi:[1,0,1]
	v_pk_fma_f32 v[108:109], v[236:237], s[20:21], v[108:109] op_sel_hi:[1,0,1]
	v_pk_fma_f32 v[110:111], v[238:239], s[20:21], v[110:111] op_sel_hi:[1,0,1]
	v_cvt_pk_f32_fp8_e32 v[224:225], v172
	v_cvt_pk_f32_fp8_sdwa v[226:227], v172 src0_sel:WORD_1
	v_cvt_pk_f32_fp8_e32 v[228:229], v173
	v_cvt_pk_f32_fp8_sdwa v[230:231], v173 src0_sel:WORD_1
	v_cvt_pk_f32_fp8_e32 v[232:233], v174
	v_cvt_pk_f32_fp8_sdwa v[234:235], v174 src0_sel:WORD_1
	v_cvt_pk_f32_fp8_e32 v[236:237], v175
	v_cvt_pk_f32_fp8_sdwa v[238:239], v175 src0_sel:WORD_1
	v_pk_fma_f32 v[96:97], v[224:225], s[22:23], v[96:97] op_sel_hi:[1,0,1]
	v_pk_fma_f32 v[98:99], v[226:227], s[22:23], v[98:99] op_sel_hi:[1,0,1]
	v_pk_fma_f32 v[100:101], v[228:229], s[22:23], v[100:101] op_sel_hi:[1,0,1]
	v_pk_fma_f32 v[102:103], v[230:231], s[22:23], v[102:103] op_sel_hi:[1,0,1]
	v_pk_fma_f32 v[104:105], v[232:233], s[22:23], v[104:105] op_sel_hi:[1,0,1]
	v_pk_fma_f32 v[106:107], v[234:235], s[22:23], v[106:107] op_sel_hi:[1,0,1]
	v_pk_fma_f32 v[108:109], v[236:237], s[22:23], v[108:109] op_sel_hi:[1,0,1]
	v_pk_fma_f32 v[110:111], v[238:239], s[22:23], v[110:111] op_sel_hi:[1,0,1]
	v_cvt_pk_f32_fp8_e32 v[224:225], v176
	v_cvt_pk_f32_fp8_sdwa v[226:227], v176 src0_sel:WORD_1
	v_cvt_pk_f32_fp8_e32 v[228:229], v177
	v_cvt_pk_f32_fp8_sdwa v[230:231], v177 src0_sel:WORD_1
	v_cvt_pk_f32_fp8_e32 v[232:233], v178
	v_cvt_pk_f32_fp8_sdwa v[234:235], v178 src0_sel:WORD_1
	v_cvt_pk_f32_fp8_e32 v[236:237], v179
	v_cvt_pk_f32_fp8_sdwa v[238:239], v179 src0_sel:WORD_1
	v_pk_fma_f32 v[96:97], v[224:225], s[24:25], v[96:97] op_sel_hi:[1,0,1]
	v_pk_fma_f32 v[98:99], v[226:227], s[24:25], v[98:99] op_sel_hi:[1,0,1]
	v_pk_fma_f32 v[100:101], v[228:229], s[24:25], v[100:101] op_sel_hi:[1,0,1]
	v_pk_fma_f32 v[102:103], v[230:231], s[24:25], v[102:103] op_sel_hi:[1,0,1]
	v_pk_fma_f32 v[104:105], v[232:233], s[24:25], v[104:105] op_sel_hi:[1,0,1]
	v_pk_fma_f32 v[106:107], v[234:235], s[24:25], v[106:107] op_sel_hi:[1,0,1]
	v_pk_fma_f32 v[108:109], v[236:237], s[24:25], v[108:109] op_sel_hi:[1,0,1]
	v_pk_fma_f32 v[110:111], v[238:239], s[24:25], v[110:111] op_sel_hi:[1,0,1]
	v_cvt_pk_f32_fp8_e32 v[224:225], v180
	v_cvt_pk_f32_fp8_sdwa v[226:227], v180 src0_sel:WORD_1
	v_cvt_pk_f32_fp8_e32 v[228:229], v181
	v_cvt_pk_f32_fp8_sdwa v[230:231], v181 src0_sel:WORD_1
	v_cvt_pk_f32_fp8_e32 v[232:233], v182
	v_cvt_pk_f32_fp8_sdwa v[234:235], v182 src0_sel:WORD_1
	v_cvt_pk_f32_fp8_e32 v[236:237], v183
	v_cvt_pk_f32_fp8_sdwa v[238:239], v183 src0_sel:WORD_1
	v_pk_fma_f32 v[96:97], v[224:225], s[26:27], v[96:97] op_sel_hi:[1,0,1]
	v_pk_fma_f32 v[98:99], v[226:227], s[26:27], v[98:99] op_sel_hi:[1,0,1]
	v_pk_fma_f32 v[100:101], v[228:229], s[26:27], v[100:101] op_sel_hi:[1,0,1]
	v_pk_fma_f32 v[102:103], v[230:231], s[26:27], v[102:103] op_sel_hi:[1,0,1]
	v_pk_fma_f32 v[104:105], v[232:233], s[26:27], v[104:105] op_sel_hi:[1,0,1]
	v_pk_fma_f32 v[106:107], v[234:235], s[26:27], v[106:107] op_sel_hi:[1,0,1]
	v_pk_fma_f32 v[108:109], v[236:237], s[26:27], v[108:109] op_sel_hi:[1,0,1]
	v_pk_fma_f32 v[110:111], v[238:239], s[26:27], v[110:111] op_sel_hi:[1,0,1]
	v_cvt_pk_f32_fp8_e32 v[224:225], v184
	v_cvt_pk_f32_fp8_sdwa v[226:227], v184 src0_sel:WORD_1
	v_cvt_pk_f32_fp8_e32 v[228:229], v185
	v_cvt_pk_f32_fp8_sdwa v[230:231], v185 src0_sel:WORD_1
	v_cvt_pk_f32_fp8_e32 v[232:233], v186
	v_cvt_pk_f32_fp8_sdwa v[234:235], v186 src0_sel:WORD_1
	v_cvt_pk_f32_fp8_e32 v[236:237], v187
	v_cvt_pk_f32_fp8_sdwa v[238:239], v187 src0_sel:WORD_1
	v_pk_fma_f32 v[96:97], v[224:225], s[28:29], v[96:97] op_sel_hi:[1,0,1]
	v_pk_fma_f32 v[98:99], v[226:227], s[28:29], v[98:99] op_sel_hi:[1,0,1]
	v_pk_fma_f32 v[100:101], v[228:229], s[28:29], v[100:101] op_sel_hi:[1,0,1]
	v_pk_fma_f32 v[102:103], v[230:231], s[28:29], v[102:103] op_sel_hi:[1,0,1]
	v_pk_fma_f32 v[104:105], v[232:233], s[28:29], v[104:105] op_sel_hi:[1,0,1]
	v_pk_fma_f32 v[106:107], v[234:235], s[28:29], v[106:107] op_sel_hi:[1,0,1]
	v_pk_fma_f32 v[108:109], v[236:237], s[28:29], v[108:109] op_sel_hi:[1,0,1]
	v_pk_fma_f32 v[110:111], v[238:239], s[28:29], v[110:111] op_sel_hi:[1,0,1]
	v_cvt_pk_f32_fp8_e32 v[224:225], v188
	v_cvt_pk_f32_fp8_sdwa v[226:227], v188 src0_sel:WORD_1
	v_cvt_pk_f32_fp8_e32 v[228:229], v189
	v_cvt_pk_f32_fp8_sdwa v[230:231], v189 src0_sel:WORD_1
	v_cvt_pk_f32_fp8_e32 v[232:233], v190
	v_cvt_pk_f32_fp8_sdwa v[234:235], v190 src0_sel:WORD_1
	v_cvt_pk_f32_fp8_e32 v[236:237], v191
	v_cvt_pk_f32_fp8_sdwa v[238:239], v191 src0_sel:WORD_1
	v_pk_fma_f32 v[96:97], v[224:225], s[30:31], v[96:97] op_sel_hi:[1,0,1]
	v_pk_fma_f32 v[98:99], v[226:227], s[30:31], v[98:99] op_sel_hi:[1,0,1]
	v_pk_fma_f32 v[100:101], v[228:229], s[30:31], v[100:101] op_sel_hi:[1,0,1]
	v_pk_fma_f32 v[102:103], v[230:231], s[30:31], v[102:103] op_sel_hi:[1,0,1]
	v_pk_fma_f32 v[104:105], v[232:233], s[30:31], v[104:105] op_sel_hi:[1,0,1]
	v_pk_fma_f32 v[106:107], v[234:235], s[30:31], v[106:107] op_sel_hi:[1,0,1]
	v_pk_fma_f32 v[108:109], v[236:237], s[30:31], v[108:109] op_sel_hi:[1,0,1]
	v_pk_fma_f32 v[110:111], v[238:239], s[30:31], v[110:111] op_sel_hi:[1,0,1]
	v_readlane_b32 s16, v159, s72
; DI void peer_item_v(const Params& p, int item) {
;     ...
;     V_ISSUE(vqa, 0)
; #pragma unroll 1
;     for (int g = 0; g < 16; g += 2) {
;       V_ISSUE(vqb, g + 1)
;       V_CONSUME(vqa, g)
;       if (g + 2 < 16) V_ISSUE(vqa, g + 2)
;       V_CONSUME(vqb, g + 1)
;     }
	v_readlane_b32 s18, v159, s73
	v_readlane_b32 s20, v159, s74
	v_readlane_b32 s22, v159, s75
	v_readlane_b32 s24, v159, s76
	v_readlane_b32 s26, v159, s77
	v_readlane_b32 s28, v159, s78
	v_readlane_b32 s30, v159, s79
	s_add_u32 s72, s72, 8
	s_add_u32 s73, s73, 8
	s_add_u32 s74, s74, 8
	s_add_u32 s75, s75, 8
	s_add_u32 s76, s76, 8
	s_add_u32 s77, s77, 8
	s_add_u32 s78, s78, 8
	s_add_u32 s79, s79, 8
	s_and_b32 s72, s72, 63
	s_and_b32 s73, s73, 63
	s_and_b32 s74, s74, 63
	s_and_b32 s75, s75, 63
	s_and_b32 s76, s76, 63
	s_and_b32 s77, s77, 63
	s_and_b32 s78, s78, 63
	s_and_b32 s79, s79, 63
	v_readlane_b32 s48, v144, s72
	v_readlane_b32 s49, v144, s73
	v_readlane_b32 s50, v144, s74
	v_readlane_b32 s51, v144, s75
	v_readlane_b32 s52, v144, s76
	v_readlane_b32 s53, v144, s77
	v_readlane_b32 s54, v144, s78
	v_readlane_b32 s55, v144, s79
	s_add_u32 s32, s0, s48
	s_addc_u32 s33, s1, 0
	s_add_u32 s34, s0, s49
	s_addc_u32 s35, s1, 0
	s_add_u32 s36, s0, s50
	s_addc_u32 s37, s1, 0
	s_add_u32 s38, s0, s51
	s_addc_u32 s39, s1, 0
	s_add_u32 s40, s0, s52
	s_addc_u32 s41, s1, 0
	s_add_u32 s42, s0, s53
	s_addc_u32 s43, s1, 0
	s_add_u32 s44, s0, s54
	s_addc_u32 s45, s1, 0
	s_add_u32 s46, s0, s55
	s_addc_u32 s47, s1, 0
	global_load_dwordx4 v[160:163], v240, s[32:33]
	global_load_dwordx4 v[164:167], v240, s[34:35]
	global_load_dwordx4 v[168:171], v240, s[36:37]
	global_load_dwordx4 v[172:175], v240, s[38:39]
	global_load_dwordx4 v[176:179], v240, s[40:41]
	global_load_dwordx4 v[180:183], v240, s[42:43]
	global_load_dwordx4 v[184:187], v240, s[44:45]
	global_load_dwordx4 v[188:191], v240, s[46:47]
	s_waitcnt vmcnt(8)
	v_cvt_pk_f32_fp8_e32 v[224:225], v192
	v_cvt_pk_f32_fp8_sdwa v[226:227], v192 src0_sel:WORD_1
	v_cvt_pk_f32_fp8_e32 v[228:229], v193
	v_cvt_pk_f32_fp8_sdwa v[230:231], v193 src0_sel:WORD_1
	v_cvt_pk_f32_fp8_e32 v[232:233], v194
	v_cvt_pk_f32_fp8_sdwa v[234:235], v194 src0_sel:WORD_1
	v_cvt_pk_f32_fp8_e32 v[236:237], v195
	v_cvt_pk_f32_fp8_sdwa v[238:239], v195 src0_sel:WORD_1
	v_pk_fma_f32 v[112:113], v[224:225], s[16:17], v[112:113] op_sel_hi:[1,0,1]
	v_pk_fma_f32 v[114:115], v[226:227], s[16:17], v[114:115] op_sel_hi:[1,0,1]
	v_pk_fma_f32 v[116:117], v[228:229], s[16:17], v[116:117] op_sel_hi:[1,0,1]
	v_pk_fma_f32 v[118:119], v[230:231], s[16:17], v[118:119] op_sel_hi:[1,0,1]
	v_pk_fma_f32 v[120:121], v[232:233], s[16:17], v[120:121] op_sel_hi:[1,0,1]
	v_pk_fma_f32 v[122:123], v[234:235], s[16:17], v[122:123] op_sel_hi:[1,0,1]
	v_pk_fma_f32 v[124:125], v[236:237], s[16:17], v[124:125] op_sel_hi:[1,0,1]
	v_pk_fma_f32 v[126:127], v[238:239], s[16:17], v[126:127] op_sel_hi:[1,0,1]
	v_cvt_pk_f32_fp8_e32 v[224:225], v196
	v_cvt_pk_f32_fp8_sdwa v[226:227], v196 src0_sel:WORD_1
	v_cvt_pk_f32_fp8_e32 v[228:229], v197
	v_cvt_pk_f32_fp8_sdwa v[230:231], v197 src0_sel:WORD_1
	v_cvt_pk_f32_fp8_e32 v[232:233], v198
	v_cvt_pk_f32_fp8_sdwa v[234:235], v198 src0_sel:WORD_1
	v_cvt_pk_f32_fp8_e32 v[236:237], v199
	v_cvt_pk_f32_fp8_sdwa v[238:239], v199 src0_sel:WORD_1
	v_pk_fma_f32 v[112:113], v[224:225], s[18:19], v[112:113] op_sel_hi:[1,0,1]
	v_pk_fma_f32 v[114:115], v[226:227], s[18:19], v[114:115] op_sel_hi:[1,0,1]
	v_pk_fma_f32 v[116:117], v[228:229], s[18:19], v[116:117] op_sel_hi:[1,0,1]
	v_pk_fma_f32 v[118:119], v[230:231], s[18:19], v[118:119] op_sel_hi:[1,0,1]
	v_pk_fma_f32 v[120:121], v[232:233], s[18:19], v[120:121] op_sel_hi:[1,0,1]
	v_pk_fma_f32 v[122:123], v[234:235], s[18:19], v[122:123] op_sel_hi:[1,0,1]
	v_pk_fma_f32 v[124:125], v[236:237], s[18:19], v[124:125] op_sel_hi:[1,0,1]
	v_pk_fma_f32 v[126:127], v[238:239], s[18:19], v[126:127] op_sel_hi:[1,0,1]
	v_cvt_pk_f32_fp8_e32 v[224:225], v200
	v_cvt_pk_f32_fp8_sdwa v[226:227], v200 src0_sel:WORD_1
	v_cvt_pk_f32_fp8_e32 v[228:229], v201
	v_cvt_pk_f32_fp8_sdwa v[230:231], v201 src0_sel:WORD_1
	v_cvt_pk_f32_fp8_e32 v[232:233], v202
	v_cvt_pk_f32_fp8_sdwa v[234:235], v202 src0_sel:WORD_1
	v_cvt_pk_f32_fp8_e32 v[236:237], v203
	v_cvt_pk_f32_fp8_sdwa v[238:239], v203 src0_sel:WORD_1
	v_pk_fma_f32 v[112:113], v[224:225], s[20:21], v[112:113] op_sel_hi:[1,0,1]
	v_pk_fma_f32 v[114:115], v[226:227], s[20:21], v[114:115] op_sel_hi:[1,0,1]
	v_pk_fma_f32 v[116:117], v[228:229], s[20:21], v[116:117] op_sel_hi:[1,0,1]
	v_pk_fma_f32 v[118:119], v[230:231], s[20:21], v[118:119] op_sel_hi:[1,0,1]
	v_pk_fma_f32 v[120:121], v[232:233], s[20:21], v[120:121] op_sel_hi:[1,0,1]
	v_pk_fma_f32 v[122:123], v[234:235], s[20:21], v[122:123] op_sel_hi:[1,0,1]
	v_pk_fma_f32 v[124:125], v[236:237], s[20:21], v[124:125] op_sel_hi:[1,0,1]
	v_pk_fma_f32 v[126:127], v[238:239], s[20:21], v[126:127] op_sel_hi:[1,0,1]
	v_cvt_pk_f32_fp8_e32 v[224:225], v204
	v_cvt_pk_f32_fp8_sdwa v[226:227], v204 src0_sel:WORD_1
	v_cvt_pk_f32_fp8_e32 v[228:229], v205
	v_cvt_pk_f32_fp8_sdwa v[230:231], v205 src0_sel:WORD_1
	v_cvt_pk_f32_fp8_e32 v[232:233], v206
	v_cvt_pk_f32_fp8_sdwa v[234:235], v206 src0_sel:WORD_1
	v_cvt_pk_f32_fp8_e32 v[236:237], v207
	v_cvt_pk_f32_fp8_sdwa v[238:239], v207 src0_sel:WORD_1
	v_pk_fma_f32 v[112:113], v[224:225], s[22:23], v[112:113] op_sel_hi:[1,0,1]
	v_pk_fma_f32 v[114:115], v[226:227], s[22:23], v[114:115] op_sel_hi:[1,0,1]
	v_pk_fma_f32 v[116:117], v[228:229], s[22:23], v[116:117] op_sel_hi:[1,0,1]
	v_pk_fma_f32 v[118:119], v[230:231], s[22:23], v[118:119] op_sel_hi:[1,0,1]
	v_pk_fma_f32 v[120:121], v[232:233], s[22:23], v[120:121] op_sel_hi:[1,0,1]
	v_pk_fma_f32 v[122:123], v[234:235], s[22:23], v[122:123] op_sel_hi:[1,0,1]
	v_pk_fma_f32 v[124:125], v[236:237], s[22:23], v[124:125] op_sel_hi:[1,0,1]
	v_pk_fma_f32 v[126:127], v[238:239], s[22:23], v[126:127] op_sel_hi:[1,0,1]
	v_cvt_pk_f32_fp8_e32 v[224:225], v208
; DI void peer_item_v(const Params& p, int item) {
;     ...
;     for (int g = 0; g < 16; g += 2) {
;       V_ISSUE(vqb, g + 1)
;       V_CONSUME(vqa, g)
;       if (g + 2 < 16) V_ISSUE(vqa, g + 2)
;       V_CONSUME(vqb, g + 1)
;     }
;     ...
;     float* orow = p.out + tok * 1024 + lane * 4;
;     float4 y[4];
;     float ss = 0.f;
; #pragma unroll
;     for (int i = 0; i < 4; ++i) {
;       y[i] = *(const float4*)(orow + 256 * i);
;       y[i].x += out[4 * i]; y[i].y += out[4 * i + 1]; y[i].z += out[4 * i + 2]; y[i].w += out[4 * i + 3];
;       ss += y[i].x * y[i].x + y[i].y * y[i].y + y[i].z * y[i].z + y[i].w * y[i].w;
;     }
;     ss = wave_sum(ss);
	v_cvt_pk_f32_fp8_sdwa v[226:227], v208 src0_sel:WORD_1
	v_cvt_pk_f32_fp8_e32 v[228:229], v209
	v_cvt_pk_f32_fp8_sdwa v[230:231], v209 src0_sel:WORD_1
	v_cvt_pk_f32_fp8_e32 v[232:233], v210
	v_cvt_pk_f32_fp8_sdwa v[234:235], v210 src0_sel:WORD_1
	v_cvt_pk_f32_fp8_e32 v[236:237], v211
	v_cvt_pk_f32_fp8_sdwa v[238:239], v211 src0_sel:WORD_1
	v_pk_fma_f32 v[112:113], v[224:225], s[24:25], v[112:113] op_sel_hi:[1,0,1]
	v_pk_fma_f32 v[114:115], v[226:227], s[24:25], v[114:115] op_sel_hi:[1,0,1]
	v_pk_fma_f32 v[116:117], v[228:229], s[24:25], v[116:117] op_sel_hi:[1,0,1]
	v_pk_fma_f32 v[118:119], v[230:231], s[24:25], v[118:119] op_sel_hi:[1,0,1]
	v_pk_fma_f32 v[120:121], v[232:233], s[24:25], v[120:121] op_sel_hi:[1,0,1]
	v_pk_fma_f32 v[122:123], v[234:235], s[24:25], v[122:123] op_sel_hi:[1,0,1]
	v_pk_fma_f32 v[124:125], v[236:237], s[24:25], v[124:125] op_sel_hi:[1,0,1]
	v_pk_fma_f32 v[126:127], v[238:239], s[24:25], v[126:127] op_sel_hi:[1,0,1]
	v_cvt_pk_f32_fp8_e32 v[224:225], v212
	v_cvt_pk_f32_fp8_sdwa v[226:227], v212 src0_sel:WORD_1
	v_cvt_pk_f32_fp8_e32 v[228:229], v213
	v_cvt_pk_f32_fp8_sdwa v[230:231], v213 src0_sel:WORD_1
	v_cvt_pk_f32_fp8_e32 v[232:233], v214
	v_cvt_pk_f32_fp8_sdwa v[234:235], v214 src0_sel:WORD_1
	v_cvt_pk_f32_fp8_e32 v[236:237], v215
	v_cvt_pk_f32_fp8_sdwa v[238:239], v215 src0_sel:WORD_1
	v_pk_fma_f32 v[112:113], v[224:225], s[26:27], v[112:113] op_sel_hi:[1,0,1]
	v_pk_fma_f32 v[114:115], v[226:227], s[26:27], v[114:115] op_sel_hi:[1,0,1]
	v_pk_fma_f32 v[116:117], v[228:229], s[26:27], v[116:117] op_sel_hi:[1,0,1]
	v_pk_fma_f32 v[118:119], v[230:231], s[26:27], v[118:119] op_sel_hi:[1,0,1]
	v_pk_fma_f32 v[120:121], v[232:233], s[26:27], v[120:121] op_sel_hi:[1,0,1]
	v_pk_fma_f32 v[122:123], v[234:235], s[26:27], v[122:123] op_sel_hi:[1,0,1]
	v_pk_fma_f32 v[124:125], v[236:237], s[26:27], v[124:125] op_sel_hi:[1,0,1]
	v_pk_fma_f32 v[126:127], v[238:239], s[26:27], v[126:127] op_sel_hi:[1,0,1]
	v_cvt_pk_f32_fp8_e32 v[224:225], v216
	v_cvt_pk_f32_fp8_sdwa v[226:227], v216 src0_sel:WORD_1
	v_cvt_pk_f32_fp8_e32 v[228:229], v217
	v_cvt_pk_f32_fp8_sdwa v[230:231], v217 src0_sel:WORD_1
	v_cvt_pk_f32_fp8_e32 v[232:233], v218
	v_cvt_pk_f32_fp8_sdwa v[234:235], v218 src0_sel:WORD_1
	v_cvt_pk_f32_fp8_e32 v[236:237], v219
	v_cvt_pk_f32_fp8_sdwa v[238:239], v219 src0_sel:WORD_1
	v_pk_fma_f32 v[112:113], v[224:225], s[28:29], v[112:113] op_sel_hi:[1,0,1]
	v_pk_fma_f32 v[114:115], v[226:227], s[28:29], v[114:115] op_sel_hi:[1,0,1]
	v_pk_fma_f32 v[116:117], v[228:229], s[28:29], v[116:117] op_sel_hi:[1,0,1]
	v_pk_fma_f32 v[118:119], v[230:231], s[28:29], v[118:119] op_sel_hi:[1,0,1]
	v_pk_fma_f32 v[120:121], v[232:233], s[28:29], v[120:121] op_sel_hi:[1,0,1]
	v_pk_fma_f32 v[122:123], v[234:235], s[28:29], v[122:123] op_sel_hi:[1,0,1]
	v_pk_fma_f32 v[124:125], v[236:237], s[28:29], v[124:125] op_sel_hi:[1,0,1]
	v_pk_fma_f32 v[126:127], v[238:239], s[28:29], v[126:127] op_sel_hi:[1,0,1]
	v_cvt_pk_f32_fp8_e32 v[224:225], v220
	v_cvt_pk_f32_fp8_sdwa v[226:227], v220 src0_sel:WORD_1
	v_cvt_pk_f32_fp8_e32 v[228:229], v221
	v_cvt_pk_f32_fp8_sdwa v[230:231], v221 src0_sel:WORD_1
	v_cvt_pk_f32_fp8_e32 v[232:233], v222
	v_cvt_pk_f32_fp8_sdwa v[234:235], v222 src0_sel:WORD_1
	v_cvt_pk_f32_fp8_e32 v[236:237], v223
	v_cvt_pk_f32_fp8_sdwa v[238:239], v223 src0_sel:WORD_1
	v_pk_fma_f32 v[112:113], v[224:225], s[30:31], v[112:113] op_sel_hi:[1,0,1]
	v_pk_fma_f32 v[114:115], v[226:227], s[30:31], v[114:115] op_sel_hi:[1,0,1]
	v_pk_fma_f32 v[116:117], v[228:229], s[30:31], v[116:117] op_sel_hi:[1,0,1]
	v_pk_fma_f32 v[118:119], v[230:231], s[30:31], v[118:119] op_sel_hi:[1,0,1]
	v_pk_fma_f32 v[120:121], v[232:233], s[30:31], v[120:121] op_sel_hi:[1,0,1]
	v_pk_fma_f32 v[122:123], v[234:235], s[30:31], v[122:123] op_sel_hi:[1,0,1]
	v_pk_fma_f32 v[124:125], v[236:237], s[30:31], v[124:125] op_sel_hi:[1,0,1]
	v_pk_fma_f32 v[126:127], v[238:239], s[30:31], v[126:127] op_sel_hi:[1,0,1]
	s_add_u32 s12, s12, 1
	s_cmp_lt_u32 s12, 8
	s_cbranch_scc1 .Lvq_kB
	s_waitcnt vmcnt(0)
	s_add_u32 s32, s62, 16384
	s_addc_u32 s33, s63, 0
	s_add_u32 s34, s62, 20480
	s_addc_u32 s35, s63, 0
	s_add_u32 s36, s62, 24576
	s_addc_u32 s37, s63, 0
	s_add_u32 s38, s62, 28672
	s_addc_u32 s39, s63, 0
	v_pk_add_f32 v[0:1], v[0:1], v[64:65]
	v_pk_add_f32 v[2:3], v[2:3], v[66:67]
	v_pk_add_f32 v[4:5], v[4:5], v[68:69]
	v_pk_add_f32 v[6:7], v[6:7], v[70:71]
	v_pk_add_f32 v[8:9], v[8:9], v[72:73]
	v_pk_add_f32 v[10:11], v[10:11], v[74:75]
	v_pk_add_f32 v[12:13], v[12:13], v[76:77]
	v_pk_add_f32 v[14:15], v[14:15], v[78:79]
	v_pk_mul_f32 v[224:225], v[0:1], v[0:1]
	v_pk_mul_f32 v[226:227], v[2:3], v[2:3]
	v_pk_fma_f32 v[224:225], v[4:5], v[4:5], v[224:225]
	v_pk_fma_f32 v[226:227], v[6:7], v[6:7], v[226:227]
	v_pk_fma_f32 v[224:225], v[8:9], v[8:9], v[224:225]
	v_pk_fma_f32 v[226:227], v[10:11], v[10:11], v[226:227]
	v_pk_fma_f32 v[224:225], v[12:13], v[12:13], v[224:225]
	v_pk_fma_f32 v[226:227], v[14:15], v[14:15], v[226:227]
	v_pk_add_f32 v[224:225], v[224:225], v[226:227]
	s_nop 0
	v_add_f32_e32 v224, v224, v225
	ds_bpermute_b32 v225, v242, v224
	s_waitcnt lgkmcnt(0)
	v_add_f32_e32 v224, v224, v225
	ds_bpermute_b32 v225, v243, v224
	s_waitcnt lgkmcnt(0)
	v_add_f32_e32 v224, v224, v225
	ds_bpermute_b32 v225, v244, v224
	s_waitcnt lgkmcnt(0)
	v_add_f32_e32 v224, v224, v225
	ds_bpermute_b32 v225, v245, v224
	s_waitcnt lgkmcnt(0)
	v_add_f32_e32 v224, v224, v225
	ds_bpermute_b32 v225, v246, v224
	s_waitcnt lgkmcnt(0)
	v_add_f32_e32 v224, v224, v225
	ds_bpermute_b32 v225, v247, v224
	s_waitcnt lgkmcnt(0)
; DI void peer_item_v(const Params& p, int item) {
;     ...
;     for (int i = 0; i < 4; ++i) {
;       y[i] = *(const float4*)(orow + 256 * i);
;       y[i].x += out[4 * i]; y[i].y += out[4 * i + 1]; y[i].z += out[4 * i + 2]; y[i].w += out[4 * i + 3];
;       ss += y[i].x * y[i].x + y[i].y * y[i].y + y[i].z * y[i].z + y[i].w * y[i].w;
;     }
;     ss = wave_sum(ss);
;     const float r = rsqrtf(ss * (1.f / 1024.f) + 1e-6f);
; #pragma unroll
;     for (int i = 0; i < 4; ++i) {
;       float4 g = *(const float4*)(p.g_final + 256 * i + lane * 4);
;       y[i].x *= r * g.x; y[i].y *= r * g.y; y[i].z *= r * g.z; y[i].w *= r * g.w;
;       *(float4*)(orow + 256 * i) = y[i];
	v_add_f32_e32 v224, v224, v225
	v_fmamk_f32 v224, v224, 0x3a800000, v248
	v_rsq_f32_e32 v224, v224
	s_nop 1
	v_pk_mul_f32 v[226:227], v[128:129], v[224:225] op_sel_hi:[1,0]
	v_pk_mul_f32 v[0:1], v[0:1], v[226:227]
	v_pk_mul_f32 v[228:229], v[130:131], v[224:225] op_sel_hi:[1,0]
	v_pk_mul_f32 v[2:3], v[2:3], v[228:229]
	v_pk_mul_f32 v[230:231], v[132:133], v[224:225] op_sel_hi:[1,0]
	v_pk_mul_f32 v[4:5], v[4:5], v[230:231]
	v_pk_mul_f32 v[232:233], v[134:135], v[224:225] op_sel_hi:[1,0]
	v_pk_mul_f32 v[6:7], v[6:7], v[232:233]
	v_pk_mul_f32 v[226:227], v[136:137], v[224:225] op_sel_hi:[1,0]
	v_pk_mul_f32 v[8:9], v[8:9], v[226:227]
	v_pk_mul_f32 v[228:229], v[138:139], v[224:225] op_sel_hi:[1,0]
	v_pk_mul_f32 v[10:11], v[10:11], v[228:229]
	v_pk_mul_f32 v[230:231], v[140:141], v[224:225] op_sel_hi:[1,0]
	v_pk_mul_f32 v[12:13], v[12:13], v[230:231]
	v_pk_mul_f32 v[232:233], v[142:143], v[224:225] op_sel_hi:[1,0]
	v_pk_mul_f32 v[14:15], v[14:15], v[232:233]
	v_pk_add_f32 v[16:17], v[16:17], v[80:81]
	v_pk_add_f32 v[18:19], v[18:19], v[82:83]
	v_pk_add_f32 v[20:21], v[20:21], v[84:85]
	v_pk_add_f32 v[22:23], v[22:23], v[86:87]
	v_pk_add_f32 v[24:25], v[24:25], v[88:89]
	v_pk_add_f32 v[26:27], v[26:27], v[90:91]
	v_pk_add_f32 v[28:29], v[28:29], v[92:93]
	v_pk_add_f32 v[30:31], v[30:31], v[94:95]
	v_pk_mul_f32 v[224:225], v[16:17], v[16:17]
	v_pk_mul_f32 v[226:227], v[18:19], v[18:19]
	v_pk_fma_f32 v[224:225], v[20:21], v[20:21], v[224:225]
	v_pk_fma_f32 v[226:227], v[22:23], v[22:23], v[226:227]
	v_pk_fma_f32 v[224:225], v[24:25], v[24:25], v[224:225]
	v_pk_fma_f32 v[226:227], v[26:27], v[26:27], v[226:227]
	v_pk_fma_f32 v[224:225], v[28:29], v[28:29], v[224:225]
	v_pk_fma_f32 v[226:227], v[30:31], v[30:31], v[226:227]
	v_pk_add_f32 v[224:225], v[224:225], v[226:227]
	s_nop 0
	v_add_f32_e32 v224, v224, v225
	ds_bpermute_b32 v225, v242, v224
	s_waitcnt lgkmcnt(0)
	v_add_f32_e32 v224, v224, v225
	ds_bpermute_b32 v225, v243, v224
	s_waitcnt lgkmcnt(0)
	v_add_f32_e32 v224, v224, v225
	ds_bpermute_b32 v225, v244, v224
	s_waitcnt lgkmcnt(0)
	v_add_f32_e32 v224, v224, v225
	ds_bpermute_b32 v225, v245, v224
	s_waitcnt lgkmcnt(0)
	v_add_f32_e32 v224, v224, v225
	ds_bpermute_b32 v225, v246, v224
	s_waitcnt lgkmcnt(0)
	v_add_f32_e32 v224, v224, v225
	ds_bpermute_b32 v225, v247, v224
	s_waitcnt lgkmcnt(0)
	v_add_f32_e32 v224, v224, v225
	v_fmamk_f32 v224, v224, 0x3a800000, v248
	v_rsq_f32_e32 v224, v224
	s_nop 1
	v_pk_mul_f32 v[226:227], v[128:129], v[224:225] op_sel_hi:[1,0]
	v_pk_mul_f32 v[16:17], v[16:17], v[226:227]
	v_pk_mul_f32 v[228:229], v[130:131], v[224:225] op_sel_hi:[1,0]
	v_pk_mul_f32 v[18:19], v[18:19], v[228:229]
	v_pk_mul_f32 v[230:231], v[132:133], v[224:225] op_sel_hi:[1,0]
	v_pk_mul_f32 v[20:21], v[20:21], v[230:231]
	v_pk_mul_f32 v[232:233], v[134:135], v[224:225] op_sel_hi:[1,0]
	v_pk_mul_f32 v[22:23], v[22:23], v[232:233]
	v_pk_mul_f32 v[226:227], v[136:137], v[224:225] op_sel_hi:[1,0]
	v_pk_mul_f32 v[24:25], v[24:25], v[226:227]
	v_pk_mul_f32 v[228:229], v[138:139], v[224:225] op_sel_hi:[1,0]
	v_pk_mul_f32 v[26:27], v[26:27], v[228:229]
	v_pk_mul_f32 v[230:231], v[140:141], v[224:225] op_sel_hi:[1,0]
	v_pk_mul_f32 v[28:29], v[28:29], v[230:231]
	v_pk_mul_f32 v[232:233], v[142:143], v[224:225] op_sel_hi:[1,0]
	v_pk_mul_f32 v[30:31], v[30:31], v[232:233]
	v_pk_add_f32 v[32:33], v[32:33], v[96:97]
	v_pk_add_f32 v[34:35], v[34:35], v[98:99]
	v_pk_add_f32 v[36:37], v[36:37], v[100:101]
	v_pk_add_f32 v[38:39], v[38:39], v[102:103]
	v_pk_add_f32 v[40:41], v[40:41], v[104:105]
	v_pk_add_f32 v[42:43], v[42:43], v[106:107]
	v_pk_add_f32 v[44:45], v[44:45], v[108:109]
	v_pk_add_f32 v[46:47], v[46:47], v[110:111]
	v_pk_mul_f32 v[224:225], v[32:33], v[32:33]
	v_pk_mul_f32 v[226:227], v[34:35], v[34:35]
	v_pk_fma_f32 v[224:225], v[36:37], v[36:37], v[224:225]
	v_pk_fma_f32 v[226:227], v[38:39], v[38:39], v[226:227]
	v_pk_fma_f32 v[224:225], v[40:41], v[40:41], v[224:225]
	v_pk_fma_f32 v[226:227], v[42:43], v[42:43], v[226:227]
	v_pk_fma_f32 v[224:225], v[44:45], v[44:45], v[224:225]
	v_pk_fma_f32 v[226:227], v[46:47], v[46:47], v[226:227]
	v_pk_add_f32 v[224:225], v[224:225], v[226:227]
	s_nop 0
	v_add_f32_e32 v224, v224, v225
	ds_bpermute_b32 v225, v242, v224
	s_waitcnt lgkmcnt(0)
	v_add_f32_e32 v224, v224, v225
	ds_bpermute_b32 v225, v243, v224
	s_waitcnt lgkmcnt(0)
	v_add_f32_e32 v224, v224, v225
	ds_bpermute_b32 v225, v244, v224
	s_waitcnt lgkmcnt(0)
	v_add_f32_e32 v224, v224, v225
	ds_bpermute_b32 v225, v245, v224
	s_waitcnt lgkmcnt(0)
; DI int vb_id() { return (int)blockIdx.x + half_id() * (int)gridDim.x; }
; DI int vb_n() { return (int)gridDim.x * 2; }
; DI void peer_item_v(const Params& p, int item) {
;     ...
;     ss = wave_sum(ss);
;     const float r = rsqrtf(ss * (1.f / 1024.f) + 1e-6f);
; #pragma unroll
;     for (int i = 0; i < 4; ++i) {
;       float4 g = *(const float4*)(p.g_final + 256 * i + lane * 4);
;       y[i].x *= r * g.x; y[i].y *= r * g.y; y[i].z *= r * g.z; y[i].w *= r * g.w;
;       *(float4*)(orow + 256 * i) = y[i];
;     }
; DI void phase_peer_v(const Params& p) {
;   for (int it = vb_id(); it < 512; it += vb_n()) peer_item_v(p, it);
	v_add_f32_e32 v224, v224, v225
	ds_bpermute_b32 v225, v246, v224
	s_waitcnt lgkmcnt(0)
	v_add_f32_e32 v224, v224, v225
	ds_bpermute_b32 v225, v247, v224
	s_waitcnt lgkmcnt(0)
	v_add_f32_e32 v224, v224, v225
	v_fmamk_f32 v224, v224, 0x3a800000, v248
	v_rsq_f32_e32 v224, v224
	s_nop 1
	v_pk_mul_f32 v[226:227], v[128:129], v[224:225] op_sel_hi:[1,0]
	v_pk_mul_f32 v[32:33], v[32:33], v[226:227]
	v_pk_mul_f32 v[228:229], v[130:131], v[224:225] op_sel_hi:[1,0]
	v_pk_mul_f32 v[34:35], v[34:35], v[228:229]
	v_pk_mul_f32 v[230:231], v[132:133], v[224:225] op_sel_hi:[1,0]
	v_pk_mul_f32 v[36:37], v[36:37], v[230:231]
	v_pk_mul_f32 v[232:233], v[134:135], v[224:225] op_sel_hi:[1,0]
	v_pk_mul_f32 v[38:39], v[38:39], v[232:233]
	v_pk_mul_f32 v[226:227], v[136:137], v[224:225] op_sel_hi:[1,0]
	v_pk_mul_f32 v[40:41], v[40:41], v[226:227]
	v_pk_mul_f32 v[228:229], v[138:139], v[224:225] op_sel_hi:[1,0]
	v_pk_mul_f32 v[42:43], v[42:43], v[228:229]
	v_pk_mul_f32 v[230:231], v[140:141], v[224:225] op_sel_hi:[1,0]
	v_pk_mul_f32 v[44:45], v[44:45], v[230:231]
	v_pk_mul_f32 v[232:233], v[142:143], v[224:225] op_sel_hi:[1,0]
	v_pk_mul_f32 v[46:47], v[46:47], v[232:233]
	v_pk_add_f32 v[48:49], v[48:49], v[112:113]
	v_pk_add_f32 v[50:51], v[50:51], v[114:115]
	v_pk_add_f32 v[52:53], v[52:53], v[116:117]
	v_pk_add_f32 v[54:55], v[54:55], v[118:119]
	v_pk_add_f32 v[56:57], v[56:57], v[120:121]
	v_pk_add_f32 v[58:59], v[58:59], v[122:123]
	v_pk_add_f32 v[60:61], v[60:61], v[124:125]
	v_pk_add_f32 v[62:63], v[62:63], v[126:127]
	v_pk_mul_f32 v[224:225], v[48:49], v[48:49]
	v_pk_mul_f32 v[226:227], v[50:51], v[50:51]
	v_pk_fma_f32 v[224:225], v[52:53], v[52:53], v[224:225]
	v_pk_fma_f32 v[226:227], v[54:55], v[54:55], v[226:227]
	v_pk_fma_f32 v[224:225], v[56:57], v[56:57], v[224:225]
	v_pk_fma_f32 v[226:227], v[58:59], v[58:59], v[226:227]
	v_pk_fma_f32 v[224:225], v[60:61], v[60:61], v[224:225]
	v_pk_fma_f32 v[226:227], v[62:63], v[62:63], v[226:227]
	v_pk_add_f32 v[224:225], v[224:225], v[226:227]
	s_nop 0
	v_add_f32_e32 v224, v224, v225
	ds_bpermute_b32 v225, v242, v224
	s_waitcnt lgkmcnt(0)
	v_add_f32_e32 v224, v224, v225
	ds_bpermute_b32 v225, v243, v224
	s_waitcnt lgkmcnt(0)
	v_add_f32_e32 v224, v224, v225
	ds_bpermute_b32 v225, v244, v224
	s_waitcnt lgkmcnt(0)
	v_add_f32_e32 v224, v224, v225
	ds_bpermute_b32 v225, v245, v224
	s_waitcnt lgkmcnt(0)
	v_add_f32_e32 v224, v224, v225
	ds_bpermute_b32 v225, v246, v224
	s_waitcnt lgkmcnt(0)
	v_add_f32_e32 v224, v224, v225
	ds_bpermute_b32 v225, v247, v224
	s_waitcnt lgkmcnt(0)
	v_add_f32_e32 v224, v224, v225
	v_fmamk_f32 v224, v224, 0x3a800000, v248
	v_rsq_f32_e32 v224, v224
	s_nop 1
	v_pk_mul_f32 v[226:227], v[128:129], v[224:225] op_sel_hi:[1,0]
	v_pk_mul_f32 v[48:49], v[48:49], v[226:227]
	v_pk_mul_f32 v[228:229], v[130:131], v[224:225] op_sel_hi:[1,0]
	v_pk_mul_f32 v[50:51], v[50:51], v[228:229]
	v_pk_mul_f32 v[230:231], v[132:133], v[224:225] op_sel_hi:[1,0]
	v_pk_mul_f32 v[52:53], v[52:53], v[230:231]
	v_pk_mul_f32 v[232:233], v[134:135], v[224:225] op_sel_hi:[1,0]
	v_pk_mul_f32 v[54:55], v[54:55], v[232:233]
	v_pk_mul_f32 v[226:227], v[136:137], v[224:225] op_sel_hi:[1,0]
	v_pk_mul_f32 v[56:57], v[56:57], v[226:227]
	v_pk_mul_f32 v[228:229], v[138:139], v[224:225] op_sel_hi:[1,0]
	v_pk_mul_f32 v[58:59], v[58:59], v[228:229]
	v_pk_mul_f32 v[230:231], v[140:141], v[224:225] op_sel_hi:[1,0]
	v_pk_mul_f32 v[60:61], v[60:61], v[230:231]
	v_pk_mul_f32 v[232:233], v[142:143], v[224:225] op_sel_hi:[1,0]
	v_pk_mul_f32 v[62:63], v[62:63], v[232:233]
	global_store_dwordx4 v240, v[0:3], s[32:33]
	global_store_dwordx4 v240, v[4:7], s[32:33] offset:1024
	global_store_dwordx4 v240, v[8:11], s[32:33] offset:2048
	global_store_dwordx4 v240, v[12:15], s[32:33] offset:3072
	global_store_dwordx4 v240, v[16:19], s[34:35]
	global_store_dwordx4 v240, v[20:23], s[34:35] offset:1024
	global_store_dwordx4 v240, v[24:27], s[34:35] offset:2048
	global_store_dwordx4 v240, v[28:31], s[34:35] offset:3072
	global_store_dwordx4 v240, v[32:35], s[36:37]
	global_store_dwordx4 v240, v[36:39], s[36:37] offset:1024
	global_store_dwordx4 v240, v[40:43], s[36:37] offset:2048
	global_store_dwordx4 v240, v[44:47], s[36:37] offset:3072
	global_store_dwordx4 v240, v[48:51], s[38:39]
	global_store_dwordx4 v240, v[52:55], s[38:39] offset:1024
	global_store_dwordx4 v240, v[56:59], s[38:39] offset:2048
	global_store_dwordx4 v240, v[60:63], s[38:39] offset:3072
	s_nop 1
	s_add_i32 s10, s10, s11
	s_cmpk_lt_i32 s10, 0x200
	s_cbranch_scc1 .Lvq_item
